# GEMM K loops: 16 per-phase s_setprio flips replaced by one static s_setprio 1 for waves 4-7 before the loop (reset after)
# speedup vs baseline: 1.0074x; 1.0074x over previous
.LBB0_55:
	v_mov_b64_e32 v[2:3], 0x840
	s_ashr_i32 s25, s24, 31
	v_cmp_lt_i64_e32 vcc, s[10:11], v[2:3]
	s_lshl_b64 s[10:11], s[24:25], 19
	v_readlane_b32 s14, v254, 33
	v_readlane_b32 s15, v254, 34
	s_add_u32 s34, s14, s10
	s_addc_u32 s35, s15, s11
	v_readlane_b32 s98, v254, 0
	s_and_b32 s98, s98, s99
	s_mul_i32 s98, s98, 0x40000
	s_add_u32 s34, s34, s98
	s_addc_u32 s35, s35, 0
	s_and_b64 s[10:11], vcc, exec
	s_cselect_b32 s14, s35, s7
	s_cselect_b32 s15, s34, s6
	s_ashr_i32 s23, s22, 31
	s_lshl_b64 s[10:11], s[22:23], 19
	s_add_u32 s30, s3, s10
	s_addc_u32 s31, s42, s11
	s_and_b64 s[10:11], vcc, exec
	s_cselect_b32 s16, s31, s9
	s_cselect_b32 s17, s30, s8
	s_add_u32 s23, s8, 0x100
	s_addc_u32 s25, s9, 0
	s_add_u32 s6, s6, 0x40080
	v_mov_b32_e32 v2, 0
	s_addc_u32 s7, s7, 0
	s_mov_b32 s40, -2
	v_mov_b32_e32 v3, v2
	v_mov_b32_e32 v4, v2
	v_mov_b32_e32 v5, v2
	v_mov_b32_e32 v6, v2
	v_mov_b32_e32 v7, v2
	v_mov_b32_e32 v8, v2
	v_mov_b32_e32 v9, v2
	v_mov_b32_e32 v18, v2
	v_mov_b32_e32 v19, v2
	v_mov_b32_e32 v20, v2
	v_mov_b32_e32 v21, v2
	v_mov_b32_e32 v22, v2
	v_mov_b32_e32 v23, v2
	v_mov_b32_e32 v24, v2
	v_mov_b32_e32 v25, v2
	v_mov_b32_e32 v30, v2
	v_mov_b32_e32 v31, v2
	v_mov_b32_e32 v32, v2
	v_mov_b32_e32 v33, v2
	v_mov_b32_e32 v38, v2
	v_mov_b32_e32 v39, v2
	v_mov_b32_e32 v40, v2
	v_mov_b32_e32 v41, v2
	v_mov_b32_e32 v46, v2
	v_mov_b32_e32 v47, v2
	v_mov_b32_e32 v48, v2
	v_mov_b32_e32 v49, v2
	v_mov_b32_e32 v54, v2
	v_mov_b32_e32 v55, v2
	v_mov_b32_e32 v56, v2
	v_mov_b32_e32 v57, v2
	v_mov_b32_e32 v10, v2
	v_mov_b32_e32 v11, v2
	v_mov_b32_e32 v12, v2
	v_mov_b32_e32 v13, v2
	v_mov_b32_e32 v14, v2
	v_mov_b32_e32 v15, v2
	v_mov_b32_e32 v16, v2
	v_mov_b32_e32 v17, v2
	v_mov_b32_e32 v26, v2
	v_mov_b32_e32 v27, v2
	v_mov_b32_e32 v28, v2
	v_mov_b32_e32 v29, v2
	v_mov_b32_e32 v34, v2
	v_mov_b32_e32 v35, v2
	v_mov_b32_e32 v36, v2
	v_mov_b32_e32 v37, v2
	v_mov_b32_e32 v42, v2
	v_mov_b32_e32 v43, v2
	v_mov_b32_e32 v44, v2
	v_mov_b32_e32 v45, v2
	v_mov_b32_e32 v50, v2
	v_mov_b32_e32 v51, v2
	v_mov_b32_e32 v52, v2
	v_mov_b32_e32 v53, v2
	v_mov_b32_e32 v58, v2
	v_mov_b32_e32 v59, v2
	v_mov_b32_e32 v60, v2
	v_mov_b32_e32 v61, v2
	v_mov_b32_e32 v62, v2
	v_mov_b32_e32 v63, v2
	v_mov_b32_e32 v64, v2
	v_mov_b32_e32 v65, v2
	v_mov_b32_e32 v98, v2
	v_mov_b32_e32 v99, v2
	v_mov_b32_e32 v100, v2
	v_mov_b32_e32 v101, v2
	v_mov_b32_e32 v102, v2
	v_mov_b32_e32 v103, v2
	v_mov_b32_e32 v104, v2
	v_mov_b32_e32 v105, v2
	v_mov_b32_e32 v114, v2
	v_mov_b32_e32 v115, v2
	v_mov_b32_e32 v116, v2
	v_mov_b32_e32 v117, v2
	v_mov_b32_e32 v118, v2
	v_mov_b32_e32 v119, v2
	v_mov_b32_e32 v120, v2
	v_mov_b32_e32 v121, v2
	v_mov_b32_e32 v126, v2
	v_mov_b32_e32 v127, v2
	v_mov_b32_e32 v128, v2
	v_mov_b32_e32 v129, v2
	v_mov_b32_e32 v134, v2
	v_mov_b32_e32 v135, v2
	v_mov_b32_e32 v136, v2
	v_mov_b32_e32 v137, v2
	v_mov_b32_e32 v142, v2
	v_mov_b32_e32 v143, v2
	v_mov_b32_e32 v144, v2
	v_mov_b32_e32 v145, v2
	v_mov_b32_e32 v150, v2
	v_mov_b32_e32 v151, v2
	v_mov_b32_e32 v152, v2
	v_mov_b32_e32 v153, v2
	v_mov_b32_e32 v106, v2
	v_mov_b32_e32 v107, v2
	v_mov_b32_e32 v108, v2
	v_mov_b32_e32 v109, v2
	v_mov_b32_e32 v110, v2
	v_mov_b32_e32 v111, v2
	v_mov_b32_e32 v112, v2
	v_mov_b32_e32 v113, v2
	v_mov_b32_e32 v122, v2
	v_mov_b32_e32 v123, v2
	v_mov_b32_e32 v124, v2
	v_mov_b32_e32 v125, v2
	v_mov_b32_e32 v130, v2
	v_mov_b32_e32 v131, v2
	v_mov_b32_e32 v132, v2
	v_mov_b32_e32 v133, v2
	v_mov_b32_e32 v138, v2
	v_mov_b32_e32 v139, v2
	v_mov_b32_e32 v140, v2
	v_mov_b32_e32 v141, v2
	v_mov_b32_e32 v146, v2
	v_mov_b32_e32 v147, v2
	v_mov_b32_e32 v148, v2
	v_mov_b32_e32 v149, v2
	v_mov_b32_e32 v154, v2
	v_mov_b32_e32 v155, v2
	v_mov_b32_e32 v156, v2
	v_mov_b32_e32 v157, v2
	v_mov_b32_e32 v158, v2
	v_mov_b32_e32 v159, v2
	v_mov_b32_e32 v160, v2
	v_mov_b32_e32 v161, v2
	v_readlane_b32 s99, v255, 41
	s_cmp_eq_u32 s52, 9
	s_cselect_b32 s99, s99, 0
	v_cmp_lt_u32_e32 vcc, 0xff, v163
	s_nop 1
	s_cbranch_vccz .Lsprio_skip0
	s_setprio 1
.Lsprio_skip0:
.LBB0_56:
	s_add_u32 s8, s6, 0xfffc0080
	s_addc_u32 s9, s7, -1
	s_add_i32 s41, 0, 0x10000
	v_add_u32_e32 v0, s41, v169
	ds_read_b128 v[66:69], v0
	ds_read_b128 v[70:73], v0 offset:1024
	ds_read_b128 v[74:77], v0 offset:2048
	ds_read_b128 v[78:81], v0 offset:3072
	s_cmp_eq_u32 s40, 12
	s_cselect_b32 s11, s14, s9
	s_cselect_b32 s10, s15, s8
	s_cselect_b32 s9, s16, s25
	s_cselect_b32 s8, s17, s23
	v_lshl_add_u64 v[200:201], s[6:7], 0, v[182:183]
	s_add_i32 m0, s44, 0xc000
	ds_read_b128 v[82:85], v229
	ds_read_b128 v[86:89], v229 offset:1024
	ds_read_b128 v[90:93], v229 offset:2048
	ds_read_b128 v[94:97], v229 offset:3072
	ds_read_b128 v[184:187], v229 offset:4096
	ds_read_b128 v[188:191], v229 offset:5120
	ds_read_b128 v[192:195], v229 offset:6144
	ds_read_b128 v[196:199], v229 offset:7168
	global_load_lds_dwordx4 v[200:201], off
	v_lshl_add_u64 v[200:201], s[6:7], 0, v[180:181]
	s_add_i32 m0, s44, 0xe000
	s_nop 0
	global_load_lds_dwordx4 v[200:201], off
	s_waitcnt lgkmcnt(8)
	s_barrier
	s_waitcnt lgkmcnt(0)
	s_nop 0
	s_waitcnt lgkmcnt(0)
	v_mfma_f32_16x16x32_bf16 v[158:161], v[66:69], v[82:85], v[158:161]
	v_mfma_f32_16x16x32_bf16 v[154:157], v[74:77], v[82:85], v[154:157]
	v_mfma_f32_16x16x32_bf16 v[146:149], v[66:69], v[90:93], v[146:149]
	v_mfma_f32_16x16x32_bf16 v[138:141], v[74:77], v[90:93], v[138:141]
	v_mfma_f32_16x16x32_bf16 v[130:133], v[66:69], v[184:187], v[130:133]
	v_mfma_f32_16x16x32_bf16 v[122:125], v[74:77], v[184:187], v[122:125]
	v_mfma_f32_16x16x32_bf16 v[110:113], v[66:69], v[192:195], v[110:113]
	v_mfma_f32_16x16x32_bf16 v[106:109], v[74:77], v[192:195], v[106:109]
	v_mfma_f32_16x16x32_bf16 v[158:161], v[70:73], v[86:89], v[158:161]
	v_mfma_f32_16x16x32_bf16 v[154:157], v[78:81], v[86:89], v[154:157]
	v_mfma_f32_16x16x32_bf16 v[146:149], v[70:73], v[94:97], v[146:149]
	v_mfma_f32_16x16x32_bf16 v[138:141], v[78:81], v[94:97], v[138:141]
	v_mfma_f32_16x16x32_bf16 v[130:133], v[70:73], v[188:191], v[130:133]
	v_mfma_f32_16x16x32_bf16 v[122:125], v[78:81], v[188:191], v[122:125]
	v_mfma_f32_16x16x32_bf16 v[110:113], v[70:73], v[196:199], v[110:113]
	v_mfma_f32_16x16x32_bf16 v[106:109], v[78:81], v[196:199], v[106:109]
	s_nop 0
	s_barrier
	s_add_i32 s53, 0, 0x14000
	s_add_i32 s41, s41, s43
	v_add_u32_e32 v0, s53, v169
	v_lshl_add_u64 v[200:201], s[8:9], 0, v[176:177]
	s_mov_b32 m0, s41
	ds_read_b128 v[230:233], v0
	ds_read_b128 v[234:237], v0 offset:1024
	ds_read_b128 v[238:241], v0 offset:2048
	ds_read_b128 v[242:245], v0 offset:3072
	global_load_lds_dwordx4 v[200:201], off
	v_lshl_add_u64 v[210:211], s[8:9], 0, v[178:179]
	s_add_i32 m0, s41, 0x2000
	s_nop 0
	global_load_lds_dwordx4 v[210:211], off
	s_barrier
	s_waitcnt lgkmcnt(0)
	s_nop 0
	s_waitcnt lgkmcnt(0)
	v_mfma_f32_16x16x32_bf16 v[150:153], v[230:233], v[82:85], v[150:153]
	v_mfma_f32_16x16x32_bf16 v[82:85], v[238:241], v[82:85], v[142:145]
	v_mfma_f32_16x16x32_bf16 v[150:153], v[234:237], v[86:89], v[150:153]
	v_mfma_f32_16x16x32_bf16 v[82:85], v[242:245], v[86:89], v[82:85]
	v_mfma_f32_16x16x32_bf16 v[86:89], v[230:233], v[90:93], v[134:137]
	v_mfma_f32_16x16x32_bf16 v[90:93], v[238:241], v[90:93], v[126:129]
	v_mfma_f32_16x16x32_bf16 v[114:117], v[238:241], v[184:187], v[114:117]
	v_mfma_f32_16x16x32_bf16 v[102:105], v[230:233], v[192:195], v[102:105]
	v_mfma_f32_16x16x32_bf16 v[98:101], v[238:241], v[192:195], v[98:101]
	v_mfma_f32_16x16x32_bf16 v[86:89], v[234:237], v[94:97], v[86:89]
	v_mfma_f32_16x16x32_bf16 v[90:93], v[242:245], v[94:97], v[90:93]
	v_mfma_f32_16x16x32_bf16 v[94:97], v[230:233], v[184:187], v[118:121]
	v_mfma_f32_16x16x32_bf16 v[114:117], v[242:245], v[188:191], v[114:117]
	v_mfma_f32_16x16x32_bf16 v[102:105], v[234:237], v[196:199], v[102:105]
	v_mfma_f32_16x16x32_bf16 v[98:101], v[242:245], v[196:199], v[98:101]
	v_mfma_f32_16x16x32_bf16 v[94:97], v[234:237], v[188:191], v[94:97]
	s_nop 0
	s_mov_b32 m0, s44
	v_lshl_add_u64 v[172:173], s[10:11], 0, v[176:177]
	s_barrier
	ds_read_b128 v[118:121], v229 offset:16384
	ds_read_b128 v[126:129], v229 offset:17408
	ds_read_b128 v[134:137], v229 offset:18432
	ds_read_b128 v[142:145], v229 offset:19456
	ds_read_b128 v[184:187], v229 offset:20480
	ds_read_b128 v[188:191], v229 offset:21504
	ds_read_b128 v[192:195], v229 offset:22528
	ds_read_b128 v[196:199], v229 offset:23552
	global_load_lds_dwordx4 v[172:173], off
	v_lshl_add_u64 v[174:175], s[10:11], 0, v[178:179]
	s_mov_b32 m0, s45
	s_nop 0
	global_load_lds_dwordx4 v[174:175], off
	s_barrier
	s_waitcnt lgkmcnt(0)
	s_nop 0
	s_waitcnt lgkmcnt(0)
	s_cmp_lg_u32 s99, 0
	s_cbranch_scc1 .Lfu_skip3
	v_mfma_f32_16x16x32_bf16 v[62:65], v[66:69], v[118:121], v[62:65]
	v_mfma_f32_16x16x32_bf16 v[58:61], v[74:77], v[118:121], v[58:61]
	v_mfma_f32_16x16x32_bf16 v[50:53], v[66:69], v[134:137], v[50:53]
	v_mfma_f32_16x16x32_bf16 v[42:45], v[74:77], v[134:137], v[42:45]
	v_mfma_f32_16x16x32_bf16 v[34:37], v[66:69], v[184:187], v[34:37]
	v_mfma_f32_16x16x32_bf16 v[26:29], v[74:77], v[184:187], v[26:29]
	v_mfma_f32_16x16x32_bf16 v[14:17], v[66:69], v[192:195], v[14:17]
	v_mfma_f32_16x16x32_bf16 v[10:13], v[74:77], v[192:195], v[10:13]
	v_mfma_f32_16x16x32_bf16 v[62:65], v[70:73], v[126:129], v[62:65]
	v_mfma_f32_16x16x32_bf16 v[58:61], v[78:81], v[126:129], v[58:61]
	v_mfma_f32_16x16x32_bf16 v[50:53], v[70:73], v[142:145], v[50:53]
	v_mfma_f32_16x16x32_bf16 v[42:45], v[78:81], v[142:145], v[42:45]
	v_mfma_f32_16x16x32_bf16 v[34:37], v[70:73], v[188:191], v[34:37]
	v_mfma_f32_16x16x32_bf16 v[26:29], v[78:81], v[188:191], v[26:29]
	v_mfma_f32_16x16x32_bf16 v[14:17], v[70:73], v[196:199], v[14:17]
	v_mfma_f32_16x16x32_bf16 v[10:13], v[78:81], v[196:199], v[10:13]
.Lfu_skip3:
	s_nop 0
	s_barrier
	s_add_u32 s54, s8, 0x40000
	s_addc_u32 s55, s9, 0
	s_add_i32 s41, s53, s43
	v_lshl_add_u64 v[66:67], s[54:55], 0, v[176:177]
	s_mov_b32 m0, s41
	s_nop 0
	global_load_lds_dwordx4 v[66:67], off
	v_lshl_add_u64 v[66:67], s[54:55], 0, v[178:179]
	s_add_i32 m0, s41, 0x2000
	s_nop 0
	global_load_lds_dwordx4 v[66:67], off
	s_waitcnt vmcnt(6)
	s_barrier
	s_nop 0
	s_cmp_lg_u32 s99, 0
	s_cbranch_scc1 .Lfu_skip4
	v_mfma_f32_16x16x32_bf16 v[54:57], v[230:233], v[118:121], v[54:57]
	v_mfma_f32_16x16x32_bf16 v[46:49], v[238:241], v[118:121], v[46:49]
	v_mfma_f32_16x16x32_bf16 v[38:41], v[230:233], v[134:137], v[38:41]
	v_mfma_f32_16x16x32_bf16 v[30:33], v[238:241], v[134:137], v[30:33]
	v_mfma_f32_16x16x32_bf16 v[22:25], v[230:233], v[184:187], v[22:25]
	v_mfma_f32_16x16x32_bf16 v[18:21], v[238:241], v[184:187], v[18:21]
	v_mfma_f32_16x16x32_bf16 v[6:9], v[230:233], v[192:195], v[6:9]
	v_mfma_f32_16x16x32_bf16 v[2:5], v[238:241], v[192:195], v[2:5]
	v_mfma_f32_16x16x32_bf16 v[54:57], v[234:237], v[126:129], v[54:57]
	v_mfma_f32_16x16x32_bf16 v[46:49], v[242:245], v[126:129], v[46:49]
	v_mfma_f32_16x16x32_bf16 v[38:41], v[234:237], v[142:145], v[38:41]
	v_mfma_f32_16x16x32_bf16 v[30:33], v[242:245], v[142:145], v[30:33]
	v_mfma_f32_16x16x32_bf16 v[22:25], v[234:237], v[188:191], v[22:25]
	v_mfma_f32_16x16x32_bf16 v[18:21], v[242:245], v[188:191], v[18:21]
	v_mfma_f32_16x16x32_bf16 v[6:9], v[234:237], v[196:199], v[6:9]
	v_mfma_f32_16x16x32_bf16 v[2:5], v[242:245], v[196:199], v[2:5]
.Lfu_skip4:
	s_nop 0
	s_add_i32 s41, 0, 0x18000
	v_add_u32_e32 v0, s41, v169
	s_barrier
	ds_read_b128 v[66:69], v0
	ds_read_b128 v[70:73], v0 offset:1024
	ds_read_b128 v[74:77], v0 offset:2048
	ds_read_b128 v[78:81], v0 offset:3072
	s_add_u32 s10, s10, 0x40000
	s_addc_u32 s11, s11, 0
	s_mov_b32 m0, s46
	v_lshl_add_u64 v[134:135], s[10:11], 0, v[176:177]
	ds_read_b128 v[118:121], v229 offset:32768
	ds_read_b128 v[126:129], v229 offset:33792
	ds_read_b128 v[184:187], v229 offset:34816
	ds_read_b128 v[188:191], v229 offset:35840
	ds_read_b128 v[192:195], v229 offset:36864
	ds_read_b128 v[196:199], v229 offset:37888
	ds_read_b128 v[230:233], v229 offset:38912
	ds_read_b128 v[234:237], v229 offset:39936
	global_load_lds_dwordx4 v[134:135], off
	v_lshl_add_u64 v[134:135], s[10:11], 0, v[178:179]
	s_mov_b32 m0, s47
	s_nop 0
	global_load_lds_dwordx4 v[134:135], off
	s_waitcnt lgkmcnt(8)
	s_barrier
	s_waitcnt lgkmcnt(0)
	s_nop 0
	s_waitcnt lgkmcnt(0)
	v_mfma_f32_16x16x32_bf16 v[134:137], v[66:69], v[118:121], v[158:161]
	v_mfma_f32_16x16x32_bf16 v[158:161], v[70:73], v[126:129], v[134:137]
	v_mfma_f32_16x16x32_bf16 v[134:137], v[74:77], v[118:121], v[154:157]
	v_mfma_f32_16x16x32_bf16 v[154:157], v[78:81], v[126:129], v[134:137]
	v_mfma_f32_16x16x32_bf16 v[134:137], v[66:69], v[184:187], v[146:149]
	v_mfma_f32_16x16x32_bf16 v[146:149], v[70:73], v[188:191], v[134:137]
	v_mfma_f32_16x16x32_bf16 v[134:137], v[74:77], v[184:187], v[138:141]
	v_mfma_f32_16x16x32_bf16 v[130:133], v[66:69], v[192:195], v[130:133]
	v_mfma_f32_16x16x32_bf16 v[122:125], v[74:77], v[192:195], v[122:125]
	v_mfma_f32_16x16x32_bf16 v[110:113], v[66:69], v[230:233], v[110:113]
	v_mfma_f32_16x16x32_bf16 v[106:109], v[74:77], v[230:233], v[106:109]
	v_mfma_f32_16x16x32_bf16 v[138:141], v[78:81], v[188:191], v[134:137]
	v_mfma_f32_16x16x32_bf16 v[130:133], v[70:73], v[196:199], v[130:133]
	v_mfma_f32_16x16x32_bf16 v[122:125], v[78:81], v[196:199], v[122:125]
	v_mfma_f32_16x16x32_bf16 v[110:113], v[70:73], v[234:237], v[110:113]
	v_mfma_f32_16x16x32_bf16 v[106:109], v[78:81], v[234:237], v[106:109]
	s_nop 0
	s_barrier
	s_add_i32 s10, 0, 0x1c000
	s_add_i32 s11, s41, s43
	v_add_u32_e32 v0, s10, v169
	v_lshl_add_u64 v[134:135], v[200:201], 0, s[92:93]
	s_mov_b32 m0, s11
	ds_read_b128 v[238:241], v0
	ds_read_b128 v[242:245], v0 offset:1024
	ds_read_b128 v[246:249], v0 offset:2048
	ds_read_b128 v[250:253], v0 offset:3072
	global_load_lds_dwordx4 v[134:135], off
	v_lshl_add_u64 v[134:135], v[210:211], 0, s[92:93]
	s_add_i32 m0, s11, 0x2000
	s_nop 0
	global_load_lds_dwordx4 v[134:135], off
	s_barrier
	s_waitcnt lgkmcnt(0)
	s_nop 0
	s_waitcnt lgkmcnt(0)
	v_mfma_f32_16x16x32_bf16 v[82:85], v[246:249], v[118:121], v[82:85]
	v_mfma_f32_16x16x32_bf16 v[134:137], v[238:241], v[118:121], v[150:153]
	v_mfma_f32_16x16x32_bf16 v[142:145], v[250:253], v[126:129], v[82:85]
	v_mfma_f32_16x16x32_bf16 v[82:85], v[238:241], v[184:187], v[86:89]
	v_mfma_f32_16x16x32_bf16 v[150:153], v[242:245], v[126:129], v[134:137]
	v_mfma_f32_16x16x32_bf16 v[134:137], v[242:245], v[188:191], v[82:85]
	v_mfma_f32_16x16x32_bf16 v[82:85], v[246:249], v[184:187], v[90:93]
	v_mfma_f32_16x16x32_bf16 v[126:129], v[250:253], v[188:191], v[82:85]
	v_mfma_f32_16x16x32_bf16 v[82:85], v[238:241], v[192:195], v[94:97]
	v_mfma_f32_16x16x32_bf16 v[118:121], v[242:245], v[196:199], v[82:85]
	v_mfma_f32_16x16x32_bf16 v[82:85], v[246:249], v[192:195], v[114:117]
	v_mfma_f32_16x16x32_bf16 v[114:117], v[250:253], v[196:199], v[82:85]
	v_mfma_f32_16x16x32_bf16 v[82:85], v[238:241], v[230:233], v[102:105]
	v_mfma_f32_16x16x32_bf16 v[102:105], v[242:245], v[234:237], v[82:85]
	v_mfma_f32_16x16x32_bf16 v[82:85], v[246:249], v[230:233], v[98:101]
	v_mfma_f32_16x16x32_bf16 v[98:101], v[250:253], v[234:237], v[82:85]
	s_nop 0
	s_mov_b32 m0, s48
	v_lshl_add_u64 v[172:173], v[172:173], 0, s[92:93]
	s_barrier
	s_nop 2
	ds_read_b128 v[82:85], v229 offset:49152
	ds_read_b128 v[86:89], v229 offset:50176
	ds_read_b128 v[90:93], v229 offset:51200
	ds_read_b128 v[94:97], v229 offset:52224
	ds_read_b128 v[184:187], v229 offset:53248
	ds_read_b128 v[188:191], v229 offset:54272
	ds_read_b128 v[192:195], v229 offset:55296
	ds_read_b128 v[196:199], v229 offset:56320
	global_load_lds_dwordx4 v[172:173], off
	v_lshl_add_u64 v[172:173], v[174:175], 0, s[92:93]
	s_mov_b32 m0, s49
	s_nop 0
	global_load_lds_dwordx4 v[172:173], off
	s_barrier
	s_waitcnt lgkmcnt(0)
	s_nop 0
	s_waitcnt lgkmcnt(0)
	s_cmp_lg_u32 s99, 0
	s_cbranch_scc1 .Lfu_skip7
	v_mfma_f32_16x16x32_bf16 v[62:65], v[66:69], v[82:85], v[62:65]
	v_mfma_f32_16x16x32_bf16 v[58:61], v[74:77], v[82:85], v[58:61]
	v_mfma_f32_16x16x32_bf16 v[50:53], v[66:69], v[90:93], v[50:53]
	v_mfma_f32_16x16x32_bf16 v[42:45], v[74:77], v[90:93], v[42:45]
	v_mfma_f32_16x16x32_bf16 v[34:37], v[66:69], v[184:187], v[34:37]
	v_mfma_f32_16x16x32_bf16 v[26:29], v[74:77], v[184:187], v[26:29]
	v_mfma_f32_16x16x32_bf16 v[14:17], v[66:69], v[192:195], v[14:17]
	v_mfma_f32_16x16x32_bf16 v[10:13], v[74:77], v[192:195], v[10:13]
	v_mfma_f32_16x16x32_bf16 v[62:65], v[70:73], v[86:89], v[62:65]
	v_mfma_f32_16x16x32_bf16 v[58:61], v[78:81], v[86:89], v[58:61]
	v_mfma_f32_16x16x32_bf16 v[50:53], v[70:73], v[94:97], v[50:53]
	v_mfma_f32_16x16x32_bf16 v[42:45], v[78:81], v[94:97], v[42:45]
	v_mfma_f32_16x16x32_bf16 v[34:37], v[70:73], v[188:191], v[34:37]
	v_mfma_f32_16x16x32_bf16 v[26:29], v[78:81], v[188:191], v[26:29]
	v_mfma_f32_16x16x32_bf16 v[14:17], v[70:73], v[196:199], v[14:17]
	v_mfma_f32_16x16x32_bf16 v[10:13], v[78:81], v[196:199], v[10:13]
.Lfu_skip7:
	s_nop 0
	s_barrier
	s_add_u32 s8, s8, 0x40080
	s_addc_u32 s9, s9, 0
	s_add_i32 s10, s10, s43
	v_lshl_add_u64 v[66:67], s[8:9], 0, v[176:177]
	s_mov_b32 m0, s10
	s_nop 0
	global_load_lds_dwordx4 v[66:67], off
	v_lshl_add_u64 v[66:67], s[8:9], 0, v[178:179]
	s_add_i32 m0, s10, 0x2000
	s_nop 0
	global_load_lds_dwordx4 v[66:67], off
	s_waitcnt vmcnt(6)
	s_cmp_lg_u32 s40, 0
	s_cbranch_scc1 .Lcw_skip
	v_and_b32_e32 v66, 31, v163
	v_lshlrev_b32_e32 v66, 4, v66
	s_lshl_b32 s8, s13, 9
	v_add_u32_e32 v66, s8, v66
	s_mov_b64 s[10:11], exec
	s_mov_b32 exec_lo, -1
	s_mov_b32 exec_hi, 0
	s_mov_b32 m0, 0x20000
	s_nop 0
	global_load_lds_dwordx4 v66, s[26:27]
	s_mov_b32 m0, 0x20200
	s_nop 0
	global_load_lds_dwordx4 v66, s[36:37]
	s_mov_b32 m0, 0x20400
	s_nop 0
	global_load_lds_dwordx4 v66, s[38:39]
	s_mov_b32 m0, 0x20600
	s_nop 0
	global_load_lds_dwordx4 v66, s[28:29]
	s_mov_b64 exec, s[10:11]
.Lcw_skip:
	s_barrier
	s_nop 0
	s_cmp_lg_u32 s99, 0
	s_cbranch_scc1 .Lfu_skip8
	v_mfma_f32_16x16x32_bf16 v[54:57], v[238:241], v[82:85], v[54:57]
	v_mfma_f32_16x16x32_bf16 v[46:49], v[246:249], v[82:85], v[46:49]
	v_mfma_f32_16x16x32_bf16 v[38:41], v[238:241], v[90:93], v[38:41]
	v_mfma_f32_16x16x32_bf16 v[30:33], v[246:249], v[90:93], v[30:33]
	v_mfma_f32_16x16x32_bf16 v[22:25], v[238:241], v[184:187], v[22:25]
	v_mfma_f32_16x16x32_bf16 v[18:21], v[246:249], v[184:187], v[18:21]
	v_mfma_f32_16x16x32_bf16 v[6:9], v[238:241], v[192:195], v[6:9]
	v_mfma_f32_16x16x32_bf16 v[2:5], v[246:249], v[192:195], v[2:5]
	v_mfma_f32_16x16x32_bf16 v[54:57], v[242:245], v[86:89], v[54:57]
	v_mfma_f32_16x16x32_bf16 v[46:49], v[250:253], v[86:89], v[46:49]
	v_mfma_f32_16x16x32_bf16 v[38:41], v[242:245], v[94:97], v[38:41]
	v_mfma_f32_16x16x32_bf16 v[30:33], v[250:253], v[94:97], v[30:33]
	v_mfma_f32_16x16x32_bf16 v[22:25], v[242:245], v[188:191], v[22:25]
	v_mfma_f32_16x16x32_bf16 v[18:21], v[250:253], v[188:191], v[18:21]
	v_mfma_f32_16x16x32_bf16 v[6:9], v[242:245], v[196:199], v[6:9]
	v_mfma_f32_16x16x32_bf16 v[2:5], v[250:253], v[196:199], v[2:5]
.Lfu_skip8:
	s_nop 0
	s_add_i32 s40, s40, 2
	s_add_u32 s23, s23, 0x100
	s_addc_u32 s25, s25, 0
	s_add_u32 s6, s6, 0x100
	s_addc_u32 s7, s7, 0
	s_cmp_gt_u32 s40, 13
	s_barrier
	s_cbranch_scc0 .LBB0_56
	s_setprio 0
	v_mov_b32_e32 v0, v163
	v_lshrrev_b32_e32 v66, 1, v0
	v_and_b32_e32 v66, 0x78, v66
	v_lshlrev_b32_e32 v200, 2, v66
	v_add_u32_e32 v200, 0x20000, v200
	v_lshl_or_b32 v184, s13, 7, v66
	v_ashrrev_i32_e32 v185, 31, v184
	ds_read_b128 v[66:69], v200 offset:16
	ds_read_b128 v[82:85], v200
	ds_read_b128 v[70:73], v200 offset:528
	ds_read_b128 v[86:89], v200 offset:512
	ds_read_b128 v[74:77], v200 offset:1040
	ds_read_b128 v[90:93], v200 offset:1024
	ds_read_b128 v[78:81], v200 offset:1552
	ds_read_b128 v[94:97], v200 offset:1536
	v_and_b32_e32 v230, 15, v0
	v_ashrrev_i32_e32 v0, 2, v0
	v_and_b32_e32 v0, 0xffffffc0, v0
	v_lshl_add_u32 v231, s12, 8, v0
	v_readlane_b32 s98, v254, 0
	s_and_b32 s98, s98, s99
	s_lshl_b32 s98, s98, 7
	v_add_u32_e32 v231, s98, v231
	v_mov_b32_dpp v186, v134 row_ror:15 row_mask:0xf bank_mask:0xf
	v_mov_b32_e32 v188, v1
	v_mov_b32_dpp v187, v135 row_ror:15 row_mask:0xf bank_mask:0xf
	v_mov_b32_e32 v189, v1
	v_mov_b32_dpp v194, v136 row_ror:15 row_mask:0xf bank_mask:0xf
	v_mov_b32_e32 v196, v1
	v_mov_b32_dpp v195, v137 row_ror:15 row_mask:0xf bank_mask:0xf
	v_mov_b32_e32 v197, v1
	v_mov_b32_dpp v198, v126 row_ror:15 row_mask:0xf bank_mask:0xf
	v_mov_b32_e32 v200, v1
	v_mov_b32_dpp v199, v127 row_ror:15 row_mask:0xf bank_mask:0xf
	v_mov_b32_e32 v201, v1
	v_mov_b32_dpp v190, v128 row_ror:15 row_mask:0xf bank_mask:0xf
	v_mov_b32_e32 v192, v1
	v_mov_b32_dpp v191, v129 row_ror:15 row_mask:0xf bank_mask:0xf
	v_mov_b32_e32 v193, v1
	v_or_b32_e32 v0, v231, v230
	v_mov_b32_dpp v188, v150 row_shr:1 row_mask:0xf bank_mask:0xf
	v_mov_b32_dpp v186, v150 row_shl:1 row_mask:0xf bank_mask:0xf
	v_mov_b32_dpp v189, v151 row_shr:1 row_mask:0xf bank_mask:0xf
	v_mov_b32_dpp v187, v151 row_shl:1 row_mask:0xf bank_mask:0xf
	v_mov_b32_dpp v196, v152 row_shr:1 row_mask:0xf bank_mask:0xf
	v_mov_b32_dpp v194, v152 row_shl:1 row_mask:0xf bank_mask:0xf
	v_mov_b32_dpp v197, v153 row_shr:1 row_mask:0xf bank_mask:0xf
	v_mov_b32_dpp v195, v153 row_shl:1 row_mask:0xf bank_mask:0xf
	v_mov_b32_dpp v200, v142 row_shr:1 row_mask:0xf bank_mask:0xf
	v_mov_b32_dpp v198, v142 row_shl:1 row_mask:0xf bank_mask:0xf
	v_mov_b32_dpp v201, v143 row_shr:1 row_mask:0xf bank_mask:0xf
	v_mov_b32_dpp v199, v143 row_shl:1 row_mask:0xf bank_mask:0xf
	v_mov_b32_dpp v192, v144 row_shr:1 row_mask:0xf bank_mask:0xf
	v_mov_b32_dpp v190, v144 row_shl:1 row_mask:0xf bank_mask:0xf
	v_mov_b32_dpp v193, v145 row_shr:1 row_mask:0xf bank_mask:0xf
	v_mov_b32_dpp v191, v145 row_shl:1 row_mask:0xf bank_mask:0xf
	v_cmp_eq_u32_e64 s[6:7], 0, v230
	v_cmp_ne_u32_e64 s[10:11], 0, v230
	s_and_saveexec_b64 s[8:9], s[10:11]
	s_cbranch_execz .LBB0_59
	s_waitcnt lgkmcnt(0)
	v_pk_fma_f32 v[200:201], v[66:67], v[200:201], v[78:79]
	v_pk_fma_f32 v[196:197], v[84:85], v[196:197], v[96:97]
	v_pk_fma_f32 v[200:201], v[142:143], v[70:71], v[200:201]
	v_pk_fma_f32 v[196:197], v[152:153], v[88:89], v[196:197]
	v_pk_fma_f32 v[198:199], v[74:75], v[198:199], v[200:201]
	v_pk_fma_f32 v[194:195], v[92:93], v[194:195], v[196:197]
	v_mul_f32_e32 v172, 0xbfb8aa3b, v198
	v_exp_f32_e32 v172, v172
	v_mul_f32_e32 v173, 0xbfb8aa3b, v199
	v_exp_f32_e32 v173, v173
	v_pk_fma_f32 v[188:189], v[82:83], v[188:189], v[94:95]
	v_add_f32_e32 v172, 1.0, v172
	v_rcp_f32_e32 v200, v172
	v_add_f32_e32 v173, 1.0, v173
	v_mul_f32_e32 v172, 0xbfb8aa3b, v194
	v_rcp_f32_e32 v201, v173
	v_exp_f32_e32 v172, v172
	v_mul_f32_e32 v173, 0xbfb8aa3b, v195
	v_exp_f32_e32 v173, v173
	v_pk_mul_f32 v[198:199], v[198:199], v[200:201]
	v_add_f32_e32 v172, 1.0, v172
	v_pk_fma_f32 v[188:189], v[150:151], v[86:87], v[188:189]
	v_pk_mul_f32 v[196:197], v[154:155], v[198:199]
	v_rcp_f32_e32 v198, v172
	v_add_f32_e32 v172, 1.0, v173
	v_pk_fma_f32 v[186:187], v[90:91], v[186:187], v[188:189]
	v_rcp_f32_e32 v199, v172
	v_mul_f32_e32 v172, 0xbfb8aa3b, v186
	v_exp_f32_e32 v172, v172
	v_mul_f32_e32 v173, 0xbfb8aa3b, v187
	v_exp_f32_e32 v173, v173
	v_pk_fma_f32 v[192:193], v[68:69], v[192:193], v[80:81]
	v_add_f32_e32 v172, 1.0, v172
	v_pk_fma_f32 v[192:193], v[144:145], v[72:73], v[192:193]
	v_pk_mul_f32 v[188:189], v[194:195], v[198:199]
	v_pk_fma_f32 v[190:191], v[76:77], v[190:191], v[192:193]
	v_rcp_f32_e32 v194, v172
	v_add_f32_e32 v172, 1.0, v173
	v_mul_f32_e32 v173, 0xbfb8aa3b, v190
	v_exp_f32_e32 v173, v173
	v_mul_f32_e32 v174, 0xbfb8aa3b, v191
	v_exp_f32_e32 v174, v174
	v_rcp_f32_e32 v195, v172
	v_add_f32_e32 v172, 1.0, v173
	v_rcp_f32_e32 v192, v172
	v_add_f32_e32 v172, 1.0, v174
	v_rcp_f32_e32 v193, v172
	v_readlane_b32 s12, v254, 35
	v_readlane_b32 s13, v254, 36
	v_pk_mul_f32 v[186:187], v[186:187], v[194:195]
	v_pk_mul_f32 v[190:191], v[190:191], v[192:193]
	v_mov_b64_e32 v[192:193], s[12:13]
	s_movk_i32 s12, 0x1600
	v_pk_mul_f32 v[188:189], v[160:161], v[188:189]
	v_pk_mul_f32 v[186:187], v[158:159], v[186:187]
	v_pk_mul_f32 v[190:191], v[156:157], v[190:191]
	v_mad_i64_i32 v[192:193], s[12:13], v0, s12, v[192:193]
	v_lshl_add_u64 v[192:193], v[184:185], 1, v[192:193]
	v_cvt_pk_bf16_f32 v186, v186, v187
	v_cvt_pk_bf16_f32 v187, v188, v189
	v_cvt_pk_bf16_f32 v188, v196, v197
	v_cvt_pk_bf16_f32 v189, v190, v191
	global_store_dwordx4 v[192:193], v[186:189], off

.LBB0_345:
	s_ashr_i32 s15, s14, 31
	v_cmp_lt_i64_e32 vcc, s[16:17], v[166:167]
	s_lshl_b64 s[16:17], s[14:15], 19
	v_readlane_b32 s18, v254, 33
	v_readlane_b32 s19, v254, 34
	s_add_u32 s16, s18, s16
	s_addc_u32 s17, s19, s17
	s_and_b64 s[18:19], vcc, exec
	s_cselect_b32 s15, s17, s23
	s_cselect_b32 s45, s16, s22
	s_ashr_i32 s13, s12, 31
	s_lshl_b64 s[18:19], s[12:13], 19
	s_add_u32 s18, s3, s18
	s_addc_u32 s19, s30, s19
	s_and_b64 s[26:27], vcc, exec
	s_cselect_b32 s13, s19, s25
	s_cselect_b32 s46, s18, s24
	s_add_u32 s47, s24, 0x100
	v_mov_b32_e32 v2, 0
	s_addc_u32 s48, s25, 0
	s_mov_b32 s49, -2
	v_mov_b32_e32 v3, v2
	v_mov_b32_e32 v4, v2
	v_mov_b32_e32 v5, v2
	v_mov_b32_e32 v6, v2
	v_mov_b32_e32 v7, v2
	v_mov_b32_e32 v8, v2
	v_mov_b32_e32 v9, v2
	v_mov_b32_e32 v10, v2
	v_mov_b32_e32 v11, v2
	v_mov_b32_e32 v12, v2
	v_mov_b32_e32 v13, v2
	v_mov_b32_e32 v14, v2
	v_mov_b32_e32 v15, v2
	v_mov_b32_e32 v16, v2
	v_mov_b32_e32 v17, v2
	v_mov_b32_e32 v34, v2
	v_mov_b32_e32 v35, v2
	v_mov_b32_e32 v36, v2
	v_mov_b32_e32 v37, v2
	v_mov_b32_e32 v38, v2
	v_mov_b32_e32 v39, v2
	v_mov_b32_e32 v40, v2
	v_mov_b32_e32 v41, v2
	v_mov_b32_e32 v46, v2
	v_mov_b32_e32 v47, v2
	v_mov_b32_e32 v48, v2
	v_mov_b32_e32 v49, v2
	v_mov_b32_e32 v50, v2
	v_mov_b32_e32 v51, v2
	v_mov_b32_e32 v52, v2
	v_mov_b32_e32 v53, v2
	v_mov_b32_e32 v18, v2
	v_mov_b32_e32 v19, v2
	v_mov_b32_e32 v20, v2
	v_mov_b32_e32 v21, v2
	v_mov_b32_e32 v22, v2
	v_mov_b32_e32 v23, v2
	v_mov_b32_e32 v24, v2
	v_mov_b32_e32 v25, v2
	v_mov_b32_e32 v26, v2
	v_mov_b32_e32 v27, v2
	v_mov_b32_e32 v28, v2
	v_mov_b32_e32 v29, v2
	v_mov_b32_e32 v30, v2
	v_mov_b32_e32 v31, v2
	v_mov_b32_e32 v32, v2
	v_mov_b32_e32 v33, v2
	v_mov_b32_e32 v42, v2
	v_mov_b32_e32 v43, v2
	v_mov_b32_e32 v44, v2
	v_mov_b32_e32 v45, v2
	v_mov_b32_e32 v54, v2
	v_mov_b32_e32 v55, v2
	v_mov_b32_e32 v56, v2
	v_mov_b32_e32 v57, v2
	v_mov_b32_e32 v58, v2
	v_mov_b32_e32 v59, v2
	v_mov_b32_e32 v60, v2
	v_mov_b32_e32 v61, v2
	v_mov_b32_e32 v62, v2
	v_mov_b32_e32 v63, v2
	v_mov_b32_e32 v64, v2
	v_mov_b32_e32 v65, v2
	v_mov_b32_e32 v66, v2
	v_mov_b32_e32 v67, v2
	v_mov_b32_e32 v68, v2
	v_mov_b32_e32 v69, v2
	v_mov_b32_e32 v70, v2
	v_mov_b32_e32 v71, v2
	v_mov_b32_e32 v72, v2
	v_mov_b32_e32 v73, v2
	v_mov_b32_e32 v78, v2
	v_mov_b32_e32 v79, v2
	v_mov_b32_e32 v80, v2
	v_mov_b32_e32 v81, v2
	v_mov_b32_e32 v82, v2
	v_mov_b32_e32 v83, v2
	v_mov_b32_e32 v84, v2
	v_mov_b32_e32 v85, v2
	v_mov_b32_e32 v114, v2
	v_mov_b32_e32 v115, v2
	v_mov_b32_e32 v116, v2
	v_mov_b32_e32 v117, v2
	v_mov_b32_e32 v118, v2
	v_mov_b32_e32 v119, v2
	v_mov_b32_e32 v120, v2
	v_mov_b32_e32 v121, v2
	v_mov_b32_e32 v126, v2
	v_mov_b32_e32 v127, v2
	v_mov_b32_e32 v128, v2
	v_mov_b32_e32 v129, v2
	v_mov_b32_e32 v130, v2
	v_mov_b32_e32 v131, v2
	v_mov_b32_e32 v132, v2
	v_mov_b32_e32 v133, v2
	v_mov_b32_e32 v74, v2
	v_mov_b32_e32 v75, v2
	v_mov_b32_e32 v76, v2
	v_mov_b32_e32 v77, v2
	v_mov_b32_e32 v86, v2
	v_mov_b32_e32 v87, v2
	v_mov_b32_e32 v88, v2
	v_mov_b32_e32 v89, v2
	v_mov_b32_e32 v90, v2
	v_mov_b32_e32 v91, v2
	v_mov_b32_e32 v92, v2
	v_mov_b32_e32 v93, v2
	v_mov_b32_e32 v94, v2
	v_mov_b32_e32 v95, v2
	v_mov_b32_e32 v96, v2
	v_mov_b32_e32 v97, v2
	v_mov_b32_e32 v122, v2
	v_mov_b32_e32 v123, v2
	v_mov_b32_e32 v124, v2
	v_mov_b32_e32 v125, v2
	v_mov_b32_e32 v134, v2
	v_mov_b32_e32 v135, v2
	v_mov_b32_e32 v136, v2
	v_mov_b32_e32 v137, v2
	v_mov_b32_e32 v138, v2
	v_mov_b32_e32 v139, v2
	v_mov_b32_e32 v140, v2
	v_mov_b32_e32 v141, v2
	v_mov_b32_e32 v142, v2
	v_mov_b32_e32 v143, v2
	v_mov_b32_e32 v144, v2
	v_mov_b32_e32 v145, v2
	v_cmp_lt_u32_e32 vcc, 0xff, v163
	s_nop 1
	s_cbranch_vccz .Lsprio_skip1
	s_setprio 1
.Lsprio_skip1:
.LBB0_346:
	s_add_u32 s24, s22, 0x100
	s_addc_u32 s25, s23, 0
	s_add_i32 s50, 0, 0x10000
	v_add_u32_e32 v110, s50, v160
	ds_read_b128 v[98:101], v110
	ds_read_b128 v[102:105], v110 offset:1024
	ds_read_b128 v[106:109], v110 offset:2048
	ds_read_b128 v[110:113], v110 offset:3072
	s_cmp_eq_u32 s49, 12
	s_cselect_b32 s29, s15, s25
	s_cselect_b32 s28, s45, s24
	s_cselect_b32 s27, s13, s48
	s_cselect_b32 s26, s46, s47
	v_lshl_add_u64 v[200:201], s[22:23], 0, v[150:151]
	s_add_i32 m0, s35, 0xc000
	ds_read_b128 v[152:155], v161
	ds_read_b128 v[156:159], v161 offset:1024
	ds_read_b128 v[176:179], v161 offset:2048
	ds_read_b128 v[180:183], v161 offset:3072
	ds_read_b128 v[184:187], v161 offset:4096
	ds_read_b128 v[188:191], v161 offset:5120
	ds_read_b128 v[192:195], v161 offset:6144
	ds_read_b128 v[196:199], v161 offset:7168
	global_load_lds_dwordx4 v[200:201], off
	v_lshl_add_u64 v[200:201], s[22:23], 0, v[148:149]
	s_add_i32 m0, s35, 0xe000
	s_nop 0
	global_load_lds_dwordx4 v[200:201], off
	s_waitcnt lgkmcnt(8)
	s_barrier
	s_waitcnt lgkmcnt(0)
	s_nop 0
	s_waitcnt lgkmcnt(0)
	v_mfma_f32_16x16x32_bf16 v[142:145], v[98:101], v[152:155], v[142:145]
	v_mfma_f32_16x16x32_bf16 v[138:141], v[106:109], v[152:155], v[138:141]
	v_mfma_f32_16x16x32_bf16 v[134:137], v[98:101], v[176:179], v[134:137]
	v_mfma_f32_16x16x32_bf16 v[122:125], v[106:109], v[176:179], v[122:125]
	v_mfma_f32_16x16x32_bf16 v[94:97], v[98:101], v[184:187], v[94:97]
	v_mfma_f32_16x16x32_bf16 v[90:93], v[106:109], v[184:187], v[90:93]
	v_mfma_f32_16x16x32_bf16 v[86:89], v[98:101], v[192:195], v[86:89]
	v_mfma_f32_16x16x32_bf16 v[74:77], v[106:109], v[192:195], v[74:77]
	v_mfma_f32_16x16x32_bf16 v[142:145], v[102:105], v[156:159], v[142:145]
	v_mfma_f32_16x16x32_bf16 v[138:141], v[110:113], v[156:159], v[138:141]
	v_mfma_f32_16x16x32_bf16 v[134:137], v[102:105], v[180:183], v[134:137]
	v_mfma_f32_16x16x32_bf16 v[122:125], v[110:113], v[180:183], v[122:125]
	v_mfma_f32_16x16x32_bf16 v[94:97], v[102:105], v[188:191], v[94:97]
	v_mfma_f32_16x16x32_bf16 v[90:93], v[110:113], v[188:191], v[90:93]
	v_mfma_f32_16x16x32_bf16 v[86:89], v[102:105], v[196:199], v[86:89]
	v_mfma_f32_16x16x32_bf16 v[74:77], v[110:113], v[196:199], v[74:77]
	s_nop 0
	s_barrier
	s_add_i32 s51, 0, 0x14000
	s_add_i32 s22, s50, s31
	v_add_u32_e32 v169, s51, v160
	v_lshl_add_u64 v[200:201], s[26:27], 0, v[0:1]
	s_mov_b32 m0, s22
	ds_read_b128 v[230:233], v169
	ds_read_b128 v[234:237], v169 offset:1024
	ds_read_b128 v[238:241], v169 offset:2048
	ds_read_b128 v[242:245], v169 offset:3072
	global_load_lds_dwordx4 v[200:201], off
	v_lshl_add_u64 v[246:247], s[26:27], 0, v[146:147]
	s_add_i32 m0, s22, 0x2000
	s_nop 0
	global_load_lds_dwordx4 v[246:247], off
	s_barrier
	s_waitcnt lgkmcnt(0)
	s_nop 0
	s_waitcnt lgkmcnt(0)
	v_mfma_f32_16x16x32_bf16 v[130:133], v[230:233], v[152:155], v[130:133]
	v_mfma_f32_16x16x32_bf16 v[126:129], v[238:241], v[152:155], v[126:129]
	v_mfma_f32_16x16x32_bf16 v[118:121], v[230:233], v[176:179], v[118:121]
	v_mfma_f32_16x16x32_bf16 v[114:117], v[238:241], v[176:179], v[114:117]
	v_mfma_f32_16x16x32_bf16 v[82:85], v[230:233], v[184:187], v[82:85]
	v_mfma_f32_16x16x32_bf16 v[78:81], v[238:241], v[184:187], v[78:81]
	v_mfma_f32_16x16x32_bf16 v[70:73], v[230:233], v[192:195], v[70:73]
	v_mfma_f32_16x16x32_bf16 v[66:69], v[238:241], v[192:195], v[66:69]
	v_mfma_f32_16x16x32_bf16 v[130:133], v[234:237], v[156:159], v[130:133]
	v_mfma_f32_16x16x32_bf16 v[126:129], v[242:245], v[156:159], v[126:129]
	v_mfma_f32_16x16x32_bf16 v[118:121], v[234:237], v[180:183], v[118:121]
	v_mfma_f32_16x16x32_bf16 v[114:117], v[242:245], v[180:183], v[114:117]
	v_mfma_f32_16x16x32_bf16 v[82:85], v[234:237], v[188:191], v[82:85]
	v_mfma_f32_16x16x32_bf16 v[78:81], v[242:245], v[188:191], v[78:81]
	v_mfma_f32_16x16x32_bf16 v[70:73], v[234:237], v[196:199], v[70:73]
	v_mfma_f32_16x16x32_bf16 v[66:69], v[242:245], v[196:199], v[66:69]
	s_nop 0
	s_mov_b32 m0, s35
	v_lshl_add_u64 v[248:249], s[28:29], 0, v[0:1]
	s_barrier
	ds_read_b128 v[152:155], v161 offset:16384
	ds_read_b128 v[156:159], v161 offset:17408
	ds_read_b128 v[176:179], v161 offset:18432
	ds_read_b128 v[180:183], v161 offset:19456
	ds_read_b128 v[184:187], v161 offset:20480
	ds_read_b128 v[188:191], v161 offset:21504
	ds_read_b128 v[192:195], v161 offset:22528
	ds_read_b128 v[196:199], v161 offset:23552
	global_load_lds_dwordx4 v[248:249], off
	v_lshl_add_u64 v[250:251], s[28:29], 0, v[146:147]
	s_mov_b32 m0, s36
	s_nop 0
	global_load_lds_dwordx4 v[250:251], off
	s_barrier
	s_waitcnt lgkmcnt(0)
	s_nop 0
	s_waitcnt lgkmcnt(0)
	v_mfma_f32_16x16x32_bf16 v[62:65], v[98:101], v[152:155], v[62:65]
	v_mfma_f32_16x16x32_bf16 v[58:61], v[106:109], v[152:155], v[58:61]
	v_mfma_f32_16x16x32_bf16 v[54:57], v[98:101], v[176:179], v[54:57]
	v_mfma_f32_16x16x32_bf16 v[42:45], v[106:109], v[176:179], v[42:45]
	v_mfma_f32_16x16x32_bf16 v[30:33], v[98:101], v[184:187], v[30:33]
	v_mfma_f32_16x16x32_bf16 v[26:29], v[106:109], v[184:187], v[26:29]
	v_mfma_f32_16x16x32_bf16 v[22:25], v[98:101], v[192:195], v[22:25]
	v_mfma_f32_16x16x32_bf16 v[18:21], v[106:109], v[192:195], v[18:21]
	v_mfma_f32_16x16x32_bf16 v[62:65], v[102:105], v[156:159], v[62:65]
	v_mfma_f32_16x16x32_bf16 v[58:61], v[110:113], v[156:159], v[58:61]
	v_mfma_f32_16x16x32_bf16 v[54:57], v[102:105], v[180:183], v[54:57]
	v_mfma_f32_16x16x32_bf16 v[42:45], v[110:113], v[180:183], v[42:45]
	v_mfma_f32_16x16x32_bf16 v[30:33], v[102:105], v[188:191], v[30:33]
	v_mfma_f32_16x16x32_bf16 v[26:29], v[110:113], v[188:191], v[26:29]
	v_mfma_f32_16x16x32_bf16 v[22:25], v[102:105], v[196:199], v[22:25]
	v_mfma_f32_16x16x32_bf16 v[18:21], v[110:113], v[196:199], v[18:21]
	s_nop 0
	s_barrier
	s_add_u32 s22, s26, 0x40000
	s_addc_u32 s23, s27, 0
	s_add_i32 s50, s51, s31
	v_lshl_add_u64 v[98:99], s[22:23], 0, v[0:1]
	s_mov_b32 m0, s50
	s_nop 0
	global_load_lds_dwordx4 v[98:99], off
	v_lshl_add_u64 v[98:99], s[22:23], 0, v[146:147]
	s_add_i32 m0, s50, 0x2000
	s_nop 0
	global_load_lds_dwordx4 v[98:99], off
	s_waitcnt vmcnt(6)
	s_barrier
	s_nop 0
	v_mfma_f32_16x16x32_bf16 v[50:53], v[230:233], v[152:155], v[50:53]
	v_mfma_f32_16x16x32_bf16 v[46:49], v[238:241], v[152:155], v[46:49]
	v_mfma_f32_16x16x32_bf16 v[38:41], v[230:233], v[176:179], v[38:41]
	v_mfma_f32_16x16x32_bf16 v[34:37], v[238:241], v[176:179], v[34:37]
	v_mfma_f32_16x16x32_bf16 v[14:17], v[230:233], v[184:187], v[14:17]
	v_mfma_f32_16x16x32_bf16 v[10:13], v[238:241], v[184:187], v[10:13]
	v_mfma_f32_16x16x32_bf16 v[6:9], v[230:233], v[192:195], v[6:9]
	v_mfma_f32_16x16x32_bf16 v[2:5], v[238:241], v[192:195], v[2:5]
	v_mfma_f32_16x16x32_bf16 v[50:53], v[234:237], v[156:159], v[50:53]
	v_mfma_f32_16x16x32_bf16 v[46:49], v[242:245], v[156:159], v[46:49]
	v_mfma_f32_16x16x32_bf16 v[38:41], v[234:237], v[180:183], v[38:41]
	v_mfma_f32_16x16x32_bf16 v[34:37], v[242:245], v[180:183], v[34:37]
	v_mfma_f32_16x16x32_bf16 v[14:17], v[234:237], v[188:191], v[14:17]
	v_mfma_f32_16x16x32_bf16 v[10:13], v[242:245], v[188:191], v[10:13]
	v_mfma_f32_16x16x32_bf16 v[6:9], v[234:237], v[196:199], v[6:9]
	v_mfma_f32_16x16x32_bf16 v[2:5], v[242:245], v[196:199], v[2:5]
	s_nop 0
	s_add_i32 s50, 0, 0x18000
	v_add_u32_e32 v110, s50, v160
	s_barrier
	ds_read_b128 v[98:101], v110
	ds_read_b128 v[102:105], v110 offset:1024
	ds_read_b128 v[106:109], v110 offset:2048
	ds_read_b128 v[110:113], v110 offset:3072
	s_add_u32 s22, s28, 0x40000
	s_addc_u32 s23, s29, 0
	s_mov_b32 m0, s37
	v_lshl_add_u64 v[230:231], s[22:23], 0, v[0:1]
	ds_read_b128 v[152:155], v161 offset:32768
	ds_read_b128 v[156:159], v161 offset:33792
	ds_read_b128 v[176:179], v161 offset:34816
	ds_read_b128 v[180:183], v161 offset:35840
	ds_read_b128 v[184:187], v161 offset:36864
	ds_read_b128 v[188:191], v161 offset:37888
	ds_read_b128 v[192:195], v161 offset:38912
	ds_read_b128 v[196:199], v161 offset:39936
	global_load_lds_dwordx4 v[230:231], off
	v_lshl_add_u64 v[230:231], s[22:23], 0, v[146:147]
	s_mov_b32 m0, s38
	s_nop 0
	global_load_lds_dwordx4 v[230:231], off
	s_waitcnt lgkmcnt(8)
	s_barrier
	s_waitcnt lgkmcnt(0)
	s_nop 0
	s_waitcnt lgkmcnt(0)
	v_mfma_f32_16x16x32_bf16 v[142:145], v[98:101], v[152:155], v[142:145]
	v_mfma_f32_16x16x32_bf16 v[138:141], v[106:109], v[152:155], v[138:141]
	v_mfma_f32_16x16x32_bf16 v[134:137], v[98:101], v[176:179], v[134:137]
	v_mfma_f32_16x16x32_bf16 v[122:125], v[106:109], v[176:179], v[122:125]
	v_mfma_f32_16x16x32_bf16 v[94:97], v[98:101], v[184:187], v[94:97]
	v_mfma_f32_16x16x32_bf16 v[90:93], v[106:109], v[184:187], v[90:93]
	v_mfma_f32_16x16x32_bf16 v[86:89], v[98:101], v[192:195], v[86:89]
	v_mfma_f32_16x16x32_bf16 v[74:77], v[106:109], v[192:195], v[74:77]
	v_mfma_f32_16x16x32_bf16 v[142:145], v[102:105], v[156:159], v[142:145]
	v_mfma_f32_16x16x32_bf16 v[138:141], v[110:113], v[156:159], v[138:141]
	v_mfma_f32_16x16x32_bf16 v[134:137], v[102:105], v[180:183], v[134:137]
	v_mfma_f32_16x16x32_bf16 v[122:125], v[110:113], v[180:183], v[122:125]
	v_mfma_f32_16x16x32_bf16 v[94:97], v[102:105], v[188:191], v[94:97]
	v_mfma_f32_16x16x32_bf16 v[90:93], v[110:113], v[188:191], v[90:93]
	v_mfma_f32_16x16x32_bf16 v[86:89], v[102:105], v[196:199], v[86:89]
	v_mfma_f32_16x16x32_bf16 v[74:77], v[110:113], v[196:199], v[74:77]
	s_nop 0
	s_barrier
	s_add_i32 s28, 0, 0x1c000
	s_add_i32 s22, s50, s31
	v_add_u32_e32 v169, s28, v160
	v_lshl_add_u64 v[200:201], v[200:201], 0, s[92:93]
	s_mov_b32 m0, s22
	ds_read_b128 v[230:233], v169
	ds_read_b128 v[234:237], v169 offset:1024
	ds_read_b128 v[238:241], v169 offset:2048
	ds_read_b128 v[242:245], v169 offset:3072
	global_load_lds_dwordx4 v[200:201], off
	v_lshl_add_u64 v[200:201], v[246:247], 0, s[92:93]
	s_add_i32 m0, s22, 0x2000
	s_nop 0
	global_load_lds_dwordx4 v[200:201], off
	s_barrier
	s_waitcnt lgkmcnt(0)
	s_nop 0
	s_waitcnt lgkmcnt(0)
	v_mfma_f32_16x16x32_bf16 v[130:133], v[230:233], v[152:155], v[130:133]
	v_mfma_f32_16x16x32_bf16 v[126:129], v[238:241], v[152:155], v[126:129]
	v_mfma_f32_16x16x32_bf16 v[118:121], v[230:233], v[176:179], v[118:121]
	v_mfma_f32_16x16x32_bf16 v[114:117], v[238:241], v[176:179], v[114:117]
	v_mfma_f32_16x16x32_bf16 v[82:85], v[230:233], v[184:187], v[82:85]
	v_mfma_f32_16x16x32_bf16 v[78:81], v[238:241], v[184:187], v[78:81]
	v_mfma_f32_16x16x32_bf16 v[70:73], v[230:233], v[192:195], v[70:73]
	v_mfma_f32_16x16x32_bf16 v[66:69], v[238:241], v[192:195], v[66:69]
	v_mfma_f32_16x16x32_bf16 v[130:133], v[234:237], v[156:159], v[130:133]
	v_mfma_f32_16x16x32_bf16 v[126:129], v[242:245], v[156:159], v[126:129]
	v_mfma_f32_16x16x32_bf16 v[118:121], v[234:237], v[180:183], v[118:121]
	v_mfma_f32_16x16x32_bf16 v[114:117], v[242:245], v[180:183], v[114:117]
	v_mfma_f32_16x16x32_bf16 v[82:85], v[234:237], v[188:191], v[82:85]
	v_mfma_f32_16x16x32_bf16 v[78:81], v[242:245], v[188:191], v[78:81]
	v_mfma_f32_16x16x32_bf16 v[70:73], v[234:237], v[196:199], v[70:73]
	v_mfma_f32_16x16x32_bf16 v[66:69], v[242:245], v[196:199], v[66:69]
	s_nop 0
	s_mov_b32 m0, s41
	v_lshl_add_u64 v[200:201], v[248:249], 0, s[92:93]
	s_barrier
	ds_read_b128 v[152:155], v161 offset:49152
	ds_read_b128 v[156:159], v161 offset:50176
	ds_read_b128 v[176:179], v161 offset:51200
	ds_read_b128 v[180:183], v161 offset:52224
	ds_read_b128 v[184:187], v161 offset:53248
	ds_read_b128 v[188:191], v161 offset:54272
	ds_read_b128 v[192:195], v161 offset:55296
	ds_read_b128 v[196:199], v161 offset:56320
	global_load_lds_dwordx4 v[200:201], off
	v_lshl_add_u64 v[200:201], v[250:251], 0, s[92:93]
	s_mov_b32 m0, s42
	s_nop 0
	global_load_lds_dwordx4 v[200:201], off
	s_barrier
	s_waitcnt lgkmcnt(0)
	s_nop 0
	s_waitcnt lgkmcnt(0)
	v_mfma_f32_16x16x32_bf16 v[62:65], v[98:101], v[152:155], v[62:65]
	v_mfma_f32_16x16x32_bf16 v[58:61], v[106:109], v[152:155], v[58:61]
	v_mfma_f32_16x16x32_bf16 v[54:57], v[98:101], v[176:179], v[54:57]
	v_mfma_f32_16x16x32_bf16 v[42:45], v[106:109], v[176:179], v[42:45]
	v_mfma_f32_16x16x32_bf16 v[30:33], v[98:101], v[184:187], v[30:33]
	v_mfma_f32_16x16x32_bf16 v[26:29], v[106:109], v[184:187], v[26:29]
	v_mfma_f32_16x16x32_bf16 v[22:25], v[98:101], v[192:195], v[22:25]
	v_mfma_f32_16x16x32_bf16 v[18:21], v[106:109], v[192:195], v[18:21]
	v_mfma_f32_16x16x32_bf16 v[62:65], v[102:105], v[156:159], v[62:65]
	v_mfma_f32_16x16x32_bf16 v[58:61], v[110:113], v[156:159], v[58:61]
	v_mfma_f32_16x16x32_bf16 v[54:57], v[102:105], v[180:183], v[54:57]
	v_mfma_f32_16x16x32_bf16 v[42:45], v[110:113], v[180:183], v[42:45]
	v_mfma_f32_16x16x32_bf16 v[30:33], v[102:105], v[188:191], v[30:33]
	v_mfma_f32_16x16x32_bf16 v[26:29], v[110:113], v[188:191], v[26:29]
	v_mfma_f32_16x16x32_bf16 v[22:25], v[102:105], v[196:199], v[22:25]
	v_mfma_f32_16x16x32_bf16 v[18:21], v[110:113], v[196:199], v[18:21]
	s_nop 0
	s_barrier
	s_add_u32 s22, s26, 0x40080
	s_addc_u32 s23, s27, 0
	s_add_i32 s26, s28, s31
	v_lshl_add_u64 v[98:99], s[22:23], 0, v[0:1]
	s_mov_b32 m0, s26
	s_nop 0
	global_load_lds_dwordx4 v[98:99], off
	v_lshl_add_u64 v[98:99], s[22:23], 0, v[146:147]
	s_add_i32 m0, s26, 0x2000
	s_nop 0
	global_load_lds_dwordx4 v[98:99], off
	s_waitcnt vmcnt(6)
	s_barrier
	s_nop 0
	v_mfma_f32_16x16x32_bf16 v[50:53], v[230:233], v[152:155], v[50:53]
	v_mfma_f32_16x16x32_bf16 v[46:49], v[238:241], v[152:155], v[46:49]
	v_mfma_f32_16x16x32_bf16 v[38:41], v[230:233], v[176:179], v[38:41]
	v_mfma_f32_16x16x32_bf16 v[34:37], v[238:241], v[176:179], v[34:37]
	v_mfma_f32_16x16x32_bf16 v[14:17], v[230:233], v[184:187], v[14:17]
	v_mfma_f32_16x16x32_bf16 v[10:13], v[238:241], v[184:187], v[10:13]
	v_mfma_f32_16x16x32_bf16 v[6:9], v[230:233], v[192:195], v[6:9]
	v_mfma_f32_16x16x32_bf16 v[2:5], v[238:241], v[192:195], v[2:5]
	v_mfma_f32_16x16x32_bf16 v[50:53], v[234:237], v[156:159], v[50:53]
	v_mfma_f32_16x16x32_bf16 v[46:49], v[242:245], v[156:159], v[46:49]
	v_mfma_f32_16x16x32_bf16 v[38:41], v[234:237], v[180:183], v[38:41]
	v_mfma_f32_16x16x32_bf16 v[34:37], v[242:245], v[180:183], v[34:37]
	v_mfma_f32_16x16x32_bf16 v[14:17], v[234:237], v[188:191], v[14:17]
	v_mfma_f32_16x16x32_bf16 v[10:13], v[242:245], v[188:191], v[10:13]
	v_mfma_f32_16x16x32_bf16 v[6:9], v[234:237], v[196:199], v[6:9]
	v_mfma_f32_16x16x32_bf16 v[2:5], v[242:245], v[196:199], v[2:5]
	s_nop 0
	s_add_i32 s49, s49, 2
	s_add_u32 s47, s47, 0x100
	s_addc_u32 s48, s48, 0
	s_cmp_gt_u32 s49, 13
	s_mov_b64 s[22:23], s[24:25]
	s_barrier
	s_cbranch_scc0 .LBB0_346
	s_setprio 0
	v_mov_b32_e32 v154, v163
	s_lshl_b32 s13, s20, 8
	v_ashrrev_i32_e32 v99, 2, v154
	v_and_b32_e32 v99, 0xffffffc0, v99
	v_add_u32_e32 v155, s13, v99
	s_addk_i32 s13, 0xe000
	s_lshr_b32 s13, s13, 11
	s_lshl_b32 s15, s21, 8
	s_add_i32 s13, s13, 1
	s_cmp_gt_i32 s20, 31
	s_cselect_b64 s[20:21], -1, 0
	v_lshrrev_b32_e32 v99, 1, v154
	s_and_b64 vcc, s[20:21], exec
	v_and_b32_e32 v98, 0xc0, v154
	v_and_b32_e32 v99, 24, v99
	s_cselect_b32 s13, s13, 0
	v_or3_b32 v152, v98, s15, v99
	s_mul_hi_u32 s15, s13, 0x6000
	s_mulk_i32 s13, 0x6000
	s_add_u32 s20, s39, s13
	s_addc_u32 s21, s40, s15
	v_ashrrev_i32_e32 v153, 31, v152
	v_lshl_add_u64 v[106:107], v[152:153], 2, s[20:21]
	global_load_dwordx4 v[102:105], v[106:107], off offset:16
	global_load_dwordx4 v[110:113], v[106:107], off
	global_load_dwordx4 v[98:101], v[106:107], off offset:144
	s_nop 0
	global_load_dwordx4 v[106:109], v[106:107], off offset:128
	v_and_or_b32 v154, v154, 15, v155
	s_mov_b64 s[20:21], -1
	v_ashrrev_i32_e32 v155, 31, v154
	s_cbranch_vccz .LBB0_349
	v_lshlrev_b64 v[158:159], 12, v[154:155]
	s_mov_b32 s20, 0xfe000000
	v_lshl_add_u64 v[156:157], s[6:7], 0, v[158:159]
	s_mov_b32 s21, -1
	v_lshl_add_u64 v[156:157], v[156:157], 0, s[20:21]
	s_mov_b64 s[20:21], 0

.LBB0_723:
	s_cmp_eq_u32 s27, 0
	s_cselect_b32 s99, 2, 0
	s_cmp_eq_u32 s27, 1
	s_cselect_b32 s99, 4, s99
	s_add_i32 s98, s99, -2
	s_add_u32 s28, s12, 0x100
	v_mov_b32_e32 v2, 0
	s_addc_u32 s29, s13, 0
	s_mov_b32 s30, -2
	v_mov_b32_e32 v3, v2
	v_mov_b32_e32 v4, v2
	v_mov_b32_e32 v5, v2
	v_mov_b32_e32 v6, v2
	v_mov_b32_e32 v7, v2
	v_mov_b32_e32 v8, v2
	v_mov_b32_e32 v9, v2
	v_mov_b32_e32 v18, v2
	v_mov_b32_e32 v19, v2
	v_mov_b32_e32 v20, v2
	v_mov_b32_e32 v21, v2
	v_mov_b32_e32 v22, v2
	v_mov_b32_e32 v23, v2
	v_mov_b32_e32 v24, v2
	v_mov_b32_e32 v25, v2
	v_mov_b32_e32 v34, v2
	v_mov_b32_e32 v35, v2
	v_mov_b32_e32 v36, v2
	v_mov_b32_e32 v37, v2
	v_mov_b32_e32 v38, v2
	v_mov_b32_e32 v39, v2
	v_mov_b32_e32 v40, v2
	v_mov_b32_e32 v41, v2
	v_mov_b32_e32 v50, v2
	v_mov_b32_e32 v51, v2
	v_mov_b32_e32 v52, v2
	v_mov_b32_e32 v53, v2
	v_mov_b32_e32 v54, v2
	v_mov_b32_e32 v55, v2
	v_mov_b32_e32 v56, v2
	v_mov_b32_e32 v57, v2
	v_mov_b32_e32 v10, v2
	v_mov_b32_e32 v11, v2
	v_mov_b32_e32 v12, v2
	v_mov_b32_e32 v13, v2
	v_mov_b32_e32 v14, v2
	v_mov_b32_e32 v15, v2
	v_mov_b32_e32 v16, v2
	v_mov_b32_e32 v17, v2
	v_mov_b32_e32 v26, v2
	v_mov_b32_e32 v27, v2
	v_mov_b32_e32 v28, v2
	v_mov_b32_e32 v29, v2
	v_mov_b32_e32 v30, v2
	v_mov_b32_e32 v31, v2
	v_mov_b32_e32 v32, v2
	v_mov_b32_e32 v33, v2
	v_mov_b32_e32 v42, v2
	v_mov_b32_e32 v43, v2
	v_mov_b32_e32 v44, v2
	v_mov_b32_e32 v45, v2
	v_mov_b32_e32 v46, v2
	v_mov_b32_e32 v47, v2
	v_mov_b32_e32 v48, v2
	v_mov_b32_e32 v49, v2
	v_mov_b32_e32 v58, v2
	v_mov_b32_e32 v59, v2
	v_mov_b32_e32 v60, v2
	v_mov_b32_e32 v61, v2
	v_mov_b32_e32 v62, v2
	v_mov_b32_e32 v63, v2
	v_mov_b32_e32 v64, v2
	v_mov_b32_e32 v65, v2
	v_mov_b32_e32 v66, v2
	v_mov_b32_e32 v67, v2
	v_mov_b32_e32 v68, v2
	v_mov_b32_e32 v69, v2
	v_mov_b32_e32 v70, v2
	v_mov_b32_e32 v71, v2
	v_mov_b32_e32 v72, v2
	v_mov_b32_e32 v73, v2
	v_mov_b32_e32 v82, v2
	v_mov_b32_e32 v83, v2
	v_mov_b32_e32 v84, v2
	v_mov_b32_e32 v85, v2
	v_mov_b32_e32 v86, v2
	v_mov_b32_e32 v87, v2
	v_mov_b32_e32 v88, v2
	v_mov_b32_e32 v89, v2
	v_mov_b32_e32 v98, v2
	v_mov_b32_e32 v99, v2
	v_mov_b32_e32 v100, v2
	v_mov_b32_e32 v101, v2
	v_mov_b32_e32 v102, v2
	v_mov_b32_e32 v103, v2
	v_mov_b32_e32 v104, v2
	v_mov_b32_e32 v105, v2
	v_mov_b32_e32 v114, v2
	v_mov_b32_e32 v115, v2
	v_mov_b32_e32 v116, v2
	v_mov_b32_e32 v117, v2
	v_mov_b32_e32 v118, v2
	v_mov_b32_e32 v119, v2
	v_mov_b32_e32 v120, v2
	v_mov_b32_e32 v121, v2
	v_mov_b32_e32 v74, v2
	v_mov_b32_e32 v75, v2
	v_mov_b32_e32 v76, v2
	v_mov_b32_e32 v77, v2
	v_mov_b32_e32 v78, v2
	v_mov_b32_e32 v79, v2
	v_mov_b32_e32 v80, v2
	v_mov_b32_e32 v81, v2
	v_mov_b32_e32 v90, v2
	v_mov_b32_e32 v91, v2
	v_mov_b32_e32 v92, v2
	v_mov_b32_e32 v93, v2
	v_mov_b32_e32 v94, v2
	v_mov_b32_e32 v95, v2
	v_mov_b32_e32 v96, v2
	v_mov_b32_e32 v97, v2
	v_mov_b32_e32 v106, v2
	v_mov_b32_e32 v107, v2
	v_mov_b32_e32 v108, v2
	v_mov_b32_e32 v109, v2
	v_mov_b32_e32 v110, v2
	v_mov_b32_e32 v111, v2
	v_mov_b32_e32 v112, v2
	v_mov_b32_e32 v113, v2
	v_mov_b32_e32 v122, v2
	v_mov_b32_e32 v123, v2
	v_mov_b32_e32 v124, v2
	v_mov_b32_e32 v125, v2
	v_mov_b32_e32 v126, v2
	v_mov_b32_e32 v127, v2
	v_mov_b32_e32 v128, v2
	v_mov_b32_e32 v129, v2
	v_cmp_lt_u32_e32 vcc, 0xff, v163
	s_nop 1
	s_cbranch_vccz .Lsprio_skip2
	s_setprio 1
.Lsprio_skip2:
.LBB0_724:
	s_add_u32 s6, s10, 0x100
	s_addc_u32 s7, s11, 0
	s_add_i32 s31, 0, 0x10000
	v_add_u32_e32 v0, s31, v146
	ds_read_b128 v[138:141], v0
	ds_read_b128 v[142:145], v0 offset:1024
	ds_read_b128 v[148:151], v0 offset:2048
	ds_read_b128 v[152:155], v0 offset:3072
	s_cmp_eq_u32 s30, s98
	s_cselect_b32 s13, s23, s7
	s_cselect_b32 s12, s22, s6
	s_cselect_b32 s9, s25, s29
	s_cselect_b32 s8, s24, s28
	v_lshl_add_u64 v[160:161], s[10:11], 0, v[136:137]
	s_add_i32 m0, s36, 0xc000
	ds_read_b128 v[156:159], v147
	ds_read_b128 v[176:179], v147 offset:1024
	ds_read_b128 v[180:183], v147 offset:2048
	ds_read_b128 v[184:187], v147 offset:3072
	ds_read_b128 v[188:191], v147 offset:4096
	ds_read_b128 v[192:195], v147 offset:5120
	ds_read_b128 v[196:199], v147 offset:6144
	ds_read_b128 v[230:233], v147 offset:7168
	global_load_lds_dwordx4 v[160:161], off
	v_lshl_add_u64 v[160:161], s[10:11], 0, v[134:135]
	s_add_i32 m0, s36, 0xe000
	s_nop 0
	global_load_lds_dwordx4 v[160:161], off
	s_waitcnt lgkmcnt(8)
	s_barrier
	s_waitcnt lgkmcnt(0)
	s_nop 0
	s_waitcnt lgkmcnt(0)
	v_mfma_f32_16x16x32_bf16 v[126:129], v[138:141], v[156:159], v[126:129]
	v_mfma_f32_16x16x32_bf16 v[122:125], v[148:151], v[156:159], v[122:125]
	v_mfma_f32_16x16x32_bf16 v[110:113], v[138:141], v[180:183], v[110:113]
	v_mfma_f32_16x16x32_bf16 v[106:109], v[148:151], v[180:183], v[106:109]
	v_mfma_f32_16x16x32_bf16 v[94:97], v[138:141], v[188:191], v[94:97]
	v_mfma_f32_16x16x32_bf16 v[90:93], v[148:151], v[188:191], v[90:93]
	v_mfma_f32_16x16x32_bf16 v[78:81], v[138:141], v[196:199], v[78:81]
	v_mfma_f32_16x16x32_bf16 v[74:77], v[148:151], v[196:199], v[74:77]
	v_mfma_f32_16x16x32_bf16 v[126:129], v[142:145], v[176:179], v[126:129]
	v_mfma_f32_16x16x32_bf16 v[122:125], v[152:155], v[176:179], v[122:125]
	v_mfma_f32_16x16x32_bf16 v[110:113], v[142:145], v[184:187], v[110:113]
	v_mfma_f32_16x16x32_bf16 v[106:109], v[152:155], v[184:187], v[106:109]
	v_mfma_f32_16x16x32_bf16 v[94:97], v[142:145], v[192:195], v[94:97]
	v_mfma_f32_16x16x32_bf16 v[90:93], v[152:155], v[192:195], v[90:93]
	v_mfma_f32_16x16x32_bf16 v[78:81], v[142:145], v[230:233], v[78:81]
	v_mfma_f32_16x16x32_bf16 v[74:77], v[152:155], v[230:233], v[74:77]
	s_nop 0
	s_barrier
	s_add_i32 s47, 0, 0x14000
	s_add_i32 s10, s31, s35
	v_add_u32_e32 v0, s47, v146
	v_lshl_add_u64 v[160:161], s[8:9], 0, v[130:131]
	s_mov_b32 m0, s10
	ds_read_b128 v[234:237], v0
	ds_read_b128 v[238:241], v0 offset:1024
	ds_read_b128 v[242:245], v0 offset:2048
	ds_read_b128 v[246:249], v0 offset:3072
	global_load_lds_dwordx4 v[160:161], off
	v_lshl_add_u64 v[200:201], s[8:9], 0, v[132:133]
	s_add_i32 m0, s10, 0x2000
	s_nop 0
	global_load_lds_dwordx4 v[200:201], off
	s_barrier
	s_waitcnt lgkmcnt(0)
	s_nop 0
	s_waitcnt lgkmcnt(0)
	v_mfma_f32_16x16x32_bf16 v[118:121], v[234:237], v[156:159], v[118:121]
	v_mfma_f32_16x16x32_bf16 v[114:117], v[242:245], v[156:159], v[114:117]
	v_mfma_f32_16x16x32_bf16 v[102:105], v[234:237], v[180:183], v[102:105]
	v_mfma_f32_16x16x32_bf16 v[98:101], v[242:245], v[180:183], v[98:101]
	v_mfma_f32_16x16x32_bf16 v[86:89], v[234:237], v[188:191], v[86:89]
	v_mfma_f32_16x16x32_bf16 v[82:85], v[242:245], v[188:191], v[82:85]
	v_mfma_f32_16x16x32_bf16 v[70:73], v[234:237], v[196:199], v[70:73]
	v_mfma_f32_16x16x32_bf16 v[66:69], v[242:245], v[196:199], v[66:69]
	v_mfma_f32_16x16x32_bf16 v[118:121], v[238:241], v[176:179], v[118:121]
	v_mfma_f32_16x16x32_bf16 v[114:117], v[246:249], v[176:179], v[114:117]
	v_mfma_f32_16x16x32_bf16 v[102:105], v[238:241], v[184:187], v[102:105]
	v_mfma_f32_16x16x32_bf16 v[98:101], v[246:249], v[184:187], v[98:101]
	v_mfma_f32_16x16x32_bf16 v[86:89], v[238:241], v[192:195], v[86:89]
	v_mfma_f32_16x16x32_bf16 v[82:85], v[246:249], v[192:195], v[82:85]
	v_mfma_f32_16x16x32_bf16 v[70:73], v[238:241], v[230:233], v[70:73]
	v_mfma_f32_16x16x32_bf16 v[66:69], v[246:249], v[230:233], v[66:69]
	s_nop 0
	s_mov_b32 m0, s36
	v_lshl_add_u64 v[250:251], s[12:13], 0, v[130:131]
	s_barrier
	ds_read_b128 v[156:159], v147 offset:16384
	ds_read_b128 v[176:179], v147 offset:17408
	ds_read_b128 v[180:183], v147 offset:18432
	ds_read_b128 v[184:187], v147 offset:19456
	ds_read_b128 v[188:191], v147 offset:20480
	ds_read_b128 v[192:195], v147 offset:21504
	ds_read_b128 v[196:199], v147 offset:22528
	ds_read_b128 v[230:233], v147 offset:23552
	global_load_lds_dwordx4 v[250:251], off
	v_lshl_add_u64 v[252:253], s[12:13], 0, v[132:133]
	s_mov_b32 m0, s37
	s_nop 0
	global_load_lds_dwordx4 v[252:253], off
	s_barrier
	s_waitcnt lgkmcnt(0)
	s_nop 0
	s_waitcnt lgkmcnt(0)
	v_mfma_f32_16x16x32_bf16 v[62:65], v[138:141], v[156:159], v[62:65]
	v_mfma_f32_16x16x32_bf16 v[58:61], v[148:151], v[156:159], v[58:61]
	v_mfma_f32_16x16x32_bf16 v[46:49], v[138:141], v[180:183], v[46:49]
	v_mfma_f32_16x16x32_bf16 v[42:45], v[148:151], v[180:183], v[42:45]
	v_mfma_f32_16x16x32_bf16 v[30:33], v[138:141], v[188:191], v[30:33]
	v_mfma_f32_16x16x32_bf16 v[26:29], v[148:151], v[188:191], v[26:29]
	v_mfma_f32_16x16x32_bf16 v[14:17], v[138:141], v[196:199], v[14:17]
	v_mfma_f32_16x16x32_bf16 v[10:13], v[148:151], v[196:199], v[10:13]
	v_mfma_f32_16x16x32_bf16 v[62:65], v[142:145], v[176:179], v[62:65]
	v_mfma_f32_16x16x32_bf16 v[58:61], v[152:155], v[176:179], v[58:61]
	v_mfma_f32_16x16x32_bf16 v[46:49], v[142:145], v[184:187], v[46:49]
	v_mfma_f32_16x16x32_bf16 v[42:45], v[152:155], v[184:187], v[42:45]
	v_mfma_f32_16x16x32_bf16 v[30:33], v[142:145], v[192:195], v[30:33]
	v_mfma_f32_16x16x32_bf16 v[26:29], v[152:155], v[192:195], v[26:29]
	v_mfma_f32_16x16x32_bf16 v[14:17], v[142:145], v[230:233], v[14:17]
	v_mfma_f32_16x16x32_bf16 v[10:13], v[152:155], v[230:233], v[10:13]
	s_nop 0
	s_barrier
	s_add_u32 s10, s8, 0x18000
	s_addc_u32 s11, s9, 0
	s_add_i32 s31, s47, s35
	v_lshl_add_u64 v[138:139], s[10:11], 0, v[130:131]
	s_mov_b32 m0, s31
	s_nop 0
	global_load_lds_dwordx4 v[138:139], off
	v_lshl_add_u64 v[138:139], s[10:11], 0, v[132:133]
	s_add_i32 m0, s31, 0x2000
	s_nop 0
	global_load_lds_dwordx4 v[138:139], off
	s_waitcnt vmcnt(6)
	s_barrier
	s_nop 0
	v_mfma_f32_16x16x32_bf16 v[54:57], v[234:237], v[156:159], v[54:57]
	v_mfma_f32_16x16x32_bf16 v[50:53], v[242:245], v[156:159], v[50:53]
	v_mfma_f32_16x16x32_bf16 v[38:41], v[234:237], v[180:183], v[38:41]
	v_mfma_f32_16x16x32_bf16 v[34:37], v[242:245], v[180:183], v[34:37]
	v_mfma_f32_16x16x32_bf16 v[22:25], v[234:237], v[188:191], v[22:25]
	v_mfma_f32_16x16x32_bf16 v[18:21], v[242:245], v[188:191], v[18:21]
	v_mfma_f32_16x16x32_bf16 v[6:9], v[234:237], v[196:199], v[6:9]
	v_mfma_f32_16x16x32_bf16 v[2:5], v[242:245], v[196:199], v[2:5]
	v_mfma_f32_16x16x32_bf16 v[54:57], v[238:241], v[176:179], v[54:57]
	v_mfma_f32_16x16x32_bf16 v[50:53], v[246:249], v[176:179], v[50:53]
	v_mfma_f32_16x16x32_bf16 v[38:41], v[238:241], v[184:187], v[38:41]
	v_mfma_f32_16x16x32_bf16 v[34:37], v[246:249], v[184:187], v[34:37]
	v_mfma_f32_16x16x32_bf16 v[22:25], v[238:241], v[192:195], v[22:25]
	v_mfma_f32_16x16x32_bf16 v[18:21], v[246:249], v[192:195], v[18:21]
	v_mfma_f32_16x16x32_bf16 v[6:9], v[238:241], v[230:233], v[6:9]
	v_mfma_f32_16x16x32_bf16 v[2:5], v[246:249], v[230:233], v[2:5]
	s_nop 0
	s_add_i32 s31, 0, 0x18000
	v_add_u32_e32 v0, s31, v146
	s_barrier
	ds_read_b128 v[138:141], v0
	ds_read_b128 v[142:145], v0 offset:1024
	ds_read_b128 v[148:151], v0 offset:2048
	ds_read_b128 v[152:155], v0 offset:3072
	s_add_u32 s10, s12, 0x18000
	s_addc_u32 s11, s13, 0
	s_mov_b32 m0, s38
	v_lshl_add_u64 v[234:235], s[10:11], 0, v[130:131]
	ds_read_b128 v[156:159], v147 offset:32768
	ds_read_b128 v[176:179], v147 offset:33792
	ds_read_b128 v[180:183], v147 offset:34816
	ds_read_b128 v[184:187], v147 offset:35840
	ds_read_b128 v[188:191], v147 offset:36864
	ds_read_b128 v[192:195], v147 offset:37888
	ds_read_b128 v[196:199], v147 offset:38912
	ds_read_b128 v[230:233], v147 offset:39936
	global_load_lds_dwordx4 v[234:235], off
	v_lshl_add_u64 v[234:235], s[10:11], 0, v[132:133]
	s_mov_b32 m0, s39
	s_nop 0
	global_load_lds_dwordx4 v[234:235], off
	s_waitcnt lgkmcnt(8)
	s_barrier
	s_waitcnt lgkmcnt(0)
	s_nop 0
	s_waitcnt lgkmcnt(0)
	v_mfma_f32_16x16x32_bf16 v[126:129], v[138:141], v[156:159], v[126:129]
	v_mfma_f32_16x16x32_bf16 v[122:125], v[148:151], v[156:159], v[122:125]
	v_mfma_f32_16x16x32_bf16 v[110:113], v[138:141], v[180:183], v[110:113]
	v_mfma_f32_16x16x32_bf16 v[106:109], v[148:151], v[180:183], v[106:109]
	v_mfma_f32_16x16x32_bf16 v[94:97], v[138:141], v[188:191], v[94:97]
	v_mfma_f32_16x16x32_bf16 v[90:93], v[148:151], v[188:191], v[90:93]
	v_mfma_f32_16x16x32_bf16 v[78:81], v[138:141], v[196:199], v[78:81]
	v_mfma_f32_16x16x32_bf16 v[74:77], v[148:151], v[196:199], v[74:77]
	v_mfma_f32_16x16x32_bf16 v[126:129], v[142:145], v[176:179], v[126:129]
	v_mfma_f32_16x16x32_bf16 v[122:125], v[152:155], v[176:179], v[122:125]
	v_mfma_f32_16x16x32_bf16 v[110:113], v[142:145], v[184:187], v[110:113]
	v_mfma_f32_16x16x32_bf16 v[106:109], v[152:155], v[184:187], v[106:109]
	v_mfma_f32_16x16x32_bf16 v[94:97], v[142:145], v[192:195], v[94:97]
	v_mfma_f32_16x16x32_bf16 v[90:93], v[152:155], v[192:195], v[90:93]
	v_mfma_f32_16x16x32_bf16 v[78:81], v[142:145], v[230:233], v[78:81]
	v_mfma_f32_16x16x32_bf16 v[74:77], v[152:155], v[230:233], v[74:77]
	s_nop 0
	s_barrier
	s_add_i32 s10, 0, 0x1c000
	s_add_i32 s11, s31, s35
	v_add_u32_e32 v0, s10, v146
	v_lshl_add_u64 v[160:161], v[160:161], 0, s[92:93]
	s_mov_b32 m0, s11
	ds_read_b128 v[234:237], v0
	ds_read_b128 v[238:241], v0 offset:1024
	ds_read_b128 v[242:245], v0 offset:2048
	ds_read_b128 v[246:249], v0 offset:3072
	global_load_lds_dwordx4 v[160:161], off
	v_lshl_add_u64 v[160:161], v[200:201], 0, s[92:93]
	s_add_i32 m0, s11, 0x2000
	s_nop 0
	global_load_lds_dwordx4 v[160:161], off
	s_barrier
	s_waitcnt lgkmcnt(0)
	s_nop 0
	s_waitcnt lgkmcnt(0)
	v_mfma_f32_16x16x32_bf16 v[118:121], v[234:237], v[156:159], v[118:121]
	v_mfma_f32_16x16x32_bf16 v[114:117], v[242:245], v[156:159], v[114:117]
	v_mfma_f32_16x16x32_bf16 v[102:105], v[234:237], v[180:183], v[102:105]
	v_mfma_f32_16x16x32_bf16 v[98:101], v[242:245], v[180:183], v[98:101]
	v_mfma_f32_16x16x32_bf16 v[86:89], v[234:237], v[188:191], v[86:89]
	v_mfma_f32_16x16x32_bf16 v[82:85], v[242:245], v[188:191], v[82:85]
	v_mfma_f32_16x16x32_bf16 v[70:73], v[234:237], v[196:199], v[70:73]
	v_mfma_f32_16x16x32_bf16 v[66:69], v[242:245], v[196:199], v[66:69]
	v_mfma_f32_16x16x32_bf16 v[118:121], v[238:241], v[176:179], v[118:121]
	v_mfma_f32_16x16x32_bf16 v[114:117], v[246:249], v[176:179], v[114:117]
	v_mfma_f32_16x16x32_bf16 v[102:105], v[238:241], v[184:187], v[102:105]
	v_mfma_f32_16x16x32_bf16 v[98:101], v[246:249], v[184:187], v[98:101]
	v_mfma_f32_16x16x32_bf16 v[86:89], v[238:241], v[192:195], v[86:89]
	v_mfma_f32_16x16x32_bf16 v[82:85], v[246:249], v[192:195], v[82:85]
	v_mfma_f32_16x16x32_bf16 v[70:73], v[238:241], v[230:233], v[70:73]
	v_mfma_f32_16x16x32_bf16 v[66:69], v[246:249], v[230:233], v[66:69]
	s_nop 0
	s_mov_b32 m0, s40
	v_lshl_add_u64 v[160:161], v[250:251], 0, s[92:93]
	s_barrier
	ds_read_b128 v[156:159], v147 offset:49152
	ds_read_b128 v[176:179], v147 offset:50176
	ds_read_b128 v[180:183], v147 offset:51200
	ds_read_b128 v[184:187], v147 offset:52224
	ds_read_b128 v[188:191], v147 offset:53248
	ds_read_b128 v[192:195], v147 offset:54272
	ds_read_b128 v[196:199], v147 offset:55296
	ds_read_b128 v[230:233], v147 offset:56320
	global_load_lds_dwordx4 v[160:161], off
	v_lshl_add_u64 v[160:161], v[252:253], 0, s[92:93]
	s_mov_b32 m0, s41
	s_nop 0
	global_load_lds_dwordx4 v[160:161], off
	s_barrier
	s_waitcnt lgkmcnt(0)
	s_nop 0
	s_waitcnt lgkmcnt(0)
	v_mfma_f32_16x16x32_bf16 v[62:65], v[138:141], v[156:159], v[62:65]
	v_mfma_f32_16x16x32_bf16 v[58:61], v[148:151], v[156:159], v[58:61]
	v_mfma_f32_16x16x32_bf16 v[46:49], v[138:141], v[180:183], v[46:49]
	v_mfma_f32_16x16x32_bf16 v[42:45], v[148:151], v[180:183], v[42:45]
	v_mfma_f32_16x16x32_bf16 v[30:33], v[138:141], v[188:191], v[30:33]
	v_mfma_f32_16x16x32_bf16 v[26:29], v[148:151], v[188:191], v[26:29]
	v_mfma_f32_16x16x32_bf16 v[14:17], v[138:141], v[196:199], v[14:17]
	v_mfma_f32_16x16x32_bf16 v[10:13], v[148:151], v[196:199], v[10:13]
	v_mfma_f32_16x16x32_bf16 v[62:65], v[142:145], v[176:179], v[62:65]
	v_mfma_f32_16x16x32_bf16 v[58:61], v[152:155], v[176:179], v[58:61]
	v_mfma_f32_16x16x32_bf16 v[46:49], v[142:145], v[184:187], v[46:49]
	v_mfma_f32_16x16x32_bf16 v[42:45], v[152:155], v[184:187], v[42:45]
	v_mfma_f32_16x16x32_bf16 v[30:33], v[142:145], v[192:195], v[30:33]
	v_mfma_f32_16x16x32_bf16 v[26:29], v[152:155], v[192:195], v[26:29]
	v_mfma_f32_16x16x32_bf16 v[14:17], v[142:145], v[230:233], v[14:17]
	v_mfma_f32_16x16x32_bf16 v[10:13], v[152:155], v[230:233], v[10:13]
	s_nop 0
	s_barrier
	s_add_u32 s8, s8, 0x18080
	s_addc_u32 s9, s9, 0
	s_add_i32 s10, s10, s35
	v_lshl_add_u64 v[138:139], s[8:9], 0, v[130:131]
	s_mov_b32 m0, s10
	s_nop 0
	global_load_lds_dwordx4 v[138:139], off
	v_lshl_add_u64 v[138:139], s[8:9], 0, v[132:133]
	s_add_i32 m0, s10, 0x2000
	s_nop 0
	global_load_lds_dwordx4 v[138:139], off
	s_waitcnt vmcnt(6)
	s_barrier
	s_nop 0
	v_mfma_f32_16x16x32_bf16 v[54:57], v[234:237], v[156:159], v[54:57]
	v_mfma_f32_16x16x32_bf16 v[50:53], v[242:245], v[156:159], v[50:53]
	v_mfma_f32_16x16x32_bf16 v[38:41], v[234:237], v[180:183], v[38:41]
	v_mfma_f32_16x16x32_bf16 v[34:37], v[242:245], v[180:183], v[34:37]
	v_mfma_f32_16x16x32_bf16 v[22:25], v[234:237], v[188:191], v[22:25]
	v_mfma_f32_16x16x32_bf16 v[18:21], v[242:245], v[188:191], v[18:21]
	v_mfma_f32_16x16x32_bf16 v[6:9], v[234:237], v[196:199], v[6:9]
	v_mfma_f32_16x16x32_bf16 v[2:5], v[242:245], v[196:199], v[2:5]
	v_mfma_f32_16x16x32_bf16 v[54:57], v[238:241], v[176:179], v[54:57]
	v_mfma_f32_16x16x32_bf16 v[50:53], v[246:249], v[176:179], v[50:53]
	v_mfma_f32_16x16x32_bf16 v[38:41], v[238:241], v[184:187], v[38:41]
	v_mfma_f32_16x16x32_bf16 v[34:37], v[246:249], v[184:187], v[34:37]
	v_mfma_f32_16x16x32_bf16 v[22:25], v[238:241], v[192:195], v[22:25]
	v_mfma_f32_16x16x32_bf16 v[18:21], v[246:249], v[192:195], v[18:21]
	v_mfma_f32_16x16x32_bf16 v[6:9], v[238:241], v[230:233], v[6:9]
	v_mfma_f32_16x16x32_bf16 v[2:5], v[246:249], v[230:233], v[2:5]
	s_nop 0
	s_add_i32 s30, s30, 2
	s_add_u32 s28, s28, 0x100
	s_addc_u32 s29, s29, 0
	s_cmp_ge_i32 s30, s99
	s_mov_b64 s[10:11], s[6:7]
	s_barrier
	s_cbranch_scc0 .LBB0_724
	s_setprio 0
	v_mov_b32_e32 v0, v163
	s_movk_i32 s6, 0xffc0
	v_and_b32_e32 v138, 0xc0, v0
	v_and_b32_e32 v149, 15, v0
	v_ashrrev_i32_e32 v139, 2, v0
	v_lshl_or_b32 v148, s27, 8, v138
	v_lshrrev_b32_e32 v0, 1, v0
	v_and_or_b32 v138, v0, 24, v148
	v_and_or_b32 v0, v139, s6, v149
	v_lshl_add_u32 v140, s26, 8, v0
	s_movk_i32 s6, 0x1fff
	v_ashrrev_i32_e32 v141, 31, v140
	v_cmp_lt_i32_e64 s[8:9], s6, v140
	s_movk_i32 s6, 0x17f
	v_lshlrev_b64 v[144:145], 10, v[140:141]
	v_cmp_gt_i32_e64 s[10:11], s33, v140
	v_cmp_lt_i32_e64 s[6:7], s6, v138
	s_and_saveexec_b64 s[12:13], s[6:7]
	s_xor_b64 s[12:13], exec, s[12:13]
	s_cbranch_execz .LBB0_729
	s_movk_i32 s26, 0x380
	v_cmp_gt_u32_e32 vcc, s26, v148
	s_and_saveexec_b64 s[26:27], vcc
	s_cbranch_execz .LBB0_728
	v_lshl_add_u64 v[142:143], s[18:19], 0, v[144:145]
	v_mov_b32_e32 v139, v1
	v_lshl_add_u64 v[142:143], v[138:139], 1, v[142:143]
	v_cvt_pk_bf16_f32 v150, v126, v127
	v_cvt_pk_bf16_f32 v151, v128, v129
	v_cvt_pk_bf16_f32 v152, v122, v123
	v_cvt_pk_bf16_f32 v153, v124, v125
	global_store_dwordx4 v[142:143], v[150:153], off offset:-768

.LBB0_892:
	s_ashr_i32 s13, s12, 31
	v_cmp_lt_i64_e32 vcc, s[16:17], v[166:167]
	s_lshl_b64 s[16:17], s[12:13], 18
	s_add_u32 s16, s3, s16
	s_addc_u32 s17, s24, s17
	s_and_b32 s98, s10, 1
	s_lshl_b32 s98, s98, 9
	s_add_u32 s16, s16, s98
	s_addc_u32 s17, s17, 0
	v_readlane_b32 s98, v254, 0
	s_and_b32 s98, s98, s99
	s_lshl_b32 s98, s98, 17
	s_add_u32 s16, s16, s98
	s_addc_u32 s17, s17, 0
	s_and_b32 s98, s10, 1
	s_lshl_b32 s98, s98, 9
	s_and_b64 s[18:19], vcc, exec
	s_cselect_b32 s13, s17, s21
	s_cselect_b32 s39, s16, s20
	s_ashr_i32 s11, s10, 31
	s_lshl_b64 s[18:19], s[10:11], 18
	s_add_u32 s18, s25, s18
	s_addc_u32 s19, s26, s19
	s_add_u32 s18, s18, s98
	s_addc_u32 s19, s19, 0
	s_and_b64 s[22:23], vcc, exec
	s_cselect_b32 s11, s19, s9
	s_cselect_b32 s40, s18, s8
	s_add_u32 s41, s8, 0x100
	s_addc_u32 s42, s9, 0
	s_add_u32 s8, s20, 0x20080
	v_mov_b32_e32 v2, 0
	s_addc_u32 s9, s21, 0
	s_mov_b32 s43, -2
	v_mov_b32_e32 v3, v2
	v_mov_b32_e32 v4, v2
	v_mov_b32_e32 v5, v2
	v_mov_b32_e32 v6, v2
	v_mov_b32_e32 v7, v2
	v_mov_b32_e32 v8, v2
	v_mov_b32_e32 v9, v2
	v_mov_b32_e32 v14, v2
	v_mov_b32_e32 v15, v2
	v_mov_b32_e32 v16, v2
	v_mov_b32_e32 v17, v2
	v_mov_b32_e32 v22, v2
	v_mov_b32_e32 v23, v2
	v_mov_b32_e32 v24, v2
	v_mov_b32_e32 v25, v2
	v_mov_b32_e32 v30, v2
	v_mov_b32_e32 v31, v2
	v_mov_b32_e32 v32, v2
	v_mov_b32_e32 v33, v2
	v_mov_b32_e32 v38, v2
	v_mov_b32_e32 v39, v2
	v_mov_b32_e32 v40, v2
	v_mov_b32_e32 v41, v2
	v_mov_b32_e32 v46, v2
	v_mov_b32_e32 v47, v2
	v_mov_b32_e32 v48, v2
	v_mov_b32_e32 v49, v2
	v_mov_b32_e32 v54, v2
	v_mov_b32_e32 v55, v2
	v_mov_b32_e32 v56, v2
	v_mov_b32_e32 v57, v2
	v_mov_b32_e32 v10, v2
	v_mov_b32_e32 v11, v2
	v_mov_b32_e32 v12, v2
	v_mov_b32_e32 v13, v2
	v_mov_b32_e32 v18, v2
	v_mov_b32_e32 v19, v2
	v_mov_b32_e32 v20, v2
	v_mov_b32_e32 v21, v2
	v_mov_b32_e32 v26, v2
	v_mov_b32_e32 v27, v2
	v_mov_b32_e32 v28, v2
	v_mov_b32_e32 v29, v2
	v_mov_b32_e32 v34, v2
	v_mov_b32_e32 v35, v2
	v_mov_b32_e32 v36, v2
	v_mov_b32_e32 v37, v2
	v_mov_b32_e32 v42, v2
	v_mov_b32_e32 v43, v2
	v_mov_b32_e32 v44, v2
	v_mov_b32_e32 v45, v2
	v_mov_b32_e32 v50, v2
	v_mov_b32_e32 v51, v2
	v_mov_b32_e32 v52, v2
	v_mov_b32_e32 v53, v2
	v_mov_b32_e32 v58, v2
	v_mov_b32_e32 v59, v2
	v_mov_b32_e32 v60, v2
	v_mov_b32_e32 v61, v2
	v_mov_b32_e32 v62, v2
	v_mov_b32_e32 v63, v2
	v_mov_b32_e32 v64, v2
	v_mov_b32_e32 v65, v2
	v_mov_b32_e32 v66, v2
	v_mov_b32_e32 v67, v2
	v_mov_b32_e32 v68, v2
	v_mov_b32_e32 v69, v2
	v_mov_b32_e32 v70, v2
	v_mov_b32_e32 v71, v2
	v_mov_b32_e32 v72, v2
	v_mov_b32_e32 v73, v2
	v_mov_b32_e32 v78, v2
	v_mov_b32_e32 v79, v2
	v_mov_b32_e32 v80, v2
	v_mov_b32_e32 v81, v2
	v_mov_b32_e32 v86, v2
	v_mov_b32_e32 v87, v2
	v_mov_b32_e32 v88, v2
	v_mov_b32_e32 v89, v2
	v_mov_b32_e32 v94, v2
	v_mov_b32_e32 v95, v2
	v_mov_b32_e32 v96, v2
	v_mov_b32_e32 v97, v2
	v_mov_b32_e32 v102, v2
	v_mov_b32_e32 v103, v2
	v_mov_b32_e32 v104, v2
	v_mov_b32_e32 v105, v2
	v_mov_b32_e32 v110, v2
	v_mov_b32_e32 v111, v2
	v_mov_b32_e32 v112, v2
	v_mov_b32_e32 v113, v2
	v_mov_b32_e32 v118, v2
	v_mov_b32_e32 v119, v2
	v_mov_b32_e32 v120, v2
	v_mov_b32_e32 v121, v2
	v_mov_b32_e32 v74, v2
	v_mov_b32_e32 v75, v2
	v_mov_b32_e32 v76, v2
	v_mov_b32_e32 v77, v2
	v_mov_b32_e32 v82, v2
	v_mov_b32_e32 v83, v2
	v_mov_b32_e32 v84, v2
	v_mov_b32_e32 v85, v2
	v_mov_b32_e32 v90, v2
	v_mov_b32_e32 v91, v2
	v_mov_b32_e32 v92, v2
	v_mov_b32_e32 v93, v2
	v_mov_b32_e32 v98, v2
	v_mov_b32_e32 v99, v2
	v_mov_b32_e32 v100, v2
	v_mov_b32_e32 v101, v2
	v_mov_b32_e32 v106, v2
	v_mov_b32_e32 v107, v2
	v_mov_b32_e32 v108, v2
	v_mov_b32_e32 v109, v2
	v_mov_b32_e32 v114, v2
	v_mov_b32_e32 v115, v2
	v_mov_b32_e32 v116, v2
	v_mov_b32_e32 v117, v2
	v_mov_b32_e32 v122, v2
	v_mov_b32_e32 v123, v2
	v_mov_b32_e32 v124, v2
	v_mov_b32_e32 v125, v2
	v_mov_b32_e32 v126, v2
	v_mov_b32_e32 v127, v2
	v_mov_b32_e32 v128, v2
	v_mov_b32_e32 v129, v2
	v_readlane_b32 s99, v255, 41
	s_cmp_eq_u32 s38, 2
	s_cselect_b32 s99, s99, 0
	v_cmp_lt_u32_e32 vcc, 0xff, v163
	s_nop 1
	s_cbranch_vccz .Lsprio_skip3
	s_setprio 1
.Lsprio_skip3:
.LBB0_893:
	s_add_u32 s20, s8, 0xfffe0080
	s_addc_u32 s21, s9, -1
	s_add_i32 s44, 0, 0x10000
	v_add_u32_e32 v150, s44, v136
	ds_read_b128 v[138:141], v150
	ds_read_b128 v[142:145], v150 offset:1024
	ds_read_b128 v[146:149], v150 offset:2048
	ds_read_b128 v[150:153], v150 offset:3072
	s_cmp_eq_u32 s43, 0
	s_cselect_b32 s23, s13, s21
	s_cselect_b32 s22, s39, s20
	s_cselect_b32 s21, s11, s42
	s_cselect_b32 s20, s40, s41
	v_lshl_add_u64 v[200:201], s[8:9], 0, v[134:135]
	s_add_i32 m0, s29, 0xc000
	ds_read_b128 v[154:157], v137
	ds_read_b128 v[158:161], v137 offset:1024
	ds_read_b128 v[176:179], v137 offset:2048
	ds_read_b128 v[180:183], v137 offset:3072
	ds_read_b128 v[184:187], v137 offset:4096
	ds_read_b128 v[188:191], v137 offset:5120
	ds_read_b128 v[192:195], v137 offset:6144
	ds_read_b128 v[196:199], v137 offset:7168
	global_load_lds_dwordx4 v[200:201], off
	v_lshl_add_u64 v[200:201], s[8:9], 0, v[132:133]
	s_add_i32 m0, s29, 0xe000
	s_nop 0
	global_load_lds_dwordx4 v[200:201], off
	s_waitcnt lgkmcnt(8)
	s_barrier
	s_waitcnt lgkmcnt(0)
	s_nop 0
	s_waitcnt lgkmcnt(0)
	v_mfma_f32_16x16x32_bf16 v[126:129], v[138:141], v[154:157], v[126:129]
	v_mfma_f32_16x16x32_bf16 v[122:125], v[146:149], v[154:157], v[122:125]
	v_mfma_f32_16x16x32_bf16 v[114:117], v[138:141], v[176:179], v[114:117]
	v_mfma_f32_16x16x32_bf16 v[106:109], v[146:149], v[176:179], v[106:109]
	v_mfma_f32_16x16x32_bf16 v[98:101], v[138:141], v[184:187], v[98:101]
	v_mfma_f32_16x16x32_bf16 v[90:93], v[146:149], v[184:187], v[90:93]
	v_mfma_f32_16x16x32_bf16 v[82:85], v[138:141], v[192:195], v[82:85]
	v_mfma_f32_16x16x32_bf16 v[74:77], v[146:149], v[192:195], v[74:77]
	v_mfma_f32_16x16x32_bf16 v[126:129], v[142:145], v[158:161], v[126:129]
	v_mfma_f32_16x16x32_bf16 v[122:125], v[150:153], v[158:161], v[122:125]
	v_mfma_f32_16x16x32_bf16 v[114:117], v[142:145], v[180:183], v[114:117]
	v_mfma_f32_16x16x32_bf16 v[106:109], v[150:153], v[180:183], v[106:109]
	v_mfma_f32_16x16x32_bf16 v[98:101], v[142:145], v[188:191], v[98:101]
	v_mfma_f32_16x16x32_bf16 v[90:93], v[150:153], v[188:191], v[90:93]
	v_mfma_f32_16x16x32_bf16 v[82:85], v[142:145], v[196:199], v[82:85]
	v_mfma_f32_16x16x32_bf16 v[74:77], v[150:153], v[196:199], v[74:77]
	s_nop 0
	s_barrier
	s_add_i32 s46, 0, 0x14000
	s_add_i32 s44, s44, s27
	v_add_u32_e32 v169, s46, v136
	v_lshl_add_u64 v[200:201], s[20:21], 0, v[0:1]
	s_mov_b32 m0, s44
	ds_read_b128 v[230:233], v169
	ds_read_b128 v[234:237], v169 offset:1024
	ds_read_b128 v[238:241], v169 offset:2048
	ds_read_b128 v[242:245], v169 offset:3072
	global_load_lds_dwordx4 v[200:201], off
	v_lshl_add_u64 v[246:247], s[20:21], 0, v[130:131]
	s_add_i32 m0, s44, 0x2000
	s_nop 0
	global_load_lds_dwordx4 v[246:247], off
	s_barrier
	s_waitcnt lgkmcnt(0)
	s_nop 0
	s_waitcnt lgkmcnt(0)
	v_mfma_f32_16x16x32_bf16 v[118:121], v[230:233], v[154:157], v[118:121]
	v_mfma_f32_16x16x32_bf16 v[110:113], v[238:241], v[154:157], v[110:113]
	v_mfma_f32_16x16x32_bf16 v[102:105], v[230:233], v[176:179], v[102:105]
	v_mfma_f32_16x16x32_bf16 v[94:97], v[238:241], v[176:179], v[94:97]
	v_mfma_f32_16x16x32_bf16 v[86:89], v[230:233], v[184:187], v[86:89]
	v_mfma_f32_16x16x32_bf16 v[78:81], v[238:241], v[184:187], v[78:81]
	v_mfma_f32_16x16x32_bf16 v[70:73], v[230:233], v[192:195], v[70:73]
	v_mfma_f32_16x16x32_bf16 v[66:69], v[238:241], v[192:195], v[66:69]
	v_mfma_f32_16x16x32_bf16 v[118:121], v[234:237], v[158:161], v[118:121]
	v_mfma_f32_16x16x32_bf16 v[110:113], v[242:245], v[158:161], v[110:113]
	v_mfma_f32_16x16x32_bf16 v[102:105], v[234:237], v[180:183], v[102:105]
	v_mfma_f32_16x16x32_bf16 v[94:97], v[242:245], v[180:183], v[94:97]
	v_mfma_f32_16x16x32_bf16 v[86:89], v[234:237], v[188:191], v[86:89]
	v_mfma_f32_16x16x32_bf16 v[78:81], v[242:245], v[188:191], v[78:81]
	v_mfma_f32_16x16x32_bf16 v[70:73], v[234:237], v[196:199], v[70:73]
	v_mfma_f32_16x16x32_bf16 v[66:69], v[242:245], v[196:199], v[66:69]
	s_nop 0
	s_mov_b32 m0, s29
	v_lshl_add_u64 v[248:249], s[22:23], 0, v[0:1]
	s_barrier
	ds_read_b128 v[154:157], v137 offset:16384
	ds_read_b128 v[158:161], v137 offset:17408
	ds_read_b128 v[176:179], v137 offset:18432
	ds_read_b128 v[180:183], v137 offset:19456
	ds_read_b128 v[184:187], v137 offset:20480
	ds_read_b128 v[188:191], v137 offset:21504
	ds_read_b128 v[192:195], v137 offset:22528
	ds_read_b128 v[196:199], v137 offset:23552
	global_load_lds_dwordx4 v[248:249], off
	v_lshl_add_u64 v[250:251], s[22:23], 0, v[130:131]
	s_mov_b32 m0, s30
	s_nop 0
	global_load_lds_dwordx4 v[250:251], off
	s_barrier
	s_waitcnt lgkmcnt(0)
	s_nop 0
	s_waitcnt lgkmcnt(0)
	s_cmp_lg_u32 s99, 0
	s_cbranch_scc1 .La3_skip3
	v_mfma_f32_16x16x32_bf16 v[62:65], v[138:141], v[154:157], v[62:65]
	v_mfma_f32_16x16x32_bf16 v[58:61], v[146:149], v[154:157], v[58:61]
	v_mfma_f32_16x16x32_bf16 v[50:53], v[138:141], v[176:179], v[50:53]
	v_mfma_f32_16x16x32_bf16 v[42:45], v[146:149], v[176:179], v[42:45]
	v_mfma_f32_16x16x32_bf16 v[34:37], v[138:141], v[184:187], v[34:37]
	v_mfma_f32_16x16x32_bf16 v[26:29], v[146:149], v[184:187], v[26:29]
	v_mfma_f32_16x16x32_bf16 v[18:21], v[138:141], v[192:195], v[18:21]
	v_mfma_f32_16x16x32_bf16 v[10:13], v[146:149], v[192:195], v[10:13]
	v_mfma_f32_16x16x32_bf16 v[62:65], v[142:145], v[158:161], v[62:65]
	v_mfma_f32_16x16x32_bf16 v[58:61], v[150:153], v[158:161], v[58:61]
	v_mfma_f32_16x16x32_bf16 v[50:53], v[142:145], v[180:183], v[50:53]
	v_mfma_f32_16x16x32_bf16 v[42:45], v[150:153], v[180:183], v[42:45]
	v_mfma_f32_16x16x32_bf16 v[34:37], v[142:145], v[188:191], v[34:37]
	v_mfma_f32_16x16x32_bf16 v[26:29], v[150:153], v[188:191], v[26:29]
	v_mfma_f32_16x16x32_bf16 v[18:21], v[142:145], v[196:199], v[18:21]
	v_mfma_f32_16x16x32_bf16 v[10:13], v[150:153], v[196:199], v[10:13]
.La3_skip3:
	s_nop 0
	s_barrier
	s_add_u32 s44, s20, 0x20000
	s_addc_u32 s45, s21, 0
	s_add_i32 s46, s46, s27
	v_lshl_add_u64 v[138:139], s[44:45], 0, v[0:1]
	s_mov_b32 m0, s46
	s_nop 0
	global_load_lds_dwordx4 v[138:139], off
	v_lshl_add_u64 v[138:139], s[44:45], 0, v[130:131]
	s_add_i32 m0, s46, 0x2000
	s_nop 0
	global_load_lds_dwordx4 v[138:139], off
	s_waitcnt vmcnt(6)
	s_barrier
	s_nop 0
	s_cmp_lg_u32 s99, 0
	s_cbranch_scc1 .La3_skip4
	v_mfma_f32_16x16x32_bf16 v[54:57], v[230:233], v[154:157], v[54:57]
	v_mfma_f32_16x16x32_bf16 v[46:49], v[238:241], v[154:157], v[46:49]
	v_mfma_f32_16x16x32_bf16 v[38:41], v[230:233], v[176:179], v[38:41]
	v_mfma_f32_16x16x32_bf16 v[30:33], v[238:241], v[176:179], v[30:33]
	v_mfma_f32_16x16x32_bf16 v[22:25], v[230:233], v[184:187], v[22:25]
	v_mfma_f32_16x16x32_bf16 v[14:17], v[238:241], v[184:187], v[14:17]
	v_mfma_f32_16x16x32_bf16 v[6:9], v[230:233], v[192:195], v[6:9]
	v_mfma_f32_16x16x32_bf16 v[2:5], v[238:241], v[192:195], v[2:5]
	v_mfma_f32_16x16x32_bf16 v[54:57], v[234:237], v[158:161], v[54:57]
	v_mfma_f32_16x16x32_bf16 v[46:49], v[242:245], v[158:161], v[46:49]
	v_mfma_f32_16x16x32_bf16 v[38:41], v[234:237], v[180:183], v[38:41]
	v_mfma_f32_16x16x32_bf16 v[30:33], v[242:245], v[180:183], v[30:33]
	v_mfma_f32_16x16x32_bf16 v[22:25], v[234:237], v[188:191], v[22:25]
	v_mfma_f32_16x16x32_bf16 v[14:17], v[242:245], v[188:191], v[14:17]
	v_mfma_f32_16x16x32_bf16 v[6:9], v[234:237], v[196:199], v[6:9]
	v_mfma_f32_16x16x32_bf16 v[2:5], v[242:245], v[196:199], v[2:5]
.La3_skip4:
	s_nop 0
	s_add_i32 s44, 0, 0x18000
	v_add_u32_e32 v150, s44, v136
	s_barrier
	ds_read_b128 v[138:141], v150
	ds_read_b128 v[142:145], v150 offset:1024
	ds_read_b128 v[146:149], v150 offset:2048
	ds_read_b128 v[150:153], v150 offset:3072
	s_add_u32 s22, s22, 0x20000
	s_addc_u32 s23, s23, 0
	s_mov_b32 m0, s31
	v_lshl_add_u64 v[230:231], s[22:23], 0, v[0:1]
	ds_read_b128 v[154:157], v137 offset:32768
	ds_read_b128 v[158:161], v137 offset:33792
	ds_read_b128 v[176:179], v137 offset:34816
	ds_read_b128 v[180:183], v137 offset:35840
	ds_read_b128 v[184:187], v137 offset:36864
	ds_read_b128 v[188:191], v137 offset:37888
	ds_read_b128 v[192:195], v137 offset:38912
	ds_read_b128 v[196:199], v137 offset:39936
	global_load_lds_dwordx4 v[230:231], off
	v_lshl_add_u64 v[230:231], s[22:23], 0, v[130:131]
	s_mov_b32 m0, s34
	s_nop 0
	global_load_lds_dwordx4 v[230:231], off
	s_waitcnt lgkmcnt(8)
	s_barrier
	s_waitcnt lgkmcnt(0)
	s_nop 0
	s_waitcnt lgkmcnt(0)
	v_mfma_f32_16x16x32_bf16 v[126:129], v[138:141], v[154:157], v[126:129]
	v_mfma_f32_16x16x32_bf16 v[122:125], v[146:149], v[154:157], v[122:125]
	v_mfma_f32_16x16x32_bf16 v[114:117], v[138:141], v[176:179], v[114:117]
	v_mfma_f32_16x16x32_bf16 v[106:109], v[146:149], v[176:179], v[106:109]
	v_mfma_f32_16x16x32_bf16 v[98:101], v[138:141], v[184:187], v[98:101]
	v_mfma_f32_16x16x32_bf16 v[90:93], v[146:149], v[184:187], v[90:93]
	v_mfma_f32_16x16x32_bf16 v[82:85], v[138:141], v[192:195], v[82:85]
	v_mfma_f32_16x16x32_bf16 v[74:77], v[146:149], v[192:195], v[74:77]
	v_mfma_f32_16x16x32_bf16 v[126:129], v[142:145], v[158:161], v[126:129]
	v_mfma_f32_16x16x32_bf16 v[122:125], v[150:153], v[158:161], v[122:125]
	v_mfma_f32_16x16x32_bf16 v[114:117], v[142:145], v[180:183], v[114:117]
	v_mfma_f32_16x16x32_bf16 v[106:109], v[150:153], v[180:183], v[106:109]
	v_mfma_f32_16x16x32_bf16 v[98:101], v[142:145], v[188:191], v[98:101]
	v_mfma_f32_16x16x32_bf16 v[90:93], v[150:153], v[188:191], v[90:93]
	v_mfma_f32_16x16x32_bf16 v[82:85], v[142:145], v[196:199], v[82:85]
	v_mfma_f32_16x16x32_bf16 v[74:77], v[150:153], v[196:199], v[74:77]
	s_nop 0
	s_barrier
	s_add_i32 s22, 0, 0x1c000
	s_add_i32 s23, s44, s27
	v_add_u32_e32 v169, s22, v136
	v_lshl_add_u64 v[200:201], v[200:201], 0, s[92:93]
	s_mov_b32 m0, s23
	ds_read_b128 v[230:233], v169
	ds_read_b128 v[234:237], v169 offset:1024
	ds_read_b128 v[238:241], v169 offset:2048
	ds_read_b128 v[242:245], v169 offset:3072
	global_load_lds_dwordx4 v[200:201], off
	v_lshl_add_u64 v[200:201], v[246:247], 0, s[92:93]
	s_add_i32 m0, s23, 0x2000
	s_nop 0
	global_load_lds_dwordx4 v[200:201], off
	s_barrier
	s_waitcnt lgkmcnt(0)
	s_nop 0
	s_waitcnt lgkmcnt(0)
	v_mfma_f32_16x16x32_bf16 v[118:121], v[230:233], v[154:157], v[118:121]
	v_mfma_f32_16x16x32_bf16 v[110:113], v[238:241], v[154:157], v[110:113]
	v_mfma_f32_16x16x32_bf16 v[102:105], v[230:233], v[176:179], v[102:105]
	v_mfma_f32_16x16x32_bf16 v[94:97], v[238:241], v[176:179], v[94:97]
	v_mfma_f32_16x16x32_bf16 v[86:89], v[230:233], v[184:187], v[86:89]
	v_mfma_f32_16x16x32_bf16 v[78:81], v[238:241], v[184:187], v[78:81]
	v_mfma_f32_16x16x32_bf16 v[70:73], v[230:233], v[192:195], v[70:73]
	v_mfma_f32_16x16x32_bf16 v[66:69], v[238:241], v[192:195], v[66:69]
	v_mfma_f32_16x16x32_bf16 v[118:121], v[234:237], v[158:161], v[118:121]
	v_mfma_f32_16x16x32_bf16 v[110:113], v[242:245], v[158:161], v[110:113]
	v_mfma_f32_16x16x32_bf16 v[102:105], v[234:237], v[180:183], v[102:105]
	v_mfma_f32_16x16x32_bf16 v[94:97], v[242:245], v[180:183], v[94:97]
	v_mfma_f32_16x16x32_bf16 v[86:89], v[234:237], v[188:191], v[86:89]
	v_mfma_f32_16x16x32_bf16 v[78:81], v[242:245], v[188:191], v[78:81]
	v_mfma_f32_16x16x32_bf16 v[70:73], v[234:237], v[196:199], v[70:73]
	v_mfma_f32_16x16x32_bf16 v[66:69], v[242:245], v[196:199], v[66:69]
	s_nop 0
	s_mov_b32 m0, s35
	v_lshl_add_u64 v[200:201], v[248:249], 0, s[92:93]
	s_barrier
	ds_read_b128 v[154:157], v137 offset:49152
	ds_read_b128 v[158:161], v137 offset:50176
	ds_read_b128 v[176:179], v137 offset:51200
	ds_read_b128 v[180:183], v137 offset:52224
	ds_read_b128 v[184:187], v137 offset:53248
	ds_read_b128 v[188:191], v137 offset:54272
	ds_read_b128 v[192:195], v137 offset:55296
	ds_read_b128 v[196:199], v137 offset:56320
	global_load_lds_dwordx4 v[200:201], off
	v_lshl_add_u64 v[200:201], v[250:251], 0, s[92:93]
	s_mov_b32 m0, s36
	s_nop 0
	global_load_lds_dwordx4 v[200:201], off
	s_barrier
	s_waitcnt lgkmcnt(0)
	s_nop 0
	s_waitcnt lgkmcnt(0)
	s_cmp_lg_u32 s99, 0
	s_cbranch_scc1 .La3_skip7
	v_mfma_f32_16x16x32_bf16 v[62:65], v[138:141], v[154:157], v[62:65]
	v_mfma_f32_16x16x32_bf16 v[58:61], v[146:149], v[154:157], v[58:61]
	v_mfma_f32_16x16x32_bf16 v[50:53], v[138:141], v[176:179], v[50:53]
	v_mfma_f32_16x16x32_bf16 v[42:45], v[146:149], v[176:179], v[42:45]
	v_mfma_f32_16x16x32_bf16 v[34:37], v[138:141], v[184:187], v[34:37]
	v_mfma_f32_16x16x32_bf16 v[26:29], v[146:149], v[184:187], v[26:29]
	v_mfma_f32_16x16x32_bf16 v[18:21], v[138:141], v[192:195], v[18:21]
	v_mfma_f32_16x16x32_bf16 v[10:13], v[146:149], v[192:195], v[10:13]
	v_mfma_f32_16x16x32_bf16 v[62:65], v[142:145], v[158:161], v[62:65]
	v_mfma_f32_16x16x32_bf16 v[58:61], v[150:153], v[158:161], v[58:61]
	v_mfma_f32_16x16x32_bf16 v[50:53], v[142:145], v[180:183], v[50:53]
	v_mfma_f32_16x16x32_bf16 v[42:45], v[150:153], v[180:183], v[42:45]
	v_mfma_f32_16x16x32_bf16 v[34:37], v[142:145], v[188:191], v[34:37]
	v_mfma_f32_16x16x32_bf16 v[26:29], v[150:153], v[188:191], v[26:29]
	v_mfma_f32_16x16x32_bf16 v[18:21], v[142:145], v[196:199], v[18:21]
	v_mfma_f32_16x16x32_bf16 v[10:13], v[150:153], v[196:199], v[10:13]
.La3_skip7:
	s_nop 0
	s_barrier
	s_add_u32 s20, s20, 0x20080
	s_addc_u32 s21, s21, 0
	s_add_i32 s22, s22, s27
	v_lshl_add_u64 v[138:139], s[20:21], 0, v[0:1]
	s_mov_b32 m0, s22
	s_nop 0
	global_load_lds_dwordx4 v[138:139], off
	v_lshl_add_u64 v[138:139], s[20:21], 0, v[130:131]
	s_add_i32 m0, s22, 0x2000
	s_nop 0
	global_load_lds_dwordx4 v[138:139], off
	s_waitcnt vmcnt(6)
	s_barrier
	s_nop 0
	s_cmp_lg_u32 s99, 0
	s_cbranch_scc1 .La3_skip8
	v_mfma_f32_16x16x32_bf16 v[54:57], v[230:233], v[154:157], v[54:57]
	v_mfma_f32_16x16x32_bf16 v[46:49], v[238:241], v[154:157], v[46:49]
	v_mfma_f32_16x16x32_bf16 v[38:41], v[230:233], v[176:179], v[38:41]
	v_mfma_f32_16x16x32_bf16 v[30:33], v[238:241], v[176:179], v[30:33]
	v_mfma_f32_16x16x32_bf16 v[22:25], v[230:233], v[184:187], v[22:25]
	v_mfma_f32_16x16x32_bf16 v[14:17], v[238:241], v[184:187], v[14:17]
	v_mfma_f32_16x16x32_bf16 v[6:9], v[230:233], v[192:195], v[6:9]
	v_mfma_f32_16x16x32_bf16 v[2:5], v[238:241], v[192:195], v[2:5]
	v_mfma_f32_16x16x32_bf16 v[54:57], v[234:237], v[158:161], v[54:57]
	v_mfma_f32_16x16x32_bf16 v[46:49], v[242:245], v[158:161], v[46:49]
	v_mfma_f32_16x16x32_bf16 v[38:41], v[234:237], v[180:183], v[38:41]
	v_mfma_f32_16x16x32_bf16 v[30:33], v[242:245], v[180:183], v[30:33]
	v_mfma_f32_16x16x32_bf16 v[22:25], v[234:237], v[188:191], v[22:25]
	v_mfma_f32_16x16x32_bf16 v[14:17], v[242:245], v[188:191], v[14:17]
	v_mfma_f32_16x16x32_bf16 v[6:9], v[234:237], v[196:199], v[6:9]
	v_mfma_f32_16x16x32_bf16 v[2:5], v[242:245], v[196:199], v[2:5]
.La3_skip8:
	s_nop 0
	s_add_i32 s43, s43, 2
	s_add_u32 s41, s41, 0x100
	s_addc_u32 s42, s42, 0
	s_add_u32 s8, s8, 0x100
	s_addc_u32 s9, s9, 0
	s_cmp_gt_u32 s43, 1
	s_barrier
	s_cbranch_scc0 .LBB0_893
	s_setprio 0
	v_mov_b32_e32 v138, v163
	s_lshl_b32 s7, s7, 8
	v_and_b32_e32 v139, 15, v138
	v_and_b32_e32 v140, 0xc0, v138
	v_ashrrev_i32_e32 v141, 2, v138
	v_lshrrev_b32_e32 v138, 1, v138
	v_and_b32_e32 v138, 24, v138
	v_or3_b32 v138, v140, s7, v138
	s_movk_i32 s7, 0xffc0
	v_and_or_b32 v139, v141, s7, v139
	v_lshl_add_u32 v140, s6, 8, v139
	v_readlane_b32 s98, v254, 0
	s_and_b32 s98, s98, s99
	s_lshl_b32 s98, s98, 7
	v_add_u32_e32 v140, s98, v140
	v_ashrrev_i32_e32 v141, 31, v140
	s_mov_b32 s20, 0x3db504f3
	s_movk_i32 s6, 0x1ff
	v_readlane_b32 s8, v254, 35
	v_lshlrev_b64 v[142:143], 11, v[140:141]
	v_pk_mul_f32 v[144:145], v[128:129], s[20:21] op_sel_hi:[1,0]
	v_pk_mul_f32 v[146:147], v[126:127], s[20:21] op_sel_hi:[1,0]
	v_pk_mul_f32 v[148:149], v[124:125], s[20:21] op_sel_hi:[1,0]
	v_pk_mul_f32 v[150:151], v[122:123], s[20:21] op_sel_hi:[1,0]
	v_cmp_lt_i32_e32 vcc, s6, v138
	v_readlane_b32 s9, v254, 36
	v_ashrrev_i32_e32 v139, 31, v138
	v_cndmask_b32_e32 v141, v129, v145, vcc
	v_cndmask_b32_e32 v144, v128, v144, vcc
	v_cndmask_b32_e32 v127, v127, v147, vcc
	v_cndmask_b32_e32 v126, v126, v146, vcc
	v_cndmask_b32_e32 v145, v125, v149, vcc
	v_cndmask_b32_e32 v146, v124, v148, vcc
	v_cndmask_b32_e32 v147, v123, v151, vcc
	v_cndmask_b32_e32 v148, v122, v150, vcc
	v_lshl_add_u64 v[122:123], s[8:9], 0, v[142:143]
	v_lshlrev_b64 v[128:129], 1, v[138:139]
	v_lshl_add_u64 v[122:123], v[122:123], 0, v[128:129]
	v_cvt_pk_bf16_f32 v124, v126, v127
	v_cvt_pk_bf16_f32 v125, v144, v141
	v_cvt_pk_bf16_f32 v126, v148, v147
	v_cvt_pk_bf16_f32 v127, v146, v145
	v_or_b32_e32 v141, 32, v138
	global_store_dwordx4 v[122:123], v[124:127], off
	v_pk_mul_f32 v[138:139], v[112:113], s[20:21] op_sel_hi:[1,0]
	v_pk_mul_f32 v[142:143], v[110:111], s[20:21] op_sel_hi:[1,0]
	v_pk_mul_f32 v[124:125], v[120:121], s[20:21] op_sel_hi:[1,0]
	v_pk_mul_f32 v[126:127], v[118:119], s[20:21] op_sel_hi:[1,0]
	v_cmp_lt_i32_e64 s[6:7], s6, v141
	s_nop 1
	v_cndmask_b32_e64 v121, v121, v125, s[6:7]
	v_cndmask_b32_e64 v120, v120, v124, s[6:7]
	v_cndmask_b32_e64 v119, v119, v127, s[6:7]
	v_cndmask_b32_e64 v118, v118, v126, s[6:7]
	v_cndmask_b32_e64 v113, v113, v139, s[6:7]
	v_cndmask_b32_e64 v124, v112, v138, s[6:7]
	v_cndmask_b32_e64 v112, v111, v143, s[6:7]
	v_cndmask_b32_e64 v125, v110, v142, s[6:7]
	v_cvt_pk_bf16_f32 v110, v118, v119
	v_cvt_pk_bf16_f32 v111, v120, v121
	v_cvt_pk_bf16_f32 v112, v125, v112
	v_cvt_pk_bf16_f32 v113, v124, v113
	global_store_dwordx4 v[122:123], v[110:113], off offset:64
	v_pk_mul_f32 v[118:119], v[114:115], s[20:21] op_sel_hi:[1,0]
	v_pk_mul_f32 v[120:121], v[108:109], s[20:21] op_sel_hi:[1,0]
	v_or_b32_e32 v110, 16, v140
	v_ashrrev_i32_e32 v111, 31, v110
	v_lshlrev_b64 v[110:111], 11, v[110:111]
	v_pk_mul_f32 v[112:113], v[116:117], s[20:21] op_sel_hi:[1,0]
	v_pk_mul_f32 v[124:125], v[106:107], s[20:21] op_sel_hi:[1,0]
	v_cndmask_b32_e32 v113, v117, v113, vcc
	v_cndmask_b32_e32 v112, v116, v112, vcc
	v_cndmask_b32_e32 v115, v115, v119, vcc
	v_cndmask_b32_e32 v114, v114, v118, vcc
	v_cndmask_b32_e32 v109, v109, v121, vcc
	v_cndmask_b32_e32 v116, v108, v120, vcc
	v_cndmask_b32_e32 v108, v107, v125, vcc
	v_cndmask_b32_e32 v117, v106, v124, vcc
	v_lshl_add_u64 v[106:107], s[8:9], 0, v[110:111]
	v_lshl_add_u64 v[110:111], v[106:107], 0, v[128:129]
	v_cvt_pk_bf16_f32 v106, v114, v115
	v_cvt_pk_bf16_f32 v107, v112, v113
	v_cvt_pk_bf16_f32 v108, v117, v108
	v_cvt_pk_bf16_f32 v109, v116, v109
	global_store_dwordx4 v[110:111], v[106:109], off
	v_pk_mul_f32 v[112:113], v[96:97], s[20:21] op_sel_hi:[1,0]
	v_pk_mul_f32 v[114:115], v[94:95], s[20:21] op_sel_hi:[1,0]
	v_pk_mul_f32 v[106:107], v[104:105], s[20:21] op_sel_hi:[1,0]
	v_pk_mul_f32 v[108:109], v[102:103], s[20:21] op_sel_hi:[1,0]
	v_cndmask_b32_e64 v105, v105, v107, s[6:7]
	v_cndmask_b32_e64 v104, v104, v106, s[6:7]
	v_cndmask_b32_e64 v103, v103, v109, s[6:7]
	v_cndmask_b32_e64 v102, v102, v108, s[6:7]
	v_cndmask_b32_e64 v97, v97, v113, s[6:7]
	v_cndmask_b32_e64 v106, v96, v112, s[6:7]
	v_cndmask_b32_e64 v96, v95, v115, s[6:7]
	v_cndmask_b32_e64 v107, v94, v114, s[6:7]
	v_cvt_pk_bf16_f32 v94, v102, v103
	v_cvt_pk_bf16_f32 v95, v104, v105
	v_cvt_pk_bf16_f32 v96, v107, v96
	v_cvt_pk_bf16_f32 v97, v106, v97
	global_store_dwordx4 v[110:111], v[94:97], off offset:64
	v_pk_mul_f32 v[102:103], v[98:99], s[20:21] op_sel_hi:[1,0]
	v_pk_mul_f32 v[104:105], v[92:93], s[20:21] op_sel_hi:[1,0]
	v_or_b32_e32 v94, 32, v140
	v_ashrrev_i32_e32 v95, 31, v94
	v_lshlrev_b64 v[94:95], 11, v[94:95]
	v_pk_mul_f32 v[96:97], v[100:101], s[20:21] op_sel_hi:[1,0]
	v_pk_mul_f32 v[106:107], v[90:91], s[20:21] op_sel_hi:[1,0]
	v_cndmask_b32_e32 v97, v101, v97, vcc
	v_cndmask_b32_e32 v96, v100, v96, vcc
	v_cndmask_b32_e32 v99, v99, v103, vcc
	v_cndmask_b32_e32 v98, v98, v102, vcc
	v_cndmask_b32_e32 v93, v93, v105, vcc
	v_cndmask_b32_e32 v100, v92, v104, vcc
	v_cndmask_b32_e32 v92, v91, v107, vcc
	v_cndmask_b32_e32 v101, v90, v106, vcc
	v_lshl_add_u64 v[90:91], s[8:9], 0, v[94:95]
	v_lshl_add_u64 v[94:95], v[90:91], 0, v[128:129]
	v_cvt_pk_bf16_f32 v90, v98, v99
	v_cvt_pk_bf16_f32 v91, v96, v97
	v_cvt_pk_bf16_f32 v92, v101, v92
	v_cvt_pk_bf16_f32 v93, v100, v93
	global_store_dwordx4 v[94:95], v[90:93], off
	v_pk_mul_f32 v[96:97], v[80:81], s[20:21] op_sel_hi:[1,0]
	v_pk_mul_f32 v[98:99], v[78:79], s[20:21] op_sel_hi:[1,0]
	v_pk_mul_f32 v[90:91], v[88:89], s[20:21] op_sel_hi:[1,0]
	v_pk_mul_f32 v[92:93], v[86:87], s[20:21] op_sel_hi:[1,0]
	v_cndmask_b32_e64 v89, v89, v91, s[6:7]
	v_cndmask_b32_e64 v88, v88, v90, s[6:7]
	v_cndmask_b32_e64 v87, v87, v93, s[6:7]
	v_cndmask_b32_e64 v86, v86, v92, s[6:7]
	v_cndmask_b32_e64 v81, v81, v97, s[6:7]
	v_cndmask_b32_e64 v90, v80, v96, s[6:7]
	v_cndmask_b32_e64 v80, v79, v99, s[6:7]
	v_cndmask_b32_e64 v91, v78, v98, s[6:7]
	v_cvt_pk_bf16_f32 v78, v86, v87
	v_cvt_pk_bf16_f32 v79, v88, v89
	v_cvt_pk_bf16_f32 v80, v91, v80
	v_cvt_pk_bf16_f32 v81, v90, v81
	global_store_dwordx4 v[94:95], v[78:81], off offset:64
	v_pk_mul_f32 v[86:87], v[82:83], s[20:21] op_sel_hi:[1,0]
	v_pk_mul_f32 v[88:89], v[76:77], s[20:21] op_sel_hi:[1,0]
	v_or_b32_e32 v78, 48, v140
	v_ashrrev_i32_e32 v79, 31, v78
	v_lshlrev_b64 v[78:79], 11, v[78:79]
	v_pk_mul_f32 v[80:81], v[84:85], s[20:21] op_sel_hi:[1,0]
	v_pk_mul_f32 v[90:91], v[74:75], s[20:21] op_sel_hi:[1,0]
	v_cndmask_b32_e32 v81, v85, v81, vcc
	v_cndmask_b32_e32 v80, v84, v80, vcc
	v_cndmask_b32_e32 v83, v83, v87, vcc
	v_cndmask_b32_e32 v82, v82, v86, vcc
	v_cndmask_b32_e32 v77, v77, v89, vcc
	v_cndmask_b32_e32 v84, v76, v88, vcc
	v_cndmask_b32_e32 v76, v75, v91, vcc
	v_cndmask_b32_e32 v85, v74, v90, vcc
	v_lshl_add_u64 v[74:75], s[8:9], 0, v[78:79]
	v_lshl_add_u64 v[78:79], v[74:75], 0, v[128:129]
	v_cvt_pk_bf16_f32 v74, v82, v83
	v_cvt_pk_bf16_f32 v75, v80, v81
	v_cvt_pk_bf16_f32 v76, v85, v76
	v_cvt_pk_bf16_f32 v77, v84, v77
	global_store_dwordx4 v[78:79], v[74:77], off
	v_pk_mul_f32 v[80:81], v[68:69], s[20:21] op_sel_hi:[1,0]
	v_pk_mul_f32 v[82:83], v[66:67], s[20:21] op_sel_hi:[1,0]
	v_pk_mul_f32 v[74:75], v[72:73], s[20:21] op_sel_hi:[1,0]
	v_pk_mul_f32 v[76:77], v[70:71], s[20:21] op_sel_hi:[1,0]
	v_cndmask_b32_e64 v73, v73, v75, s[6:7]
	v_cndmask_b32_e64 v72, v72, v74, s[6:7]
	v_cndmask_b32_e64 v71, v71, v77, s[6:7]
	v_cndmask_b32_e64 v70, v70, v76, s[6:7]
	v_cndmask_b32_e64 v69, v69, v81, s[6:7]
	v_cndmask_b32_e64 v74, v68, v80, s[6:7]
	v_cndmask_b32_e64 v68, v67, v83, s[6:7]
	v_cndmask_b32_e64 v75, v66, v82, s[6:7]
	v_cvt_pk_bf16_f32 v66, v70, v71
	v_cvt_pk_bf16_f32 v67, v72, v73
	v_cvt_pk_bf16_f32 v68, v75, v68
	v_cvt_pk_bf16_f32 v69, v74, v69
	global_store_dwordx4 v[78:79], v[66:69], off offset:64
	s_cmp_lg_u32 s99, 0
	s_cbranch_scc1 .La3_half_done
	s_mov_b64 s[8:9], 0x40000
	v_pk_mul_f32 v[70:71], v[60:61], s[20:21] op_sel_hi:[1,0]
	v_pk_mul_f32 v[66:67], v[64:65], s[20:21] op_sel_hi:[1,0]
	v_pk_mul_f32 v[68:69], v[62:63], s[20:21] op_sel_hi:[1,0]
	v_pk_mul_f32 v[72:73], v[58:59], s[20:21] op_sel_hi:[1,0]
	v_cndmask_b32_e32 v65, v65, v67, vcc
	v_cndmask_b32_e32 v64, v64, v66, vcc
	v_cndmask_b32_e32 v66, v63, v69, vcc
	v_cndmask_b32_e32 v67, v62, v68, vcc
	v_lshl_add_u64 v[62:63], v[122:123], 0, s[8:9]
	s_mov_b32 s8, 0x40000
	v_cndmask_b32_e32 v61, v61, v71, vcc
	v_cndmask_b32_e32 v68, v60, v70, vcc
	v_cndmask_b32_e32 v60, v59, v73, vcc
	v_cndmask_b32_e32 v69, v58, v72, vcc
	v_cvt_pk_bf16_f32 v59, v64, v65
	v_add_co_u32_e64 v64, s[8:9], s8, v122
	v_cvt_pk_bf16_f32 v58, v67, v66
	v_cvt_pk_bf16_f32 v60, v69, v60
	v_cvt_pk_bf16_f32 v61, v68, v61
	v_addc_co_u32_e64 v65, s[8:9], 0, v123, s[8:9]
	global_store_dwordx4 v[64:65], v[58:61], off
	v_pk_mul_f32 v[64:65], v[48:49], s[20:21] op_sel_hi:[1,0]
	v_pk_mul_f32 v[66:67], v[46:47], s[20:21] op_sel_hi:[1,0]
	v_pk_mul_f32 v[58:59], v[56:57], s[20:21] op_sel_hi:[1,0]
	v_pk_mul_f32 v[60:61], v[54:55], s[20:21] op_sel_hi:[1,0]
	v_cndmask_b32_e64 v57, v57, v59, s[6:7]
	v_cndmask_b32_e64 v56, v56, v58, s[6:7]
	v_cndmask_b32_e64 v55, v55, v61, s[6:7]
	v_cndmask_b32_e64 v54, v54, v60, s[6:7]
	v_cndmask_b32_e64 v49, v49, v65, s[6:7]
	v_cndmask_b32_e64 v58, v48, v64, s[6:7]
	v_cndmask_b32_e64 v48, v47, v67, s[6:7]
	v_cndmask_b32_e64 v59, v46, v66, s[6:7]
	v_cvt_pk_bf16_f32 v46, v54, v55
	v_cvt_pk_bf16_f32 v47, v56, v57
	v_cvt_pk_bf16_f32 v48, v59, v48
	v_cvt_pk_bf16_f32 v49, v58, v49
	global_store_dwordx4 v[62:63], v[46:49], off offset:64
	v_pk_mul_f32 v[54:55], v[44:45], s[20:21] op_sel_hi:[1,0]
	v_pk_mul_f32 v[56:57], v[42:43], s[20:21] op_sel_hi:[1,0]
	v_pk_mul_f32 v[48:49], v[50:51], s[20:21] op_sel_hi:[1,0]
	v_pk_mul_f32 v[46:47], v[52:53], s[20:21] op_sel_hi:[1,0]
	v_cndmask_b32_e32 v49, v51, v49, vcc
	v_cndmask_b32_e32 v48, v50, v48, vcc
	s_mov_b64 s[8:9], 0x48000
	v_cndmask_b32_e32 v53, v53, v47, vcc
	v_cndmask_b32_e32 v52, v52, v46, vcc
	v_cndmask_b32_e32 v45, v45, v55, vcc
	v_cndmask_b32_e32 v50, v44, v54, vcc
	v_cndmask_b32_e32 v44, v43, v57, vcc
	v_cndmask_b32_e32 v51, v42, v56, vcc
	v_lshl_add_u64 v[46:47], v[122:123], 0, s[8:9]
	v_cvt_pk_bf16_f32 v42, v48, v49
	v_add_co_u32_e64 v48, s[8:9], s95, v122
	v_cvt_pk_bf16_f32 v43, v52, v53
	v_cvt_pk_bf16_f32 v44, v51, v44
	v_cvt_pk_bf16_f32 v45, v50, v45
	v_addc_co_u32_e64 v49, s[8:9], 0, v123, s[8:9]
	global_store_dwordx4 v[48:49], v[42:45], off
	v_pk_mul_f32 v[48:49], v[32:33], s[20:21] op_sel_hi:[1,0]
	v_pk_mul_f32 v[50:51], v[30:31], s[20:21] op_sel_hi:[1,0]
	v_pk_mul_f32 v[42:43], v[40:41], s[20:21] op_sel_hi:[1,0]
	v_pk_mul_f32 v[44:45], v[38:39], s[20:21] op_sel_hi:[1,0]
	v_cndmask_b32_e64 v41, v41, v43, s[6:7]
	v_cndmask_b32_e64 v40, v40, v42, s[6:7]
	v_cndmask_b32_e64 v39, v39, v45, s[6:7]
	v_cndmask_b32_e64 v38, v38, v44, s[6:7]
	v_cndmask_b32_e64 v33, v33, v49, s[6:7]
	v_cndmask_b32_e64 v42, v32, v48, s[6:7]
	v_cndmask_b32_e64 v32, v31, v51, s[6:7]
	v_cndmask_b32_e64 v43, v30, v50, s[6:7]
	v_cvt_pk_bf16_f32 v30, v38, v39
	v_cvt_pk_bf16_f32 v31, v40, v41
	v_cvt_pk_bf16_f32 v32, v43, v32
	v_cvt_pk_bf16_f32 v33, v42, v33
	global_store_dwordx4 v[46:47], v[30:33], off offset:64
	s_mov_b64 s[8:9], 0x50000
	v_pk_mul_f32 v[38:39], v[28:29], s[20:21] op_sel_hi:[1,0]
	v_pk_mul_f32 v[30:31], v[36:37], s[20:21] op_sel_hi:[1,0]
	v_pk_mul_f32 v[32:33], v[34:35], s[20:21] op_sel_hi:[1,0]
	v_pk_mul_f32 v[40:41], v[26:27], s[20:21] op_sel_hi:[1,0]
	v_cndmask_b32_e32 v37, v37, v31, vcc
	v_cndmask_b32_e32 v36, v36, v30, vcc
	v_cndmask_b32_e32 v33, v35, v33, vcc
	v_cndmask_b32_e32 v32, v34, v32, vcc
	v_lshl_add_u64 v[30:31], v[122:123], 0, s[8:9]
	s_mov_b32 s8, 0x50000
	v_cndmask_b32_e32 v29, v29, v39, vcc
	v_cndmask_b32_e32 v34, v28, v38, vcc
	v_cndmask_b32_e32 v28, v27, v41, vcc
	v_cndmask_b32_e32 v35, v26, v40, vcc
	v_cvt_pk_bf16_f32 v26, v32, v33
	v_add_co_u32_e64 v32, s[8:9], s8, v122
	v_cvt_pk_bf16_f32 v27, v36, v37
	v_cvt_pk_bf16_f32 v28, v35, v28
	v_cvt_pk_bf16_f32 v29, v34, v29
	v_addc_co_u32_e64 v33, s[8:9], 0, v123, s[8:9]
	global_store_dwordx4 v[32:33], v[26:29], off
	v_pk_mul_f32 v[32:33], v[16:17], s[20:21] op_sel_hi:[1,0]
	v_pk_mul_f32 v[34:35], v[14:15], s[20:21] op_sel_hi:[1,0]
	v_pk_mul_f32 v[26:27], v[24:25], s[20:21] op_sel_hi:[1,0]
	v_pk_mul_f32 v[28:29], v[22:23], s[20:21] op_sel_hi:[1,0]
	v_cndmask_b32_e64 v25, v25, v27, s[6:7]
	v_cndmask_b32_e64 v24, v24, v26, s[6:7]
	v_cndmask_b32_e64 v23, v23, v29, s[6:7]
	v_cndmask_b32_e64 v22, v22, v28, s[6:7]
	v_cndmask_b32_e64 v17, v17, v33, s[6:7]
	v_cndmask_b32_e64 v26, v16, v32, s[6:7]
	v_cndmask_b32_e64 v16, v15, v35, s[6:7]
	v_cndmask_b32_e64 v27, v14, v34, s[6:7]
	v_cvt_pk_bf16_f32 v14, v22, v23
	v_cvt_pk_bf16_f32 v15, v24, v25
	v_cvt_pk_bf16_f32 v16, v27, v16
	v_cvt_pk_bf16_f32 v17, v26, v17
	global_store_dwordx4 v[30:31], v[14:17], off offset:64
	s_mov_b64 s[8:9], 0x58000
	v_pk_mul_f32 v[22:23], v[12:13], s[20:21] op_sel_hi:[1,0]
	v_pk_mul_f32 v[14:15], v[20:21], s[20:21] op_sel_hi:[1,0]
	v_pk_mul_f32 v[16:17], v[18:19], s[20:21] op_sel_hi:[1,0]
	v_pk_mul_f32 v[24:25], v[10:11], s[20:21] op_sel_hi:[1,0]
	v_cndmask_b32_e32 v21, v21, v15, vcc
	v_cndmask_b32_e32 v20, v20, v14, vcc
	v_cndmask_b32_e32 v17, v19, v17, vcc
	v_cndmask_b32_e32 v16, v18, v16, vcc
	v_lshl_add_u64 v[14:15], v[122:123], 0, s[8:9]
	s_mov_b32 s8, 0x58000
	v_cndmask_b32_e32 v13, v13, v23, vcc
	v_cndmask_b32_e32 v18, v12, v22, vcc
	v_cndmask_b32_e32 v12, v11, v25, vcc
	v_cndmask_b32_e32 v19, v10, v24, vcc
	v_cvt_pk_bf16_f32 v10, v16, v17
	v_add_co_u32_e32 v16, vcc, s8, v122
	v_cvt_pk_bf16_f32 v11, v20, v21
	v_cvt_pk_bf16_f32 v12, v19, v12
	v_cvt_pk_bf16_f32 v13, v18, v13
	v_addc_co_u32_e32 v17, vcc, 0, v123, vcc
	global_store_dwordx4 v[16:17], v[10:13], off
	v_pk_mul_f32 v[16:17], v[4:5], s[20:21] op_sel_hi:[1,0]
	v_pk_mul_f32 v[18:19], v[2:3], s[20:21] op_sel_hi:[1,0]
	v_pk_mul_f32 v[10:11], v[8:9], s[20:21] op_sel_hi:[1,0]
	v_pk_mul_f32 v[12:13], v[6:7], s[20:21] op_sel_hi:[1,0]
	v_cndmask_b32_e64 v9, v9, v11, s[6:7]
	v_cndmask_b32_e64 v8, v8, v10, s[6:7]
	v_cndmask_b32_e64 v7, v7, v13, s[6:7]
	v_cndmask_b32_e64 v6, v6, v12, s[6:7]
	v_cndmask_b32_e64 v5, v5, v17, s[6:7]
	v_cndmask_b32_e64 v10, v4, v16, s[6:7]
	v_cndmask_b32_e64 v4, v3, v19, s[6:7]
	v_cndmask_b32_e64 v11, v2, v18, s[6:7]
	v_cvt_pk_bf16_f32 v2, v6, v7
	v_cvt_pk_bf16_f32 v3, v8, v9
	v_cvt_pk_bf16_f32 v4, v11, v4
	v_cvt_pk_bf16_f32 v5, v10, v5
	s_and_b64 vcc, exec, s[4:5]
	s_mov_b32 s7, s10
	s_mov_b32 s6, s12
	s_mov_b64 s[8:9], s[18:19]
	s_mov_b64 s[20:21], s[16:17]
	global_store_dwordx4 v[14:15], v[2:5], off offset:64
	s_cbranch_vccz .LBB0_890
	s_branch .La3_exit

.LBB0_917:
	v_mov_b64_e32 v[2:3], 0x3c0
	s_ashr_i32 s21, s20, 31
	v_cmp_lt_i64_e32 vcc, s[22:23], v[2:3]
	s_lshl_b64 s[22:23], s[20:21], 19
	v_readlane_b32 s24, v254, 33
	v_readlane_b32 s25, v254, 34
	s_add_u32 s22, s24, s22
	s_addc_u32 s23, s25, s23
	s_and_b64 s[24:25], vcc, exec
	s_cselect_b32 s7, s23, s29
	s_cselect_b32 s9, s22, s28
	s_ashr_i32 s19, s18, 31
	s_lshl_b64 s[24:25], s[18:19], 19
	s_add_u32 s24, s3, s24
	s_addc_u32 s25, s36, s25
	s_and_b64 s[30:31], vcc, exec
	s_cselect_b32 s19, s25, s27
	s_cselect_b32 s21, s24, s26
	s_add_u32 s34, s26, 0x100
	s_addc_u32 s35, s27, 0
	s_add_u32 s26, s28, 0x40080
	v_mov_b32_e32 v2, 0
	s_addc_u32 s27, s29, 0
	s_mov_b32 s47, -2
	v_mov_b32_e32 v3, v2
	v_mov_b32_e32 v4, v2
	v_mov_b32_e32 v5, v2
	v_mov_b32_e32 v6, v2
	v_mov_b32_e32 v7, v2
	v_mov_b32_e32 v8, v2
	v_mov_b32_e32 v9, v2
	v_mov_b32_e32 v18, v2
	v_mov_b32_e32 v19, v2
	v_mov_b32_e32 v20, v2
	v_mov_b32_e32 v21, v2
	v_mov_b32_e32 v22, v2
	v_mov_b32_e32 v23, v2
	v_mov_b32_e32 v24, v2
	v_mov_b32_e32 v25, v2
	v_mov_b32_e32 v34, v2
	v_mov_b32_e32 v35, v2
	v_mov_b32_e32 v36, v2
	v_mov_b32_e32 v37, v2
	v_mov_b32_e32 v38, v2
	v_mov_b32_e32 v39, v2
	v_mov_b32_e32 v40, v2
	v_mov_b32_e32 v41, v2
	v_mov_b32_e32 v50, v2
	v_mov_b32_e32 v51, v2
	v_mov_b32_e32 v52, v2
	v_mov_b32_e32 v53, v2
	v_mov_b32_e32 v54, v2
	v_mov_b32_e32 v55, v2
	v_mov_b32_e32 v56, v2
	v_mov_b32_e32 v57, v2
	v_mov_b32_e32 v10, v2
	v_mov_b32_e32 v11, v2
	v_mov_b32_e32 v12, v2
	v_mov_b32_e32 v13, v2
	v_mov_b32_e32 v14, v2
	v_mov_b32_e32 v15, v2
	v_mov_b32_e32 v16, v2
	v_mov_b32_e32 v17, v2
	v_mov_b32_e32 v26, v2
	v_mov_b32_e32 v27, v2
	v_mov_b32_e32 v28, v2
	v_mov_b32_e32 v29, v2
	v_mov_b32_e32 v30, v2
	v_mov_b32_e32 v31, v2
	v_mov_b32_e32 v32, v2
	v_mov_b32_e32 v33, v2
	v_mov_b32_e32 v42, v2
	v_mov_b32_e32 v43, v2
	v_mov_b32_e32 v44, v2
	v_mov_b32_e32 v45, v2
	v_mov_b32_e32 v46, v2
	v_mov_b32_e32 v47, v2
	v_mov_b32_e32 v48, v2
	v_mov_b32_e32 v49, v2
	v_mov_b32_e32 v58, v2
	v_mov_b32_e32 v59, v2
	v_mov_b32_e32 v60, v2
	v_mov_b32_e32 v61, v2
	v_mov_b32_e32 v62, v2
	v_mov_b32_e32 v63, v2
	v_mov_b32_e32 v64, v2
	v_mov_b32_e32 v65, v2
	v_mov_b32_e32 v66, v2
	v_mov_b32_e32 v67, v2
	v_mov_b32_e32 v68, v2
	v_mov_b32_e32 v69, v2
	v_mov_b32_e32 v70, v2
	v_mov_b32_e32 v71, v2
	v_mov_b32_e32 v72, v2
	v_mov_b32_e32 v73, v2
	v_mov_b32_e32 v82, v2
	v_mov_b32_e32 v83, v2
	v_mov_b32_e32 v84, v2
	v_mov_b32_e32 v85, v2
	v_mov_b32_e32 v86, v2
	v_mov_b32_e32 v87, v2
	v_mov_b32_e32 v88, v2
	v_mov_b32_e32 v89, v2
	v_mov_b32_e32 v98, v2
	v_mov_b32_e32 v99, v2
	v_mov_b32_e32 v100, v2
	v_mov_b32_e32 v101, v2
	v_mov_b32_e32 v102, v2
	v_mov_b32_e32 v103, v2
	v_mov_b32_e32 v104, v2
	v_mov_b32_e32 v105, v2
	v_mov_b32_e32 v114, v2
	v_mov_b32_e32 v115, v2
	v_mov_b32_e32 v116, v2
	v_mov_b32_e32 v117, v2
	v_mov_b32_e32 v118, v2
	v_mov_b32_e32 v119, v2
	v_mov_b32_e32 v120, v2
	v_mov_b32_e32 v121, v2
	v_mov_b32_e32 v74, v2
	v_mov_b32_e32 v75, v2
	v_mov_b32_e32 v76, v2
	v_mov_b32_e32 v77, v2
	v_mov_b32_e32 v78, v2
	v_mov_b32_e32 v79, v2
	v_mov_b32_e32 v80, v2
	v_mov_b32_e32 v81, v2
	v_mov_b32_e32 v90, v2
	v_mov_b32_e32 v91, v2
	v_mov_b32_e32 v92, v2
	v_mov_b32_e32 v93, v2
	v_mov_b32_e32 v94, v2
	v_mov_b32_e32 v95, v2
	v_mov_b32_e32 v96, v2
	v_mov_b32_e32 v97, v2
	v_mov_b32_e32 v106, v2
	v_mov_b32_e32 v107, v2
	v_mov_b32_e32 v108, v2
	v_mov_b32_e32 v109, v2
	v_mov_b32_e32 v110, v2
	v_mov_b32_e32 v111, v2
	v_mov_b32_e32 v112, v2
	v_mov_b32_e32 v113, v2
	v_mov_b32_e32 v122, v2
	v_mov_b32_e32 v123, v2
	v_mov_b32_e32 v124, v2
	v_mov_b32_e32 v125, v2
	v_mov_b32_e32 v126, v2
	v_mov_b32_e32 v127, v2
	v_mov_b32_e32 v128, v2
	v_mov_b32_e32 v129, v2
	v_cmp_lt_u32_e32 vcc, 0xff, v163
	s_nop 1
	s_cbranch_vccz .Lsprio_skip4
	s_setprio 1
.Lsprio_skip4:
.LBB0_918:
	s_add_u32 s28, s26, 0xfffc0080
	s_addc_u32 s29, s27, -1
	s_add_i32 s48, 0, 0x10000
	v_add_u32_e32 v0, s48, v150
	ds_read_b128 v[138:141], v0
	ds_read_b128 v[142:145], v0 offset:1024
	ds_read_b128 v[146:149], v0 offset:2048
	ds_read_b128 v[152:155], v0 offset:3072
	s_cmp_eq_u32 s47, 12
	s_cselect_b32 s31, s7, s29
	s_cselect_b32 s30, s9, s28
	s_cselect_b32 s29, s19, s35
	s_cselect_b32 s28, s21, s34
	v_lshl_add_u64 v[160:161], s[26:27], 0, v[136:137]
	s_add_i32 m0, s38, 0xc000
	ds_read_b128 v[156:159], v151
	ds_read_b128 v[176:179], v151 offset:1024
	ds_read_b128 v[180:183], v151 offset:2048
	ds_read_b128 v[184:187], v151 offset:3072
	ds_read_b128 v[188:191], v151 offset:4096
	ds_read_b128 v[192:195], v151 offset:5120
	ds_read_b128 v[196:199], v151 offset:6144
	ds_read_b128 v[230:233], v151 offset:7168
	global_load_lds_dwordx4 v[160:161], off
	v_lshl_add_u64 v[160:161], s[26:27], 0, v[134:135]
	s_add_i32 m0, s38, 0xe000
	s_nop 0
	global_load_lds_dwordx4 v[160:161], off
	s_waitcnt lgkmcnt(8)
	s_barrier
	s_waitcnt lgkmcnt(0)
	s_nop 0
	s_waitcnt lgkmcnt(0)
	v_mfma_f32_16x16x32_bf16 v[126:129], v[138:141], v[156:159], v[126:129]
	v_mfma_f32_16x16x32_bf16 v[122:125], v[146:149], v[156:159], v[122:125]
	v_mfma_f32_16x16x32_bf16 v[110:113], v[138:141], v[180:183], v[110:113]
	v_mfma_f32_16x16x32_bf16 v[106:109], v[146:149], v[180:183], v[106:109]
	v_mfma_f32_16x16x32_bf16 v[94:97], v[138:141], v[188:191], v[94:97]
	v_mfma_f32_16x16x32_bf16 v[90:93], v[146:149], v[188:191], v[90:93]
	v_mfma_f32_16x16x32_bf16 v[78:81], v[138:141], v[196:199], v[78:81]
	v_mfma_f32_16x16x32_bf16 v[74:77], v[146:149], v[196:199], v[74:77]
	v_mfma_f32_16x16x32_bf16 v[126:129], v[142:145], v[176:179], v[126:129]
	v_mfma_f32_16x16x32_bf16 v[122:125], v[152:155], v[176:179], v[122:125]
	v_mfma_f32_16x16x32_bf16 v[110:113], v[142:145], v[184:187], v[110:113]
	v_mfma_f32_16x16x32_bf16 v[106:109], v[152:155], v[184:187], v[106:109]
	v_mfma_f32_16x16x32_bf16 v[94:97], v[142:145], v[192:195], v[94:97]
	v_mfma_f32_16x16x32_bf16 v[90:93], v[152:155], v[192:195], v[90:93]
	v_mfma_f32_16x16x32_bf16 v[78:81], v[142:145], v[230:233], v[78:81]
	v_mfma_f32_16x16x32_bf16 v[74:77], v[152:155], v[230:233], v[74:77]
	s_nop 0
	s_barrier
	s_add_i32 s50, 0, 0x14000
	s_add_i32 s48, s48, s37
	v_add_u32_e32 v0, s50, v150
	v_lshl_add_u64 v[160:161], s[28:29], 0, v[130:131]
	s_mov_b32 m0, s48
	ds_read_b128 v[234:237], v0
	ds_read_b128 v[238:241], v0 offset:1024
	ds_read_b128 v[242:245], v0 offset:2048
	ds_read_b128 v[246:249], v0 offset:3072
	global_load_lds_dwordx4 v[160:161], off
	v_lshl_add_u64 v[200:201], s[28:29], 0, v[132:133]
	s_add_i32 m0, s48, 0x2000
	s_nop 0
	global_load_lds_dwordx4 v[200:201], off
	s_barrier
	s_waitcnt lgkmcnt(0)
	s_nop 0
	s_waitcnt lgkmcnt(0)
	v_mfma_f32_16x16x32_bf16 v[118:121], v[234:237], v[156:159], v[118:121]
	v_mfma_f32_16x16x32_bf16 v[114:117], v[242:245], v[156:159], v[114:117]
	v_mfma_f32_16x16x32_bf16 v[102:105], v[234:237], v[180:183], v[102:105]
	v_mfma_f32_16x16x32_bf16 v[98:101], v[242:245], v[180:183], v[98:101]
	v_mfma_f32_16x16x32_bf16 v[86:89], v[234:237], v[188:191], v[86:89]
	v_mfma_f32_16x16x32_bf16 v[82:85], v[242:245], v[188:191], v[82:85]
	v_mfma_f32_16x16x32_bf16 v[70:73], v[234:237], v[196:199], v[70:73]
	v_mfma_f32_16x16x32_bf16 v[66:69], v[242:245], v[196:199], v[66:69]
	v_mfma_f32_16x16x32_bf16 v[118:121], v[238:241], v[176:179], v[118:121]
	v_mfma_f32_16x16x32_bf16 v[114:117], v[246:249], v[176:179], v[114:117]
	v_mfma_f32_16x16x32_bf16 v[102:105], v[238:241], v[184:187], v[102:105]
	v_mfma_f32_16x16x32_bf16 v[98:101], v[246:249], v[184:187], v[98:101]
	v_mfma_f32_16x16x32_bf16 v[86:89], v[238:241], v[192:195], v[86:89]
	v_mfma_f32_16x16x32_bf16 v[82:85], v[246:249], v[192:195], v[82:85]
	v_mfma_f32_16x16x32_bf16 v[70:73], v[238:241], v[230:233], v[70:73]
	v_mfma_f32_16x16x32_bf16 v[66:69], v[246:249], v[230:233], v[66:69]
	s_nop 0
	s_mov_b32 m0, s38
	v_lshl_add_u64 v[250:251], s[30:31], 0, v[130:131]
	s_barrier
	ds_read_b128 v[156:159], v151 offset:16384
	ds_read_b128 v[176:179], v151 offset:17408
	ds_read_b128 v[180:183], v151 offset:18432
	ds_read_b128 v[184:187], v151 offset:19456
	ds_read_b128 v[188:191], v151 offset:20480
	ds_read_b128 v[192:195], v151 offset:21504
	ds_read_b128 v[196:199], v151 offset:22528
	ds_read_b128 v[230:233], v151 offset:23552
	global_load_lds_dwordx4 v[250:251], off
	v_lshl_add_u64 v[252:253], s[30:31], 0, v[132:133]
	s_mov_b32 m0, s39
	s_nop 0
	global_load_lds_dwordx4 v[252:253], off
	s_barrier
	s_waitcnt lgkmcnt(0)
	s_nop 0
	s_waitcnt lgkmcnt(0)
	v_mfma_f32_16x16x32_bf16 v[62:65], v[138:141], v[156:159], v[62:65]
	v_mfma_f32_16x16x32_bf16 v[58:61], v[146:149], v[156:159], v[58:61]
	v_mfma_f32_16x16x32_bf16 v[46:49], v[138:141], v[180:183], v[46:49]
	v_mfma_f32_16x16x32_bf16 v[42:45], v[146:149], v[180:183], v[42:45]
	v_mfma_f32_16x16x32_bf16 v[30:33], v[138:141], v[188:191], v[30:33]
	v_mfma_f32_16x16x32_bf16 v[26:29], v[146:149], v[188:191], v[26:29]
	v_mfma_f32_16x16x32_bf16 v[14:17], v[138:141], v[196:199], v[14:17]
	v_mfma_f32_16x16x32_bf16 v[10:13], v[146:149], v[196:199], v[10:13]
	v_mfma_f32_16x16x32_bf16 v[62:65], v[142:145], v[176:179], v[62:65]
	v_mfma_f32_16x16x32_bf16 v[58:61], v[152:155], v[176:179], v[58:61]
	v_mfma_f32_16x16x32_bf16 v[46:49], v[142:145], v[184:187], v[46:49]
	v_mfma_f32_16x16x32_bf16 v[42:45], v[152:155], v[184:187], v[42:45]
	v_mfma_f32_16x16x32_bf16 v[30:33], v[142:145], v[192:195], v[30:33]
	v_mfma_f32_16x16x32_bf16 v[26:29], v[152:155], v[192:195], v[26:29]
	v_mfma_f32_16x16x32_bf16 v[14:17], v[142:145], v[230:233], v[14:17]
	v_mfma_f32_16x16x32_bf16 v[10:13], v[152:155], v[230:233], v[10:13]
	s_nop 0
	s_barrier
	s_add_u32 s48, s28, 0x40000
	s_addc_u32 s49, s29, 0
	s_add_i32 s50, s50, s37
	v_lshl_add_u64 v[138:139], s[48:49], 0, v[130:131]
	s_mov_b32 m0, s50
	s_nop 0
	global_load_lds_dwordx4 v[138:139], off
	v_lshl_add_u64 v[138:139], s[48:49], 0, v[132:133]
	s_add_i32 m0, s50, 0x2000
	s_nop 0
	global_load_lds_dwordx4 v[138:139], off
	s_waitcnt vmcnt(6)
	s_barrier
	s_nop 0
	v_mfma_f32_16x16x32_bf16 v[54:57], v[234:237], v[156:159], v[54:57]
	v_mfma_f32_16x16x32_bf16 v[50:53], v[242:245], v[156:159], v[50:53]
	v_mfma_f32_16x16x32_bf16 v[38:41], v[234:237], v[180:183], v[38:41]
	v_mfma_f32_16x16x32_bf16 v[34:37], v[242:245], v[180:183], v[34:37]
	v_mfma_f32_16x16x32_bf16 v[22:25], v[234:237], v[188:191], v[22:25]
	v_mfma_f32_16x16x32_bf16 v[18:21], v[242:245], v[188:191], v[18:21]
	v_mfma_f32_16x16x32_bf16 v[6:9], v[234:237], v[196:199], v[6:9]
	v_mfma_f32_16x16x32_bf16 v[2:5], v[242:245], v[196:199], v[2:5]
	v_mfma_f32_16x16x32_bf16 v[54:57], v[238:241], v[176:179], v[54:57]
	v_mfma_f32_16x16x32_bf16 v[50:53], v[246:249], v[176:179], v[50:53]
	v_mfma_f32_16x16x32_bf16 v[38:41], v[238:241], v[184:187], v[38:41]
	v_mfma_f32_16x16x32_bf16 v[34:37], v[246:249], v[184:187], v[34:37]
	v_mfma_f32_16x16x32_bf16 v[22:25], v[238:241], v[192:195], v[22:25]
	v_mfma_f32_16x16x32_bf16 v[18:21], v[246:249], v[192:195], v[18:21]
	v_mfma_f32_16x16x32_bf16 v[6:9], v[238:241], v[230:233], v[6:9]
	v_mfma_f32_16x16x32_bf16 v[2:5], v[246:249], v[230:233], v[2:5]
	s_nop 0
	s_add_i32 s48, 0, 0x18000
	v_add_u32_e32 v0, s48, v150
	s_barrier
	ds_read_b128 v[138:141], v0
	ds_read_b128 v[142:145], v0 offset:1024
	ds_read_b128 v[146:149], v0 offset:2048
	ds_read_b128 v[152:155], v0 offset:3072
	s_add_u32 s30, s30, 0x40000
	s_addc_u32 s31, s31, 0
	s_mov_b32 m0, s40
	v_lshl_add_u64 v[234:235], s[30:31], 0, v[130:131]
	ds_read_b128 v[156:159], v151 offset:32768
	ds_read_b128 v[176:179], v151 offset:33792
	ds_read_b128 v[180:183], v151 offset:34816
	ds_read_b128 v[184:187], v151 offset:35840
	ds_read_b128 v[188:191], v151 offset:36864
	ds_read_b128 v[192:195], v151 offset:37888
	ds_read_b128 v[196:199], v151 offset:38912
	ds_read_b128 v[230:233], v151 offset:39936
	global_load_lds_dwordx4 v[234:235], off
	v_lshl_add_u64 v[234:235], s[30:31], 0, v[132:133]
	s_mov_b32 m0, s41
	s_nop 0
	global_load_lds_dwordx4 v[234:235], off
	s_waitcnt lgkmcnt(8)
	s_barrier
	s_waitcnt lgkmcnt(0)
	s_nop 0
	s_waitcnt lgkmcnt(0)
	v_mfma_f32_16x16x32_bf16 v[126:129], v[138:141], v[156:159], v[126:129]
	v_mfma_f32_16x16x32_bf16 v[122:125], v[146:149], v[156:159], v[122:125]
	v_mfma_f32_16x16x32_bf16 v[110:113], v[138:141], v[180:183], v[110:113]
	v_mfma_f32_16x16x32_bf16 v[106:109], v[146:149], v[180:183], v[106:109]
	v_mfma_f32_16x16x32_bf16 v[94:97], v[138:141], v[188:191], v[94:97]
	v_mfma_f32_16x16x32_bf16 v[90:93], v[146:149], v[188:191], v[90:93]
	v_mfma_f32_16x16x32_bf16 v[78:81], v[138:141], v[196:199], v[78:81]
	v_mfma_f32_16x16x32_bf16 v[74:77], v[146:149], v[196:199], v[74:77]
	v_mfma_f32_16x16x32_bf16 v[126:129], v[142:145], v[176:179], v[126:129]
	v_mfma_f32_16x16x32_bf16 v[122:125], v[152:155], v[176:179], v[122:125]
	v_mfma_f32_16x16x32_bf16 v[110:113], v[142:145], v[184:187], v[110:113]
	v_mfma_f32_16x16x32_bf16 v[106:109], v[152:155], v[184:187], v[106:109]
	v_mfma_f32_16x16x32_bf16 v[94:97], v[142:145], v[192:195], v[94:97]
	v_mfma_f32_16x16x32_bf16 v[90:93], v[152:155], v[192:195], v[90:93]
	v_mfma_f32_16x16x32_bf16 v[78:81], v[142:145], v[230:233], v[78:81]
	v_mfma_f32_16x16x32_bf16 v[74:77], v[152:155], v[230:233], v[74:77]
	s_nop 0
	s_barrier
	s_add_i32 s30, 0, 0x1c000
	s_add_i32 s31, s48, s37
	v_add_u32_e32 v0, s30, v150
	v_lshl_add_u64 v[160:161], v[160:161], 0, s[92:93]
	s_mov_b32 m0, s31
	ds_read_b128 v[234:237], v0
	ds_read_b128 v[238:241], v0 offset:1024
	ds_read_b128 v[242:245], v0 offset:2048
	ds_read_b128 v[246:249], v0 offset:3072
	global_load_lds_dwordx4 v[160:161], off
	v_lshl_add_u64 v[160:161], v[200:201], 0, s[92:93]
	s_add_i32 m0, s31, 0x2000
	s_nop 0
	global_load_lds_dwordx4 v[160:161], off
	s_barrier
	s_waitcnt lgkmcnt(0)
	s_nop 0
	s_waitcnt lgkmcnt(0)
	v_mfma_f32_16x16x32_bf16 v[118:121], v[234:237], v[156:159], v[118:121]
	v_mfma_f32_16x16x32_bf16 v[114:117], v[242:245], v[156:159], v[114:117]
	v_mfma_f32_16x16x32_bf16 v[102:105], v[234:237], v[180:183], v[102:105]
	v_mfma_f32_16x16x32_bf16 v[98:101], v[242:245], v[180:183], v[98:101]
	v_mfma_f32_16x16x32_bf16 v[86:89], v[234:237], v[188:191], v[86:89]
	v_mfma_f32_16x16x32_bf16 v[82:85], v[242:245], v[188:191], v[82:85]
	v_mfma_f32_16x16x32_bf16 v[70:73], v[234:237], v[196:199], v[70:73]
	v_mfma_f32_16x16x32_bf16 v[66:69], v[242:245], v[196:199], v[66:69]
	v_mfma_f32_16x16x32_bf16 v[118:121], v[238:241], v[176:179], v[118:121]
	v_mfma_f32_16x16x32_bf16 v[114:117], v[246:249], v[176:179], v[114:117]
	v_mfma_f32_16x16x32_bf16 v[102:105], v[238:241], v[184:187], v[102:105]
	v_mfma_f32_16x16x32_bf16 v[98:101], v[246:249], v[184:187], v[98:101]
	v_mfma_f32_16x16x32_bf16 v[86:89], v[238:241], v[192:195], v[86:89]
	v_mfma_f32_16x16x32_bf16 v[82:85], v[246:249], v[192:195], v[82:85]
	v_mfma_f32_16x16x32_bf16 v[70:73], v[238:241], v[230:233], v[70:73]
	v_mfma_f32_16x16x32_bf16 v[66:69], v[246:249], v[230:233], v[66:69]
	s_nop 0
	s_mov_b32 m0, s42
	v_lshl_add_u64 v[160:161], v[250:251], 0, s[92:93]
	s_barrier
	ds_read_b128 v[156:159], v151 offset:49152
	ds_read_b128 v[176:179], v151 offset:50176
	ds_read_b128 v[180:183], v151 offset:51200
	ds_read_b128 v[184:187], v151 offset:52224
	ds_read_b128 v[188:191], v151 offset:53248
	ds_read_b128 v[192:195], v151 offset:54272
	ds_read_b128 v[196:199], v151 offset:55296
	ds_read_b128 v[230:233], v151 offset:56320
	global_load_lds_dwordx4 v[160:161], off
	v_lshl_add_u64 v[160:161], v[252:253], 0, s[92:93]
	s_mov_b32 m0, s43
	s_nop 0
	global_load_lds_dwordx4 v[160:161], off
	s_barrier
	s_waitcnt lgkmcnt(0)
	s_nop 0
	s_waitcnt lgkmcnt(0)
	v_mfma_f32_16x16x32_bf16 v[62:65], v[138:141], v[156:159], v[62:65]
	v_mfma_f32_16x16x32_bf16 v[58:61], v[146:149], v[156:159], v[58:61]
	v_mfma_f32_16x16x32_bf16 v[46:49], v[138:141], v[180:183], v[46:49]
	v_mfma_f32_16x16x32_bf16 v[42:45], v[146:149], v[180:183], v[42:45]
	v_mfma_f32_16x16x32_bf16 v[30:33], v[138:141], v[188:191], v[30:33]
	v_mfma_f32_16x16x32_bf16 v[26:29], v[146:149], v[188:191], v[26:29]
	v_mfma_f32_16x16x32_bf16 v[14:17], v[138:141], v[196:199], v[14:17]
	v_mfma_f32_16x16x32_bf16 v[10:13], v[146:149], v[196:199], v[10:13]
	v_mfma_f32_16x16x32_bf16 v[62:65], v[142:145], v[176:179], v[62:65]
	v_mfma_f32_16x16x32_bf16 v[58:61], v[152:155], v[176:179], v[58:61]
	v_mfma_f32_16x16x32_bf16 v[46:49], v[142:145], v[184:187], v[46:49]
	v_mfma_f32_16x16x32_bf16 v[42:45], v[152:155], v[184:187], v[42:45]
	v_mfma_f32_16x16x32_bf16 v[30:33], v[142:145], v[192:195], v[30:33]
	v_mfma_f32_16x16x32_bf16 v[26:29], v[152:155], v[192:195], v[26:29]
	v_mfma_f32_16x16x32_bf16 v[14:17], v[142:145], v[230:233], v[14:17]
	v_mfma_f32_16x16x32_bf16 v[10:13], v[152:155], v[230:233], v[10:13]
	s_nop 0
	s_barrier
	s_add_u32 s28, s28, 0x40080
	s_addc_u32 s29, s29, 0
	s_add_i32 s30, s30, s37
	v_lshl_add_u64 v[138:139], s[28:29], 0, v[130:131]
	s_mov_b32 m0, s30
	s_nop 0
	global_load_lds_dwordx4 v[138:139], off
	v_lshl_add_u64 v[138:139], s[28:29], 0, v[132:133]
	s_add_i32 m0, s30, 0x2000
	s_nop 0
	global_load_lds_dwordx4 v[138:139], off
	s_waitcnt vmcnt(6)
	s_barrier
	s_nop 0
	v_mfma_f32_16x16x32_bf16 v[54:57], v[234:237], v[156:159], v[54:57]
	v_mfma_f32_16x16x32_bf16 v[50:53], v[242:245], v[156:159], v[50:53]
	v_mfma_f32_16x16x32_bf16 v[38:41], v[234:237], v[180:183], v[38:41]
	v_mfma_f32_16x16x32_bf16 v[34:37], v[242:245], v[180:183], v[34:37]
	v_mfma_f32_16x16x32_bf16 v[22:25], v[234:237], v[188:191], v[22:25]
	v_mfma_f32_16x16x32_bf16 v[18:21], v[242:245], v[188:191], v[18:21]
	v_mfma_f32_16x16x32_bf16 v[6:9], v[234:237], v[196:199], v[6:9]
	v_mfma_f32_16x16x32_bf16 v[2:5], v[242:245], v[196:199], v[2:5]
	v_mfma_f32_16x16x32_bf16 v[54:57], v[238:241], v[176:179], v[54:57]
	v_mfma_f32_16x16x32_bf16 v[50:53], v[246:249], v[176:179], v[50:53]
	v_mfma_f32_16x16x32_bf16 v[38:41], v[238:241], v[184:187], v[38:41]
	v_mfma_f32_16x16x32_bf16 v[34:37], v[246:249], v[184:187], v[34:37]
	v_mfma_f32_16x16x32_bf16 v[22:25], v[238:241], v[192:195], v[22:25]
	v_mfma_f32_16x16x32_bf16 v[18:21], v[246:249], v[192:195], v[18:21]
	v_mfma_f32_16x16x32_bf16 v[6:9], v[238:241], v[230:233], v[6:9]
	v_mfma_f32_16x16x32_bf16 v[2:5], v[246:249], v[230:233], v[2:5]
	s_nop 0
	s_add_i32 s47, s47, 2
	s_add_u32 s34, s34, 0x100
	s_addc_u32 s35, s35, 0
	s_add_u32 s26, s26, 0x100
	s_addc_u32 s27, s27, 0
	s_cmp_gt_u32 s47, 13
	s_barrier
	s_cbranch_scc0 .LBB0_918
	s_setprio 0
	v_mov_b32_e32 v0, v163
	s_movk_i32 s7, 0xffc0
	v_and_b32_e32 v138, 0xc0, v0
	v_and_b32_e32 v139, 15, v0
	v_ashrrev_i32_e32 v140, 2, v0
	v_lshl_or_b32 v152, s8, 8, v138
	v_lshrrev_b32_e32 v0, 1, v0
	v_and_or_b32 v138, v0, 24, v152
	v_add_u32_e32 v178, 0xfffff880, v138
	v_cmp_gt_u32_e32 vcc, 16, v178
	s_and_saveexec_b64 s[98:99], vcc
	s_cbranch_execz .Lip_nobias
	v_mov_b32_e32 v179, 0
	v_lshlrev_b64 v[178:179], 2, v[178:179]
	v_lshl_add_u64 v[186:187], s[16:17], 0, v[178:179]
	global_load_dwordx4 v[178:181], v[186:187], off
	global_load_dwordx4 v[182:185], v[186:187], off offset:16
	s_waitcnt vmcnt(0)

.LBB0_1246:
	s_add_u32 s41, s16, 0x100
	v_mov_b32_e32 v2, 0
	s_addc_u32 s42, s17, 0
	s_mov_b32 s43, -2
	v_mov_b32_e32 v3, v2
	v_mov_b32_e32 v4, v2
	v_mov_b32_e32 v5, v2
	v_mov_b32_e32 v6, v2
	v_mov_b32_e32 v7, v2
	v_mov_b32_e32 v8, v2
	v_mov_b32_e32 v9, v2
	v_mov_b32_e32 v10, v2
	v_mov_b32_e32 v11, v2
	v_mov_b32_e32 v12, v2
	v_mov_b32_e32 v13, v2
	v_mov_b32_e32 v14, v2
	v_mov_b32_e32 v15, v2
	v_mov_b32_e32 v16, v2
	v_mov_b32_e32 v17, v2
	v_mov_b32_e32 v34, v2
	v_mov_b32_e32 v35, v2
	v_mov_b32_e32 v36, v2
	v_mov_b32_e32 v37, v2
	v_mov_b32_e32 v38, v2
	v_mov_b32_e32 v39, v2
	v_mov_b32_e32 v40, v2
	v_mov_b32_e32 v41, v2
	v_mov_b32_e32 v46, v2
	v_mov_b32_e32 v47, v2
	v_mov_b32_e32 v48, v2
	v_mov_b32_e32 v49, v2
	v_mov_b32_e32 v50, v2
	v_mov_b32_e32 v51, v2
	v_mov_b32_e32 v52, v2
	v_mov_b32_e32 v53, v2
	v_mov_b32_e32 v18, v2
	v_mov_b32_e32 v19, v2
	v_mov_b32_e32 v20, v2
	v_mov_b32_e32 v21, v2
	v_mov_b32_e32 v22, v2
	v_mov_b32_e32 v23, v2
	v_mov_b32_e32 v24, v2
	v_mov_b32_e32 v25, v2
	v_mov_b32_e32 v26, v2
	v_mov_b32_e32 v27, v2
	v_mov_b32_e32 v28, v2
	v_mov_b32_e32 v29, v2
	v_mov_b32_e32 v30, v2
	v_mov_b32_e32 v31, v2
	v_mov_b32_e32 v32, v2
	v_mov_b32_e32 v33, v2
	v_mov_b32_e32 v42, v2
	v_mov_b32_e32 v43, v2
	v_mov_b32_e32 v44, v2
	v_mov_b32_e32 v45, v2
	v_mov_b32_e32 v54, v2
	v_mov_b32_e32 v55, v2
	v_mov_b32_e32 v56, v2
	v_mov_b32_e32 v57, v2
	v_mov_b32_e32 v58, v2
	v_mov_b32_e32 v59, v2
	v_mov_b32_e32 v60, v2
	v_mov_b32_e32 v61, v2
	v_mov_b32_e32 v62, v2
	v_mov_b32_e32 v63, v2
	v_mov_b32_e32 v64, v2
	v_mov_b32_e32 v65, v2
	v_mov_b32_e32 v66, v2
	v_mov_b32_e32 v67, v2
	v_mov_b32_e32 v68, v2
	v_mov_b32_e32 v69, v2
	v_mov_b32_e32 v70, v2
	v_mov_b32_e32 v71, v2
	v_mov_b32_e32 v72, v2
	v_mov_b32_e32 v73, v2
	v_mov_b32_e32 v78, v2
	v_mov_b32_e32 v79, v2
	v_mov_b32_e32 v80, v2
	v_mov_b32_e32 v81, v2
	v_mov_b32_e32 v82, v2
	v_mov_b32_e32 v83, v2
	v_mov_b32_e32 v84, v2
	v_mov_b32_e32 v85, v2
	v_mov_b32_e32 v114, v2
	v_mov_b32_e32 v115, v2
	v_mov_b32_e32 v116, v2
	v_mov_b32_e32 v117, v2
	v_mov_b32_e32 v118, v2
	v_mov_b32_e32 v119, v2
	v_mov_b32_e32 v120, v2
	v_mov_b32_e32 v121, v2
	v_mov_b32_e32 v126, v2
	v_mov_b32_e32 v127, v2
	v_mov_b32_e32 v128, v2
	v_mov_b32_e32 v129, v2
	v_mov_b32_e32 v130, v2
	v_mov_b32_e32 v131, v2
	v_mov_b32_e32 v132, v2
	v_mov_b32_e32 v133, v2
	v_mov_b32_e32 v74, v2
	v_mov_b32_e32 v75, v2
	v_mov_b32_e32 v76, v2
	v_mov_b32_e32 v77, v2
	v_mov_b32_e32 v86, v2
	v_mov_b32_e32 v87, v2
	v_mov_b32_e32 v88, v2
	v_mov_b32_e32 v89, v2
	v_mov_b32_e32 v90, v2
	v_mov_b32_e32 v91, v2
	v_mov_b32_e32 v92, v2
	v_mov_b32_e32 v93, v2
	v_mov_b32_e32 v94, v2
	v_mov_b32_e32 v95, v2
	v_mov_b32_e32 v96, v2
	v_mov_b32_e32 v97, v2
	v_mov_b32_e32 v122, v2
	v_mov_b32_e32 v123, v2
	v_mov_b32_e32 v124, v2
	v_mov_b32_e32 v125, v2
	v_mov_b32_e32 v134, v2
	v_mov_b32_e32 v135, v2
	v_mov_b32_e32 v136, v2
	v_mov_b32_e32 v137, v2
	v_mov_b32_e32 v138, v2
	v_mov_b32_e32 v139, v2
	v_mov_b32_e32 v140, v2
	v_mov_b32_e32 v141, v2
	v_mov_b32_e32 v142, v2
	v_mov_b32_e32 v143, v2
	v_mov_b32_e32 v144, v2
	v_mov_b32_e32 v145, v2
	v_readlane_b32 s99, v255, 41
	s_cmp_eq_u32 s36, 2
	s_cselect_b32 s99, s99, 0
	v_cmp_lt_u32_e32 vcc, 0xff, v163
	s_nop 1
	s_cbranch_vccz .Lsprio_skip5
	s_setprio 1
.Lsprio_skip5:
.LBB0_1247:
	s_add_u32 s16, s14, 0x100
	s_addc_u32 s17, s15, 0
	s_add_i32 s44, 0, 0x10000
	v_add_u32_e32 v110, s44, v160
	ds_read_b128 v[98:101], v110
	ds_read_b128 v[102:105], v110 offset:1024
	ds_read_b128 v[106:109], v110 offset:2048
	ds_read_b128 v[110:113], v110 offset:3072
	s_cmp_eq_u32 s43, 40
	s_cselect_b32 s21, s7, s17
	s_cselect_b32 s20, s6, s16
	s_cselect_b32 s19, s9, s42
	s_cselect_b32 s18, s8, s41
	v_lshl_add_u64 v[172:173], s[14:15], 0, v[150:151]
	s_add_i32 m0, s25, 0xc000
	ds_read_b128 v[152:155], v161
	ds_read_b128 v[156:159], v161 offset:1024
	ds_read_b128 v[176:179], v161 offset:2048
	ds_read_b128 v[180:183], v161 offset:3072
	ds_read_b128 v[184:187], v161 offset:4096
	ds_read_b128 v[188:191], v161 offset:5120
	ds_read_b128 v[192:195], v161 offset:6144
	ds_read_b128 v[196:199], v161 offset:7168
	s_cmp_lg_u32 s99, 0
	s_cbranch_scc1 .Lhsd0_0
	global_load_lds_dwordx4 v[172:173], off

.Lhsd0_1:
	s_waitcnt lgkmcnt(8)
	s_barrier
	s_waitcnt lgkmcnt(0)
	s_nop 0
	s_waitcnt lgkmcnt(0)
	v_mfma_f32_16x16x32_bf16 v[142:145], v[98:101], v[152:155], v[142:145]
	v_mfma_f32_16x16x32_bf16 v[138:141], v[106:109], v[152:155], v[138:141]
	v_mfma_f32_16x16x32_bf16 v[134:137], v[98:101], v[176:179], v[134:137]
	v_mfma_f32_16x16x32_bf16 v[122:125], v[106:109], v[176:179], v[122:125]
	v_mfma_f32_16x16x32_bf16 v[94:97], v[98:101], v[184:187], v[94:97]
	v_mfma_f32_16x16x32_bf16 v[90:93], v[106:109], v[184:187], v[90:93]
	v_mfma_f32_16x16x32_bf16 v[86:89], v[98:101], v[192:195], v[86:89]
	v_mfma_f32_16x16x32_bf16 v[74:77], v[106:109], v[192:195], v[74:77]
	v_mfma_f32_16x16x32_bf16 v[142:145], v[102:105], v[156:159], v[142:145]
	v_mfma_f32_16x16x32_bf16 v[138:141], v[110:113], v[156:159], v[138:141]
	v_mfma_f32_16x16x32_bf16 v[134:137], v[102:105], v[180:183], v[134:137]
	v_mfma_f32_16x16x32_bf16 v[122:125], v[110:113], v[180:183], v[122:125]
	v_mfma_f32_16x16x32_bf16 v[94:97], v[102:105], v[188:191], v[94:97]
	v_mfma_f32_16x16x32_bf16 v[90:93], v[110:113], v[188:191], v[90:93]
	v_mfma_f32_16x16x32_bf16 v[86:89], v[102:105], v[196:199], v[86:89]
	v_mfma_f32_16x16x32_bf16 v[74:77], v[110:113], v[196:199], v[74:77]
	s_nop 0
	s_barrier
	s_add_i32 s45, 0, 0x14000
	s_add_i32 s14, s44, s23
	v_add_u32_e32 v169, s45, v160
	v_lshl_add_u64 v[172:173], s[18:19], 0, v[0:1]
	s_mov_b32 m0, s14
	ds_read_b128 v[230:233], v169
	ds_read_b128 v[234:237], v169 offset:1024
	ds_read_b128 v[238:241], v169 offset:2048
	ds_read_b128 v[242:245], v169 offset:3072
	global_load_lds_dwordx4 v[172:173], off
	v_lshl_add_u64 v[174:175], s[18:19], 0, v[146:147]
	s_add_i32 m0, s14, 0x2000
	s_nop 0
	global_load_lds_dwordx4 v[174:175], off
	s_barrier
	s_waitcnt lgkmcnt(0)
	s_nop 0
	s_waitcnt lgkmcnt(0)
	v_mfma_f32_16x16x32_bf16 v[130:133], v[230:233], v[152:155], v[130:133]
	v_mfma_f32_16x16x32_bf16 v[126:129], v[238:241], v[152:155], v[126:129]
	v_mfma_f32_16x16x32_bf16 v[118:121], v[230:233], v[176:179], v[118:121]
	v_mfma_f32_16x16x32_bf16 v[114:117], v[238:241], v[176:179], v[114:117]
	v_mfma_f32_16x16x32_bf16 v[82:85], v[230:233], v[184:187], v[82:85]
	v_mfma_f32_16x16x32_bf16 v[78:81], v[238:241], v[184:187], v[78:81]
	v_mfma_f32_16x16x32_bf16 v[70:73], v[230:233], v[192:195], v[70:73]
	v_mfma_f32_16x16x32_bf16 v[66:69], v[238:241], v[192:195], v[66:69]
	v_mfma_f32_16x16x32_bf16 v[130:133], v[234:237], v[156:159], v[130:133]
	v_mfma_f32_16x16x32_bf16 v[126:129], v[242:245], v[156:159], v[126:129]
	v_mfma_f32_16x16x32_bf16 v[118:121], v[234:237], v[180:183], v[118:121]
	v_mfma_f32_16x16x32_bf16 v[114:117], v[242:245], v[180:183], v[114:117]
	v_mfma_f32_16x16x32_bf16 v[82:85], v[234:237], v[188:191], v[82:85]
	v_mfma_f32_16x16x32_bf16 v[78:81], v[242:245], v[188:191], v[78:81]
	v_mfma_f32_16x16x32_bf16 v[70:73], v[234:237], v[196:199], v[70:73]
	v_mfma_f32_16x16x32_bf16 v[66:69], v[242:245], v[196:199], v[66:69]
	s_nop 0
	s_mov_b32 m0, s25
	v_lshl_add_u64 v[200:201], s[20:21], 0, v[0:1]
	s_barrier
	ds_read_b128 v[152:155], v161 offset:16384
	ds_read_b128 v[156:159], v161 offset:17408
	ds_read_b128 v[176:179], v161 offset:18432
	ds_read_b128 v[180:183], v161 offset:19456
	ds_read_b128 v[184:187], v161 offset:20480
	ds_read_b128 v[188:191], v161 offset:21504
	ds_read_b128 v[192:195], v161 offset:22528
	ds_read_b128 v[196:199], v161 offset:23552
	global_load_lds_dwordx4 v[200:201], off
	v_lshl_add_u64 v[210:211], s[20:21], 0, v[146:147]
	s_mov_b32 m0, s26
	s_nop 0
	global_load_lds_dwordx4 v[210:211], off
	s_barrier
	s_waitcnt lgkmcnt(0)
	s_nop 0
	s_waitcnt lgkmcnt(0)
	s_cmp_lg_u32 s99, 0
	s_cbranch_scc1 .Lfd_skip3
	v_mfma_f32_16x16x32_bf16 v[62:65], v[98:101], v[152:155], v[62:65]
	v_mfma_f32_16x16x32_bf16 v[58:61], v[106:109], v[152:155], v[58:61]
	v_mfma_f32_16x16x32_bf16 v[54:57], v[98:101], v[176:179], v[54:57]
	v_mfma_f32_16x16x32_bf16 v[42:45], v[106:109], v[176:179], v[42:45]
	v_mfma_f32_16x16x32_bf16 v[30:33], v[98:101], v[184:187], v[30:33]
	v_mfma_f32_16x16x32_bf16 v[26:29], v[106:109], v[184:187], v[26:29]
	v_mfma_f32_16x16x32_bf16 v[22:25], v[98:101], v[192:195], v[22:25]
	v_mfma_f32_16x16x32_bf16 v[18:21], v[106:109], v[192:195], v[18:21]
	v_mfma_f32_16x16x32_bf16 v[62:65], v[102:105], v[156:159], v[62:65]
	v_mfma_f32_16x16x32_bf16 v[58:61], v[110:113], v[156:159], v[58:61]
	v_mfma_f32_16x16x32_bf16 v[54:57], v[102:105], v[180:183], v[54:57]
	v_mfma_f32_16x16x32_bf16 v[42:45], v[110:113], v[180:183], v[42:45]
	v_mfma_f32_16x16x32_bf16 v[30:33], v[102:105], v[188:191], v[30:33]
	v_mfma_f32_16x16x32_bf16 v[26:29], v[110:113], v[188:191], v[26:29]
	v_mfma_f32_16x16x32_bf16 v[22:25], v[102:105], v[196:199], v[22:25]
	v_mfma_f32_16x16x32_bf16 v[18:21], v[110:113], v[196:199], v[18:21]
.Lfd_skip3:
	s_nop 0
	s_barrier
	s_add_u32 s14, s18, 0xb0000
	s_addc_u32 s15, s19, 0
	s_add_i32 s44, s45, s23
	v_lshl_add_u64 v[98:99], s[14:15], 0, v[0:1]
	s_mov_b32 m0, s44
	s_nop 0
	global_load_lds_dwordx4 v[98:99], off
	v_lshl_add_u64 v[98:99], s[14:15], 0, v[146:147]
	s_add_i32 m0, s44, 0x2000
	s_nop 0
	global_load_lds_dwordx4 v[98:99], off
	s_waitcnt vmcnt(6)
	s_barrier
	s_nop 0
	s_cmp_lg_u32 s99, 0
	s_cbranch_scc1 .Lfd_skip4
	v_mfma_f32_16x16x32_bf16 v[50:53], v[230:233], v[152:155], v[50:53]
	v_mfma_f32_16x16x32_bf16 v[46:49], v[238:241], v[152:155], v[46:49]
	v_mfma_f32_16x16x32_bf16 v[38:41], v[230:233], v[176:179], v[38:41]
	v_mfma_f32_16x16x32_bf16 v[34:37], v[238:241], v[176:179], v[34:37]
	v_mfma_f32_16x16x32_bf16 v[14:17], v[230:233], v[184:187], v[14:17]
	v_mfma_f32_16x16x32_bf16 v[10:13], v[238:241], v[184:187], v[10:13]
	v_mfma_f32_16x16x32_bf16 v[6:9], v[230:233], v[192:195], v[6:9]
	v_mfma_f32_16x16x32_bf16 v[2:5], v[238:241], v[192:195], v[2:5]
	v_mfma_f32_16x16x32_bf16 v[50:53], v[234:237], v[156:159], v[50:53]
	v_mfma_f32_16x16x32_bf16 v[46:49], v[242:245], v[156:159], v[46:49]
	v_mfma_f32_16x16x32_bf16 v[38:41], v[234:237], v[180:183], v[38:41]
	v_mfma_f32_16x16x32_bf16 v[34:37], v[242:245], v[180:183], v[34:37]
	v_mfma_f32_16x16x32_bf16 v[14:17], v[234:237], v[188:191], v[14:17]
	v_mfma_f32_16x16x32_bf16 v[10:13], v[242:245], v[188:191], v[10:13]
	v_mfma_f32_16x16x32_bf16 v[6:9], v[234:237], v[196:199], v[6:9]
	v_mfma_f32_16x16x32_bf16 v[2:5], v[242:245], v[196:199], v[2:5]
.Lfd_skip4:
	s_nop 0
	s_add_i32 s44, 0, 0x18000
	v_add_u32_e32 v110, s44, v160
	s_barrier
	ds_read_b128 v[98:101], v110
	ds_read_b128 v[102:105], v110 offset:1024
	ds_read_b128 v[106:109], v110 offset:2048
	ds_read_b128 v[110:113], v110 offset:3072
	s_add_u32 s14, s20, 0xb0000
	s_addc_u32 s15, s21, 0
	s_mov_b32 m0, s27
	v_lshl_add_u64 v[230:231], s[14:15], 0, v[0:1]
	ds_read_b128 v[152:155], v161 offset:32768
	ds_read_b128 v[156:159], v161 offset:33792
	ds_read_b128 v[176:179], v161 offset:34816
	ds_read_b128 v[180:183], v161 offset:35840
	ds_read_b128 v[184:187], v161 offset:36864
	ds_read_b128 v[188:191], v161 offset:37888
	ds_read_b128 v[192:195], v161 offset:38912
	ds_read_b128 v[196:199], v161 offset:39936
	s_cmp_lg_u32 s99, 0
	s_cbranch_scc1 .Lhsd0_2
	global_load_lds_dwordx4 v[230:231], off

.Lhsd0_3:
	s_waitcnt lgkmcnt(8)
	s_barrier
	s_waitcnt lgkmcnt(0)
	s_nop 0
	s_waitcnt lgkmcnt(0)
	v_mfma_f32_16x16x32_bf16 v[142:145], v[98:101], v[152:155], v[142:145]
	v_mfma_f32_16x16x32_bf16 v[138:141], v[106:109], v[152:155], v[138:141]
	v_mfma_f32_16x16x32_bf16 v[134:137], v[98:101], v[176:179], v[134:137]
	v_mfma_f32_16x16x32_bf16 v[122:125], v[106:109], v[176:179], v[122:125]
	v_mfma_f32_16x16x32_bf16 v[94:97], v[98:101], v[184:187], v[94:97]
	v_mfma_f32_16x16x32_bf16 v[90:93], v[106:109], v[184:187], v[90:93]
	v_mfma_f32_16x16x32_bf16 v[86:89], v[98:101], v[192:195], v[86:89]
	v_mfma_f32_16x16x32_bf16 v[74:77], v[106:109], v[192:195], v[74:77]
	v_mfma_f32_16x16x32_bf16 v[142:145], v[102:105], v[156:159], v[142:145]
	v_mfma_f32_16x16x32_bf16 v[138:141], v[110:113], v[156:159], v[138:141]
	v_mfma_f32_16x16x32_bf16 v[134:137], v[102:105], v[180:183], v[134:137]
	v_mfma_f32_16x16x32_bf16 v[122:125], v[110:113], v[180:183], v[122:125]
	v_mfma_f32_16x16x32_bf16 v[94:97], v[102:105], v[188:191], v[94:97]
	v_mfma_f32_16x16x32_bf16 v[90:93], v[110:113], v[188:191], v[90:93]
	v_mfma_f32_16x16x32_bf16 v[86:89], v[102:105], v[196:199], v[86:89]
	v_mfma_f32_16x16x32_bf16 v[74:77], v[110:113], v[196:199], v[74:77]
	s_nop 0
	s_barrier
	s_add_i32 s20, 0, 0x1c000
	s_add_i32 s14, s44, s23
	v_add_u32_e32 v169, s20, v160
	v_lshl_add_u64 v[172:173], v[172:173], 0, s[92:93]
	s_mov_b32 m0, s14
	ds_read_b128 v[230:233], v169
	ds_read_b128 v[234:237], v169 offset:1024
	ds_read_b128 v[238:241], v169 offset:2048
	ds_read_b128 v[242:245], v169 offset:3072
	global_load_lds_dwordx4 v[172:173], off
	v_lshl_add_u64 v[172:173], v[174:175], 0, s[92:93]
	s_add_i32 m0, s14, 0x2000
	s_nop 0
	global_load_lds_dwordx4 v[172:173], off
	s_barrier
	s_waitcnt lgkmcnt(0)
	s_nop 0
	s_waitcnt lgkmcnt(0)
	v_mfma_f32_16x16x32_bf16 v[130:133], v[230:233], v[152:155], v[130:133]
	v_mfma_f32_16x16x32_bf16 v[126:129], v[238:241], v[152:155], v[126:129]
	v_mfma_f32_16x16x32_bf16 v[118:121], v[230:233], v[176:179], v[118:121]
	v_mfma_f32_16x16x32_bf16 v[114:117], v[238:241], v[176:179], v[114:117]
	v_mfma_f32_16x16x32_bf16 v[82:85], v[230:233], v[184:187], v[82:85]
	v_mfma_f32_16x16x32_bf16 v[78:81], v[238:241], v[184:187], v[78:81]
	v_mfma_f32_16x16x32_bf16 v[70:73], v[230:233], v[192:195], v[70:73]
	v_mfma_f32_16x16x32_bf16 v[66:69], v[238:241], v[192:195], v[66:69]
	v_mfma_f32_16x16x32_bf16 v[130:133], v[234:237], v[156:159], v[130:133]
	v_mfma_f32_16x16x32_bf16 v[126:129], v[242:245], v[156:159], v[126:129]
	v_mfma_f32_16x16x32_bf16 v[118:121], v[234:237], v[180:183], v[118:121]
	v_mfma_f32_16x16x32_bf16 v[114:117], v[242:245], v[180:183], v[114:117]
	v_mfma_f32_16x16x32_bf16 v[82:85], v[234:237], v[188:191], v[82:85]
	v_mfma_f32_16x16x32_bf16 v[78:81], v[242:245], v[188:191], v[78:81]
	v_mfma_f32_16x16x32_bf16 v[70:73], v[234:237], v[196:199], v[70:73]
	v_mfma_f32_16x16x32_bf16 v[66:69], v[242:245], v[196:199], v[66:69]
	s_nop 0
	s_mov_b32 m0, s31
	v_lshl_add_u64 v[172:173], v[200:201], 0, s[92:93]
	s_barrier
	ds_read_b128 v[152:155], v161 offset:49152
	ds_read_b128 v[156:159], v161 offset:50176
	ds_read_b128 v[176:179], v161 offset:51200
	ds_read_b128 v[180:183], v161 offset:52224
	ds_read_b128 v[184:187], v161 offset:53248
	ds_read_b128 v[188:191], v161 offset:54272
	ds_read_b128 v[192:195], v161 offset:55296
	ds_read_b128 v[196:199], v161 offset:56320
	global_load_lds_dwordx4 v[172:173], off
	v_lshl_add_u64 v[172:173], v[210:211], 0, s[92:93]
	s_mov_b32 m0, s34
	s_nop 0
	global_load_lds_dwordx4 v[172:173], off
	s_barrier
	s_waitcnt lgkmcnt(0)
	s_nop 0
	s_waitcnt lgkmcnt(0)
	s_cmp_lg_u32 s99, 0
	s_cbranch_scc1 .Lfd_skip7
	v_mfma_f32_16x16x32_bf16 v[62:65], v[98:101], v[152:155], v[62:65]
	v_mfma_f32_16x16x32_bf16 v[58:61], v[106:109], v[152:155], v[58:61]
	v_mfma_f32_16x16x32_bf16 v[54:57], v[98:101], v[176:179], v[54:57]
	v_mfma_f32_16x16x32_bf16 v[42:45], v[106:109], v[176:179], v[42:45]
	v_mfma_f32_16x16x32_bf16 v[30:33], v[98:101], v[184:187], v[30:33]
	v_mfma_f32_16x16x32_bf16 v[26:29], v[106:109], v[184:187], v[26:29]
	v_mfma_f32_16x16x32_bf16 v[22:25], v[98:101], v[192:195], v[22:25]
	v_mfma_f32_16x16x32_bf16 v[18:21], v[106:109], v[192:195], v[18:21]
	v_mfma_f32_16x16x32_bf16 v[62:65], v[102:105], v[156:159], v[62:65]
	v_mfma_f32_16x16x32_bf16 v[58:61], v[110:113], v[156:159], v[58:61]
	v_mfma_f32_16x16x32_bf16 v[54:57], v[102:105], v[180:183], v[54:57]
	v_mfma_f32_16x16x32_bf16 v[42:45], v[110:113], v[180:183], v[42:45]
	v_mfma_f32_16x16x32_bf16 v[30:33], v[102:105], v[188:191], v[30:33]
	v_mfma_f32_16x16x32_bf16 v[26:29], v[110:113], v[188:191], v[26:29]
	v_mfma_f32_16x16x32_bf16 v[22:25], v[102:105], v[196:199], v[22:25]
	v_mfma_f32_16x16x32_bf16 v[18:21], v[110:113], v[196:199], v[18:21]
.Lfd_skip7:
	s_nop 0
	s_barrier
	s_add_u32 s14, s18, 0xb0080
	s_addc_u32 s15, s19, 0
	s_add_i32 s18, s20, s23
	v_lshl_add_u64 v[98:99], s[14:15], 0, v[0:1]
	s_mov_b32 m0, s18
	s_nop 0
	global_load_lds_dwordx4 v[98:99], off
	v_lshl_add_u64 v[98:99], s[14:15], 0, v[146:147]
	s_add_i32 m0, s18, 0x2000
	s_nop 0
	global_load_lds_dwordx4 v[98:99], off
	s_waitcnt vmcnt(6)
	s_barrier
	s_nop 0
	s_cmp_lg_u32 s99, 0
	s_cbranch_scc1 .Lfd_skip8
	v_mfma_f32_16x16x32_bf16 v[50:53], v[230:233], v[152:155], v[50:53]
	v_mfma_f32_16x16x32_bf16 v[46:49], v[238:241], v[152:155], v[46:49]
	v_mfma_f32_16x16x32_bf16 v[38:41], v[230:233], v[176:179], v[38:41]
	v_mfma_f32_16x16x32_bf16 v[34:37], v[238:241], v[176:179], v[34:37]
	v_mfma_f32_16x16x32_bf16 v[14:17], v[230:233], v[184:187], v[14:17]
	v_mfma_f32_16x16x32_bf16 v[10:13], v[238:241], v[184:187], v[10:13]
	v_mfma_f32_16x16x32_bf16 v[6:9], v[230:233], v[192:195], v[6:9]
	v_mfma_f32_16x16x32_bf16 v[2:5], v[238:241], v[192:195], v[2:5]
	v_mfma_f32_16x16x32_bf16 v[50:53], v[234:237], v[156:159], v[50:53]
	v_mfma_f32_16x16x32_bf16 v[46:49], v[242:245], v[156:159], v[46:49]
	v_mfma_f32_16x16x32_bf16 v[38:41], v[234:237], v[180:183], v[38:41]
	v_mfma_f32_16x16x32_bf16 v[34:37], v[242:245], v[180:183], v[34:37]
	v_mfma_f32_16x16x32_bf16 v[14:17], v[234:237], v[188:191], v[14:17]
	v_mfma_f32_16x16x32_bf16 v[10:13], v[242:245], v[188:191], v[10:13]
	v_mfma_f32_16x16x32_bf16 v[6:9], v[234:237], v[196:199], v[6:9]
	v_mfma_f32_16x16x32_bf16 v[2:5], v[242:245], v[196:199], v[2:5]
.Lfd_skip8:
	s_nop 0
	s_add_i32 s43, s43, 2
	s_add_u32 s41, s41, 0x100
	s_addc_u32 s42, s42, 0
	s_cmp_gt_u32 s43, 41
	s_mov_b64 s[14:15], s[16:17]
	s_barrier
	s_cbranch_scc0 .LBB0_1247
	s_setprio 0
	v_mov_b32_e32 v154, v163
	s_lshl_b32 s14, s39, 8
	v_readlane_b32 s98, v254, 0
	s_and_b32 s98, s98, s99
	s_lshl_b32 s98, s98, 7
	s_add_i32 s14, s14, s98
	v_ashrrev_i32_e32 v99, 2, v154
	v_and_b32_e32 v99, 0xffffffc0, v99
	v_add_u32_e32 v155, s14, v99
	s_addk_i32 s14, 0xe000
	s_lshr_b32 s14, s14, 11
	s_lshl_b32 s15, s40, 8
	v_lshrrev_b32_e32 v99, 1, v154
	s_add_i32 s16, s14, 1
	v_and_b32_e32 v98, 0xc0, v154
	v_and_b32_e32 v99, 24, v99
	s_cmp_gt_i32 s39, 31
	v_or3_b32 v152, v98, s15, v99
	s_cselect_b64 s[14:15], -1, 0
	s_and_b64 vcc, s[14:15], exec
	s_cselect_b32 s14, s16, 0
	s_mul_hi_u32 s15, s14, 0x6000
	s_mulk_i32 s14, 0x6000
	s_add_u32 s14, s29, s14
	s_addc_u32 s15, s30, s15
	v_ashrrev_i32_e32 v153, 31, v152
	v_lshl_add_u64 v[106:107], v[152:153], 2, s[14:15]
	global_load_dwordx4 v[102:105], v[106:107], off offset:16
	global_load_dwordx4 v[110:113], v[106:107], off
	global_load_dwordx4 v[98:101], v[106:107], off offset:144
	s_nop 0
	global_load_dwordx4 v[106:109], v[106:107], off offset:128
	v_and_or_b32 v154, v154, 15, v155
	s_mov_b64 s[14:15], -1
	v_ashrrev_i32_e32 v155, 31, v154
	s_cbranch_vccz .LBB0_1250
	v_lshlrev_b64 v[158:159], 12, v[154:155]
	s_mov_b32 s14, 0xfe000000
	v_lshl_add_u64 v[156:157], s[12:13], 0, v[158:159]
	s_mov_b32 s15, -1
	v_lshl_add_u64 v[156:157], v[156:157], 0, s[14:15]
	s_mov_b64 s[14:15], 0
